# GEMM K-loops: per-phase s_setprio flips deleted, one static s_setprio 1 for waves 4-7 (0 for waves 0-3) before each loop
# speedup vs baseline: 1.0001x; 1.0001x over previous
; template <class Epi, class Sched, bool ALIGN_EPI = false, bool SP2 = false>
; __device__ __forceinline__ void gemm_phase(PG8_LAS unsigned char* lds, const Gemm g, const Sched& S, const Epi& E) {
;     ...
;         const bool has_next = S.next(ui + 1, nxt);
;         const char* nA = has_next ? (const char*)g.A + (size_t)nxt.pm * tstep : cA; const char* nB = has_next ? (const char*)g.Bt + (size_t)nxt.pn * tstep : cB;
;         for (int t = 0; t < nt; t += 2) {
;             const bool last = (t == nt - 2);
;             const char* a1 = cA + (size_t)(t + 1) * kstep;
;             const char* a2 = last ? nA : cA + (size_t)(t + 2) * kstep; const char* b2 = last ? nB : cB + (size_t)(t + 2) * kstep;
;     ...
; #pragma unroll
;         for (int a = 0; a < 2; ++a)
; #pragma unroll
;             for (int b = 0; b < 2; ++b)
; #pragma unroll
;                 for (int m = 0; m < 4; ++m)
; #pragma unroll
;                     for (int n = 0; n < 2; ++n) acc[a][b][m][n] = (f32x4){0.f, 0.f, 0.f, 0.f};
.LBB0_85:
	s_ashr_i32 s29, s28, 31
	s_lshl_b64 s[26:27], s[28:29], 20
	s_add_u32 s30, s22, s26
	s_addc_u32 s31, s23, s27
	s_and_b64 s[26:27], s[36:37], exec
	s_cselect_b32 s29, s31, s41
	s_cselect_b32 s50, s30, s40
	s_ashr_i32 s19, s18, 31
	s_lshl_b64 s[26:27], s[18:19], 20
	v_readlane_b32 s34, v254, 40
	v_readlane_b32 s35, v254, 41
	s_add_u32 s34, s34, s26
	s_addc_u32 s35, s35, s27
	s_and_b64 s[26:27], s[36:37], exec
	s_cselect_b32 s19, s35, s39
	s_cselect_b32 s51, s34, s38
	s_add_u32 s52, s38, 0x100
	s_addc_u32 s53, s39, 0
	s_add_u32 s38, s40, 0x80080
	v_mov_b32_e32 v4, 0
	s_addc_u32 s39, s41, 0
	s_mov_b32 s54, -2
	v_mov_b32_e32 v5, v4
	v_mov_b32_e32 v6, v4
	v_mov_b32_e32 v7, v4
	v_mov_b32_e32 v8, v4
	v_mov_b32_e32 v9, v4
	v_mov_b32_e32 v10, v4
	v_mov_b32_e32 v11, v4
	v_mov_b32_e32 v16, v4
	v_mov_b32_e32 v17, v4
	v_mov_b32_e32 v18, v4
	v_mov_b32_e32 v19, v4
	v_mov_b32_e32 v24, v4
	v_mov_b32_e32 v25, v4
	v_mov_b32_e32 v26, v4
	v_mov_b32_e32 v27, v4
	s_waitcnt vmcnt(0)
	v_mov_b32_e32 v32, v4
	v_mov_b32_e32 v33, v4
	v_mov_b32_e32 v34, v4
	v_mov_b32_e32 v35, v4
	v_mov_b32_e32 v40, v4
	v_mov_b32_e32 v41, v4
	v_mov_b32_e32 v42, v4
	v_mov_b32_e32 v43, v4
	v_mov_b32_e32 v48, v4
	v_mov_b32_e32 v49, v4
	v_mov_b32_e32 v50, v4
	v_mov_b32_e32 v51, v4
	v_mov_b32_e32 v56, v4
	v_mov_b32_e32 v57, v4
	v_mov_b32_e32 v58, v4
	v_mov_b32_e32 v59, v4
	v_mov_b32_e32 v12, v4
	v_mov_b32_e32 v13, v4
	v_mov_b32_e32 v14, v4
	v_mov_b32_e32 v15, v4
	v_mov_b32_e32 v20, v4
	v_mov_b32_e32 v21, v4
	v_mov_b32_e32 v22, v4
	v_mov_b32_e32 v23, v4
	v_mov_b32_e32 v28, v4
	v_mov_b32_e32 v29, v4
	v_mov_b32_e32 v30, v4
	v_mov_b32_e32 v31, v4
	v_mov_b32_e32 v36, v4
	v_mov_b32_e32 v37, v4
	v_mov_b32_e32 v38, v4
	v_mov_b32_e32 v39, v4
	v_mov_b32_e32 v44, v4
	v_mov_b32_e32 v45, v4
	v_mov_b32_e32 v46, v4
	v_mov_b32_e32 v47, v4
	v_mov_b32_e32 v52, v4
	v_mov_b32_e32 v53, v4
	v_mov_b32_e32 v54, v4
	v_mov_b32_e32 v55, v4
	v_mov_b32_e32 v60, v4
	v_mov_b32_e32 v61, v4
	v_mov_b32_e32 v62, v4
	v_mov_b32_e32 v63, v4
	v_mov_b32_e32 v64, v4
	v_mov_b32_e32 v65, v4
	v_mov_b32_e32 v66, v4
	v_mov_b32_e32 v67, v4
	v_mov_b32_e32 v68, v4
	v_mov_b32_e32 v69, v4
	v_mov_b32_e32 v70, v4
	v_mov_b32_e32 v71, v4
	v_mov_b32_e32 v72, v4
	v_mov_b32_e32 v73, v4
	v_mov_b32_e32 v74, v4
	v_mov_b32_e32 v75, v4
	v_mov_b32_e32 v84, v4
	v_mov_b32_e32 v85, v4
	v_mov_b32_e32 v86, v4
	v_mov_b32_e32 v87, v4
	v_mov_b32_e32 v88, v4
	v_mov_b32_e32 v89, v4
	v_mov_b32_e32 v90, v4
	v_mov_b32_e32 v91, v4
	v_mov_b32_e32 v100, v4
	v_mov_b32_e32 v101, v4
	v_mov_b32_e32 v102, v4
	v_mov_b32_e32 v103, v4
	v_mov_b32_e32 v104, v4
	v_mov_b32_e32 v105, v4
	v_mov_b32_e32 v106, v4
	v_mov_b32_e32 v107, v4
	v_mov_b32_e32 v116, v4
	v_mov_b32_e32 v117, v4
	v_mov_b32_e32 v118, v4
	v_mov_b32_e32 v119, v4
	v_mov_b32_e32 v120, v4
	v_mov_b32_e32 v121, v4
	v_mov_b32_e32 v122, v4
	v_mov_b32_e32 v123, v4
	v_mov_b32_e32 v76, v4
	v_mov_b32_e32 v77, v4
	v_mov_b32_e32 v78, v4
	v_mov_b32_e32 v79, v4
	v_mov_b32_e32 v80, v4
	v_mov_b32_e32 v81, v4
	v_mov_b32_e32 v82, v4
	v_mov_b32_e32 v83, v4
	v_mov_b32_e32 v92, v4
	v_mov_b32_e32 v93, v4
	v_mov_b32_e32 v94, v4
	v_mov_b32_e32 v95, v4
	v_mov_b32_e32 v96, v4
	v_mov_b32_e32 v97, v4
	v_mov_b32_e32 v98, v4
	v_mov_b32_e32 v99, v4
	v_mov_b32_e32 v108, v4
	v_mov_b32_e32 v109, v4
	v_mov_b32_e32 v110, v4
	v_mov_b32_e32 v111, v4
	v_mov_b32_e32 v112, v4
	v_mov_b32_e32 v113, v4
	v_mov_b32_e32 v114, v4
	v_mov_b32_e32 v115, v4
	v_mov_b32_e32 v124, v4
	v_mov_b32_e32 v125, v4
	v_mov_b32_e32 v126, v4
	v_mov_b32_e32 v127, v4
	v_mov_b32_e32 v128, v4
	v_mov_b32_e32 v129, v4
	v_mov_b32_e32 v130, v4
	v_mov_b32_e32 v131, v4
	v_readfirstlane_b32 s101, v172
	s_nop 3
	s_cmp_ge_u32 s101, 0x100
	s_cbranch_scc1 .Lprio_hi_86
	s_setprio 0
	s_branch .Lprio_done_86

; #define PG8_STAGE(bufoff, gbase, voff) do { _Pragma("unroll") for (int _i = 0; _i < 2; ++_i) \
;         __builtin_amdgcn_global_load_lds((const unsigned*)((const char*)(gbase) + (voff)[_i]), (PG8_LAS unsigned*)(lds + (bufoff) + ldsw + _i * 8192), 16, 0, 0); } while (0)
; #define PG8_LDA(dst, b, h) do { _Pragma("unroll") for (int m = 0; m < 4; ++m) _Pragma("unroll") for (int k = 0; k < 2; ++k) dst[m][k] = *(const PG8_LAS bf16x8*)(lds + PG8_SA(b, h) + aoff + m * 2048 + k * 1024); } while (0)
; #define PG8_LDB(dst, b, h) do { _Pragma("unroll") for (int n = 0; n < 2; ++n) _Pragma("unroll") for (int k = 0; k < 2; ++k) dst[n][k] = *(const PG8_LAS bf16x8*)(lds + PG8_SB(b, h) + boff + n * 2048 + k * 1024); } while (0)
; #define PG8_MMA(ai, bj, At, Bt) do { __builtin_amdgcn_s_setprio(1); _Pragma("unroll") for (int m = 0; m < 4; ++m) _Pragma("unroll") for (int n = 0; n < 2; ++n) _Pragma("unroll") for (int k = 0; k < 2; ++k) \
;         acc[ai][bj][m][n] = __builtin_amdgcn_mfma_f32_16x16x32_bf16(Bt[n][k], At[m][k], acc[ai][bj][m][n], 0, 0, 0); __builtin_amdgcn_s_setprio(0); } while (0)
; #define PG8_WAIT_V(n) asm volatile("s_waitcnt vmcnt(" #n ")" ::: "memory")
; #define PG8_BAR __builtin_amdgcn_s_barrier()
; template <class Epi, class Sched, bool ALIGN_EPI = false, bool SP2 = false>
; __device__ __forceinline__ void gemm_phase(PG8_LAS unsigned char* lds, const Gemm g, const Sched& S, const Epi& E) {
;     ...
;         for (int t = 0; t < nt; t += 2) {
;             const bool last = (t == nt - 2);
;             const char* a1 = cA + (size_t)(t + 1) * kstep;
;             const char* a2 = last ? nA : cA + (size_t)(t + 2) * kstep; const char* b2 = last ? nB : cB + (size_t)(t + 2) * kstep;
;             const char* a3 = a2 + kstep; const char* b3 = b2 + kstep;
;             if (last && has_next) S.a_ready(nxt);
;             if constexpr (SP2) {
;             PG8_LDB(B0, 0, 0); PG8_LDB(B1, 0, 1); PG8_SCHED; PG8_LDA(At, 0, 0); PG8_STAGE(PG8_SA(1, 1), a1 + hstep, voffA);
;             PG8_WAIT_V(8); PG8_WAIT_L(0); PG8_BAR; PG8_MMA(0, 0, At, B0); PG8_MMA(0, 1, At, B1); PG8_BAR; PG8_SCHED;
;             PG8_LDA(At, 0, 1); PG8_STAGE(PG8_SB(0, 0), b2, voffB); PG8_STAGE(PG8_SB(0, 1), b2 + hstep, voffB); PG8_STAGE(PG8_SA(0, 0), a2, voffA);
;             PG8_WAIT_V(8); PG8_WAIT_L(0); PG8_BAR; PG8_MMA(1, 0, At, B0); PG8_MMA(1, 1, At, B1); PG8_BAR; PG8_SCHED;
.Lprio_done_86:
.LBB0_86:
	s_add_u32 s26, s38, 0xfff80080
	s_addc_u32 s27, s39, -1
	s_add_i32 s55, 0, 0x10000
	s_cmp_eq_u32 s54, 28
	s_cselect_b32 s27, s29, s27
	s_cselect_b32 s26, s50, s26
	v_add_u32_e32 v142, s55, v147
	s_cselect_b32 s41, s19, s53
	s_cselect_b32 s40, s51, s52
	s_add_i32 s58, 0, 0x14000
	ds_read_b128 v[148:151], v142
	ds_read_b128 v[156:159], v142 offset:1024
	ds_read_b128 v[160:163], v142 offset:2048
	ds_read_b128 v[164:167], v142 offset:3072
	v_add_u32_e32 v142, s58, v147
	ds_read_b128 v[168:171], v142
	ds_read_b128 v[184:187], v142 offset:1024
	ds_read_b128 v[188:191], v142 offset:2048
	ds_read_b128 v[192:195], v142 offset:3072
	v_lshl_add_u64 v[144:145], s[38:39], 0, v[140:141]
	s_add_i32 m0, s25, 0xc000
	ds_read_b128 v[196:199], v155
	ds_read_b128 v[200:203], v155 offset:1024
	ds_read_b128 v[204:207], v155 offset:2048
	ds_read_b128 v[208:211], v155 offset:3072
	ds_read_b128 v[212:215], v155 offset:4096
	ds_read_b128 v[216:219], v155 offset:5120
	ds_read_b128 v[220:223], v155 offset:6144
	ds_read_b128 v[224:227], v155 offset:7168
	global_load_lds_dwordx4 v[144:145], off
	v_lshl_add_u64 v[144:145], s[38:39], 0, v[138:139]
	s_add_i32 m0, s25, 0xe000
	s_nop 0
	global_load_lds_dwordx4 v[144:145], off
	s_waitcnt vmcnt(8)
	s_waitcnt lgkmcnt(0)
	s_barrier
	s_waitcnt lgkmcnt(0)
	v_mfma_f32_16x16x32_bf16 v[128:131], v[148:151], v[196:199], v[128:131]
	v_mfma_f32_16x16x32_bf16 v[124:127], v[160:163], v[196:199], v[124:127]
	v_mfma_f32_16x16x32_bf16 v[112:115], v[148:151], v[204:207], v[112:115]
	v_mfma_f32_16x16x32_bf16 v[108:111], v[160:163], v[204:207], v[108:111]
	v_mfma_f32_16x16x32_bf16 v[96:99], v[148:151], v[212:215], v[96:99]
	v_mfma_f32_16x16x32_bf16 v[92:95], v[160:163], v[212:215], v[92:95]
	v_mfma_f32_16x16x32_bf16 v[80:83], v[148:151], v[220:223], v[80:83]
	v_mfma_f32_16x16x32_bf16 v[76:79], v[160:163], v[220:223], v[76:79]
	v_mfma_f32_16x16x32_bf16 v[128:131], v[156:159], v[200:203], v[128:131]
	v_mfma_f32_16x16x32_bf16 v[124:127], v[164:167], v[200:203], v[124:127]
	v_mfma_f32_16x16x32_bf16 v[112:115], v[156:159], v[208:211], v[112:115]
	v_mfma_f32_16x16x32_bf16 v[108:111], v[164:167], v[208:211], v[108:111]
	v_mfma_f32_16x16x32_bf16 v[96:99], v[156:159], v[216:219], v[96:99]
	v_mfma_f32_16x16x32_bf16 v[92:95], v[164:167], v[216:219], v[92:95]
	v_mfma_f32_16x16x32_bf16 v[80:83], v[156:159], v[224:227], v[80:83]
	v_mfma_f32_16x16x32_bf16 v[76:79], v[164:167], v[224:227], v[76:79]
	v_mfma_f32_16x16x32_bf16 v[120:123], v[168:171], v[196:199], v[120:123]
	v_mfma_f32_16x16x32_bf16 v[116:119], v[188:191], v[196:199], v[116:119]
	v_mfma_f32_16x16x32_bf16 v[104:107], v[168:171], v[204:207], v[104:107]
	v_mfma_f32_16x16x32_bf16 v[100:103], v[188:191], v[204:207], v[100:103]
	v_mfma_f32_16x16x32_bf16 v[88:91], v[168:171], v[212:215], v[88:91]
	v_mfma_f32_16x16x32_bf16 v[84:87], v[188:191], v[212:215], v[84:87]
	v_mfma_f32_16x16x32_bf16 v[72:75], v[168:171], v[220:223], v[72:75]
	v_mfma_f32_16x16x32_bf16 v[68:71], v[188:191], v[220:223], v[68:71]
	v_mfma_f32_16x16x32_bf16 v[120:123], v[184:187], v[200:203], v[120:123]
	v_mfma_f32_16x16x32_bf16 v[116:119], v[192:195], v[200:203], v[116:119]
	v_mfma_f32_16x16x32_bf16 v[104:107], v[184:187], v[208:211], v[104:107]
	v_mfma_f32_16x16x32_bf16 v[100:103], v[192:195], v[208:211], v[100:103]
	v_mfma_f32_16x16x32_bf16 v[88:91], v[184:187], v[216:219], v[88:91]
	v_mfma_f32_16x16x32_bf16 v[84:87], v[192:195], v[216:219], v[84:87]
	v_mfma_f32_16x16x32_bf16 v[72:75], v[184:187], v[224:227], v[72:75]
	v_mfma_f32_16x16x32_bf16 v[68:71], v[192:195], v[224:227], v[68:71]
	s_barrier
	s_add_i32 s55, s55, s24
	v_lshl_add_u64 v[144:145], s[40:41], 0, v[174:175]
	s_mov_b32 m0, s55
	ds_read_b128 v[196:199], v155 offset:16384
	ds_read_b128 v[200:203], v155 offset:17408
	ds_read_b128 v[204:207], v155 offset:18432
	ds_read_b128 v[208:211], v155 offset:19456
	ds_read_b128 v[212:215], v155 offset:20480
	ds_read_b128 v[216:219], v155 offset:21504
	ds_read_b128 v[220:223], v155 offset:22528
	ds_read_b128 v[224:227], v155 offset:23552
	global_load_lds_dwordx4 v[144:145], off
	s_add_i32 m0, s55, 0x2000
	s_add_u32 s56, s40, 0x80000
	v_lshl_add_u64 v[228:229], s[40:41], 0, v[132:133]
	s_addc_u32 s57, s41, 0
	s_add_i32 s55, s58, s24
	global_load_lds_dwordx4 v[228:229], off
	v_lshl_add_u64 v[230:231], s[56:57], 0, v[174:175]
	s_mov_b32 m0, s55
	v_lshl_add_u64 v[232:233], s[26:27], 0, v[134:135]
	global_load_lds_dwordx4 v[230:231], off
	v_lshl_add_u64 v[230:231], s[56:57], 0, v[132:133]
	s_add_i32 m0, s55, 0x2000
	s_nop 0
	global_load_lds_dwordx4 v[230:231], off
	v_lshl_add_u64 v[230:231], s[26:27], 0, v[136:137]
	s_mov_b32 m0, s25
	s_nop 0
	global_load_lds_dwordx4 v[230:231], off
	s_mov_b32 m0, s42
	s_nop 0
	global_load_lds_dwordx4 v[232:233], off
	s_waitcnt vmcnt(8)
	s_waitcnt lgkmcnt(0)
	s_barrier
; #define PG8_STAGE(bufoff, gbase, voff) do { _Pragma("unroll") for (int _i = 0; _i < 2; ++_i) \
;         __builtin_amdgcn_global_load_lds((const unsigned*)((const char*)(gbase) + (voff)[_i]), (PG8_LAS unsigned*)(lds + (bufoff) + ldsw + _i * 8192), 16, 0, 0); } while (0)
; #define PG8_LDA(dst, b, h) do { _Pragma("unroll") for (int m = 0; m < 4; ++m) _Pragma("unroll") for (int k = 0; k < 2; ++k) dst[m][k] = *(const PG8_LAS bf16x8*)(lds + PG8_SA(b, h) + aoff + m * 2048 + k * 1024); } while (0)
; #define PG8_LDB(dst, b, h) do { _Pragma("unroll") for (int n = 0; n < 2; ++n) _Pragma("unroll") for (int k = 0; k < 2; ++k) dst[n][k] = *(const PG8_LAS bf16x8*)(lds + PG8_SB(b, h) + boff + n * 2048 + k * 1024); } while (0)
; #define PG8_MMA(ai, bj, At, Bt) do { __builtin_amdgcn_s_setprio(1); _Pragma("unroll") for (int m = 0; m < 4; ++m) _Pragma("unroll") for (int n = 0; n < 2; ++n) _Pragma("unroll") for (int k = 0; k < 2; ++k) \
;         acc[ai][bj][m][n] = __builtin_amdgcn_mfma_f32_16x16x32_bf16(Bt[n][k], At[m][k], acc[ai][bj][m][n], 0, 0, 0); __builtin_amdgcn_s_setprio(0); } while (0)
; #define PG8_WAIT_V(n) asm volatile("s_waitcnt vmcnt(" #n ")" ::: "memory")
; #define PG8_WAIT_L(n) asm volatile("s_waitcnt lgkmcnt(" #n ")" ::: "memory")
; #define PG8_BAR __builtin_amdgcn_s_barrier()
; #define PG8_SCHED __builtin_amdgcn_sched_barrier(0)
; template <class Epi, class Sched, bool ALIGN_EPI = false, bool SP2 = false>
; __device__ __forceinline__ void gemm_phase(PG8_LAS unsigned char* lds, const Gemm g, const Sched& S, const Epi& E) {
;     ...
;             PG8_WAIT_V(8); PG8_WAIT_L(0); PG8_BAR; PG8_MMA(1, 0, At, B0); PG8_MMA(1, 1, At, B1); PG8_BAR; PG8_SCHED;
;             PG8_LDB(B0, 1, 0); PG8_LDB(B1, 1, 1); PG8_SCHED; PG8_LDA(At, 1, 0); PG8_STAGE(PG8_SA(0, 1), a2 + hstep, voffA);
;             PG8_WAIT_V(8); PG8_WAIT_L(0); PG8_BAR; PG8_MMA(0, 0, At, B0); PG8_MMA(0, 1, At, B1); PG8_BAR; PG8_SCHED;
	s_waitcnt lgkmcnt(0)
	v_mfma_f32_16x16x32_bf16 v[64:67], v[148:151], v[196:199], v[64:67]
	v_mfma_f32_16x16x32_bf16 v[60:63], v[160:163], v[196:199], v[60:63]
	v_mfma_f32_16x16x32_bf16 v[52:55], v[148:151], v[204:207], v[52:55]
	v_mfma_f32_16x16x32_bf16 v[44:47], v[160:163], v[204:207], v[44:47]
	v_mfma_f32_16x16x32_bf16 v[36:39], v[148:151], v[212:215], v[36:39]
	v_mfma_f32_16x16x32_bf16 v[28:31], v[160:163], v[212:215], v[28:31]
	v_mfma_f32_16x16x32_bf16 v[20:23], v[148:151], v[220:223], v[20:23]
	v_mfma_f32_16x16x32_bf16 v[12:15], v[160:163], v[220:223], v[12:15]
	v_mfma_f32_16x16x32_bf16 v[64:67], v[156:159], v[200:203], v[64:67]
	v_mfma_f32_16x16x32_bf16 v[60:63], v[164:167], v[200:203], v[60:63]
	v_mfma_f32_16x16x32_bf16 v[52:55], v[156:159], v[208:211], v[52:55]
	v_mfma_f32_16x16x32_bf16 v[44:47], v[164:167], v[208:211], v[44:47]
	v_mfma_f32_16x16x32_bf16 v[36:39], v[156:159], v[216:219], v[36:39]
	v_mfma_f32_16x16x32_bf16 v[28:31], v[164:167], v[216:219], v[28:31]
	v_mfma_f32_16x16x32_bf16 v[20:23], v[156:159], v[224:227], v[20:23]
	v_mfma_f32_16x16x32_bf16 v[12:15], v[164:167], v[224:227], v[12:15]
	v_mfma_f32_16x16x32_bf16 v[56:59], v[168:171], v[196:199], v[56:59]
	v_mfma_f32_16x16x32_bf16 v[48:51], v[188:191], v[196:199], v[48:51]
	v_mfma_f32_16x16x32_bf16 v[40:43], v[168:171], v[204:207], v[40:43]
	v_mfma_f32_16x16x32_bf16 v[32:35], v[188:191], v[204:207], v[32:35]
	v_mfma_f32_16x16x32_bf16 v[24:27], v[168:171], v[212:215], v[24:27]
	v_mfma_f32_16x16x32_bf16 v[16:19], v[188:191], v[212:215], v[16:19]
	v_mfma_f32_16x16x32_bf16 v[8:11], v[168:171], v[220:223], v[8:11]
	v_mfma_f32_16x16x32_bf16 v[4:7], v[188:191], v[220:223], v[4:7]
	v_mfma_f32_16x16x32_bf16 v[56:59], v[184:187], v[200:203], v[56:59]
	v_mfma_f32_16x16x32_bf16 v[48:51], v[192:195], v[200:203], v[48:51]
	v_mfma_f32_16x16x32_bf16 v[40:43], v[184:187], v[208:211], v[40:43]
	v_mfma_f32_16x16x32_bf16 v[32:35], v[192:195], v[208:211], v[32:35]
	v_mfma_f32_16x16x32_bf16 v[24:27], v[184:187], v[216:219], v[24:27]
	v_mfma_f32_16x16x32_bf16 v[16:19], v[192:195], v[216:219], v[16:19]
	v_mfma_f32_16x16x32_bf16 v[8:11], v[184:187], v[224:227], v[8:11]
	v_mfma_f32_16x16x32_bf16 v[4:7], v[192:195], v[224:227], v[4:7]
	s_barrier
	s_add_i32 s55, 0, 0x18000
	v_add_u32_e32 v142, s55, v147
	s_add_i32 s56, 0, 0x1c000
	ds_read_b128 v[148:151], v142
	ds_read_b128 v[156:159], v142 offset:1024
	ds_read_b128 v[160:163], v142 offset:2048
	ds_read_b128 v[164:167], v142 offset:3072
	v_add_u32_e32 v142, s56, v147
	ds_read_b128 v[168:171], v142
	ds_read_b128 v[184:187], v142 offset:1024
	ds_read_b128 v[188:191], v142 offset:2048
	ds_read_b128 v[192:195], v142 offset:3072
	s_add_u32 s26, s26, 0x80000
	s_addc_u32 s27, s27, 0
	s_mov_b32 m0, s43
	v_lshl_add_u64 v[234:235], s[26:27], 0, v[136:137]
	ds_read_b128 v[196:199], v155 offset:32768
	ds_read_b128 v[200:203], v155 offset:33792
	ds_read_b128 v[204:207], v155 offset:34816
	ds_read_b128 v[208:211], v155 offset:35840
	ds_read_b128 v[212:215], v155 offset:36864
	ds_read_b128 v[216:219], v155 offset:37888
	ds_read_b128 v[220:223], v155 offset:38912
	ds_read_b128 v[224:227], v155 offset:39936
	global_load_lds_dwordx4 v[234:235], off
	v_lshl_add_u64 v[234:235], s[26:27], 0, v[134:135]
	s_mov_b32 m0, s44
	s_nop 0
	global_load_lds_dwordx4 v[234:235], off
	s_waitcnt vmcnt(8)
	s_waitcnt lgkmcnt(0)
	s_barrier
	s_waitcnt lgkmcnt(0)
	v_mfma_f32_16x16x32_bf16 v[128:131], v[148:151], v[196:199], v[128:131]
	v_mfma_f32_16x16x32_bf16 v[124:127], v[160:163], v[196:199], v[124:127]
	v_mfma_f32_16x16x32_bf16 v[112:115], v[148:151], v[204:207], v[112:115]
	v_mfma_f32_16x16x32_bf16 v[108:111], v[160:163], v[204:207], v[108:111]
	v_mfma_f32_16x16x32_bf16 v[96:99], v[148:151], v[212:215], v[96:99]
	v_mfma_f32_16x16x32_bf16 v[92:95], v[160:163], v[212:215], v[92:95]
	v_mfma_f32_16x16x32_bf16 v[80:83], v[148:151], v[220:223], v[80:83]
	v_mfma_f32_16x16x32_bf16 v[76:79], v[160:163], v[220:223], v[76:79]
	v_mfma_f32_16x16x32_bf16 v[128:131], v[156:159], v[200:203], v[128:131]
	v_mfma_f32_16x16x32_bf16 v[124:127], v[164:167], v[200:203], v[124:127]
	v_mfma_f32_16x16x32_bf16 v[112:115], v[156:159], v[208:211], v[112:115]
	v_mfma_f32_16x16x32_bf16 v[108:111], v[164:167], v[208:211], v[108:111]
	v_mfma_f32_16x16x32_bf16 v[96:99], v[156:159], v[216:219], v[96:99]
	v_mfma_f32_16x16x32_bf16 v[92:95], v[164:167], v[216:219], v[92:95]
	v_mfma_f32_16x16x32_bf16 v[80:83], v[156:159], v[224:227], v[80:83]
	v_mfma_f32_16x16x32_bf16 v[76:79], v[164:167], v[224:227], v[76:79]
	v_mfma_f32_16x16x32_bf16 v[120:123], v[168:171], v[196:199], v[120:123]
	v_mfma_f32_16x16x32_bf16 v[116:119], v[188:191], v[196:199], v[116:119]
	v_mfma_f32_16x16x32_bf16 v[104:107], v[168:171], v[204:207], v[104:107]
	v_mfma_f32_16x16x32_bf16 v[100:103], v[188:191], v[204:207], v[100:103]
	v_mfma_f32_16x16x32_bf16 v[88:91], v[168:171], v[212:215], v[88:91]
	v_mfma_f32_16x16x32_bf16 v[84:87], v[188:191], v[212:215], v[84:87]
	v_mfma_f32_16x16x32_bf16 v[72:75], v[168:171], v[220:223], v[72:75]
	v_mfma_f32_16x16x32_bf16 v[68:71], v[188:191], v[220:223], v[68:71]
	v_mfma_f32_16x16x32_bf16 v[120:123], v[184:187], v[200:203], v[120:123]
	v_mfma_f32_16x16x32_bf16 v[116:119], v[192:195], v[200:203], v[116:119]
	v_mfma_f32_16x16x32_bf16 v[104:107], v[184:187], v[208:211], v[104:107]
	v_mfma_f32_16x16x32_bf16 v[100:103], v[192:195], v[208:211], v[100:103]
	v_mfma_f32_16x16x32_bf16 v[88:91], v[184:187], v[216:219], v[88:91]
	v_mfma_f32_16x16x32_bf16 v[84:87], v[192:195], v[216:219], v[84:87]
	v_mfma_f32_16x16x32_bf16 v[72:75], v[184:187], v[224:227], v[72:75]
	v_mfma_f32_16x16x32_bf16 v[68:71], v[192:195], v[224:227], v[68:71]
	s_barrier
; #define PG8_STAGE(bufoff, gbase, voff) do { _Pragma("unroll") for (int _i = 0; _i < 2; ++_i) \
;         __builtin_amdgcn_global_load_lds((const unsigned*)((const char*)(gbase) + (voff)[_i]), (PG8_LAS unsigned*)(lds + (bufoff) + ldsw + _i * 8192), 16, 0, 0); } while (0)
; #define PG8_LDA(dst, b, h) do { _Pragma("unroll") for (int m = 0; m < 4; ++m) _Pragma("unroll") for (int k = 0; k < 2; ++k) dst[m][k] = *(const PG8_LAS bf16x8*)(lds + PG8_SA(b, h) + aoff + m * 2048 + k * 1024); } while (0)
; #define PG8_MMA(ai, bj, At, Bt) do { __builtin_amdgcn_s_setprio(1); _Pragma("unroll") for (int m = 0; m < 4; ++m) _Pragma("unroll") for (int n = 0; n < 2; ++n) _Pragma("unroll") for (int k = 0; k < 2; ++k) \
;         acc[ai][bj][m][n] = __builtin_amdgcn_mfma_f32_16x16x32_bf16(Bt[n][k], At[m][k], acc[ai][bj][m][n], 0, 0, 0); __builtin_amdgcn_s_setprio(0); } while (0)
; #define PG8_WAIT_V(n) asm volatile("s_waitcnt vmcnt(" #n ")" ::: "memory")
; #define PG8_WAIT_L(n) asm volatile("s_waitcnt lgkmcnt(" #n ")" ::: "memory")
; #define PG8_BAR __builtin_amdgcn_s_barrier()
; #define PG8_SCHED __builtin_amdgcn_sched_barrier(0)
; template <class Epi, class Sched, bool ALIGN_EPI = false, bool SP2 = false>
; __device__ __forceinline__ void gemm_phase(PG8_LAS unsigned char* lds, const Gemm g, const Sched& S, const Epi& E) {
;     ...
;         for (int t = 0; t < nt; t += 2) {
;     ...
;             PG8_LDA(At, 1, 1); PG8_STAGE(PG8_SB(1, 0), b3, voffB); PG8_STAGE(PG8_SB(1, 1), b3 + hstep, voffB); PG8_STAGE(PG8_SA(1, 0), a3, voffA);
;             PG8_WAIT_V(8); PG8_WAIT_L(0); PG8_BAR; PG8_MMA(1, 0, At, B0); PG8_MMA(1, 1, At, B1); PG8_BAR; PG8_SCHED;
	s_add_i32 s26, s55, s24
	v_lshl_add_u64 v[144:145], v[144:145], 0, s[10:11]
	s_mov_b32 m0, s26
	ds_read_b128 v[196:199], v155 offset:49152
	ds_read_b128 v[200:203], v155 offset:50176
	ds_read_b128 v[204:207], v155 offset:51200
	ds_read_b128 v[208:211], v155 offset:52224
	ds_read_b128 v[212:215], v155 offset:53248
	ds_read_b128 v[216:219], v155 offset:54272
	ds_read_b128 v[220:223], v155 offset:55296
	ds_read_b128 v[224:227], v155 offset:56320
	global_load_lds_dwordx4 v[144:145], off
	s_add_i32 m0, s26, 0x2000
	s_add_u32 s26, s40, 0x80080
	v_lshl_add_u64 v[144:145], v[228:229], 0, s[10:11]
	s_addc_u32 s27, s41, 0
	s_add_i32 s40, s56, s24
	global_load_lds_dwordx4 v[144:145], off
	v_lshl_add_u64 v[144:145], s[26:27], 0, v[174:175]
	s_mov_b32 m0, s40
	s_nop 0
	global_load_lds_dwordx4 v[144:145], off
	v_lshl_add_u64 v[144:145], s[26:27], 0, v[132:133]
	s_add_i32 m0, s40, 0x2000
	s_nop 0
	global_load_lds_dwordx4 v[144:145], off
	v_lshl_add_u64 v[144:145], v[230:231], 0, s[10:11]
	s_mov_b32 m0, s20
	s_nop 0
	global_load_lds_dwordx4 v[144:145], off
	v_lshl_add_u64 v[144:145], v[232:233], 0, s[10:11]
	s_mov_b32 m0, s45
	s_nop 0
	global_load_lds_dwordx4 v[144:145], off
	s_waitcnt vmcnt(8)
	s_waitcnt lgkmcnt(0)
	s_barrier
	s_waitcnt lgkmcnt(0)
	v_mfma_f32_16x16x32_bf16 v[64:67], v[148:151], v[196:199], v[64:67]
	v_mfma_f32_16x16x32_bf16 v[60:63], v[160:163], v[196:199], v[60:63]
	v_mfma_f32_16x16x32_bf16 v[52:55], v[148:151], v[204:207], v[52:55]
	v_mfma_f32_16x16x32_bf16 v[44:47], v[160:163], v[204:207], v[44:47]
	v_mfma_f32_16x16x32_bf16 v[36:39], v[148:151], v[212:215], v[36:39]
	v_mfma_f32_16x16x32_bf16 v[28:31], v[160:163], v[212:215], v[28:31]
	v_mfma_f32_16x16x32_bf16 v[20:23], v[148:151], v[220:223], v[20:23]
	v_mfma_f32_16x16x32_bf16 v[12:15], v[160:163], v[220:223], v[12:15]
	v_mfma_f32_16x16x32_bf16 v[64:67], v[156:159], v[200:203], v[64:67]
	v_mfma_f32_16x16x32_bf16 v[60:63], v[164:167], v[200:203], v[60:63]
	v_mfma_f32_16x16x32_bf16 v[52:55], v[156:159], v[208:211], v[52:55]
	v_mfma_f32_16x16x32_bf16 v[44:47], v[164:167], v[208:211], v[44:47]
	v_mfma_f32_16x16x32_bf16 v[36:39], v[156:159], v[216:219], v[36:39]
	v_mfma_f32_16x16x32_bf16 v[28:31], v[164:167], v[216:219], v[28:31]
	v_mfma_f32_16x16x32_bf16 v[20:23], v[156:159], v[224:227], v[20:23]
	v_mfma_f32_16x16x32_bf16 v[12:15], v[164:167], v[224:227], v[12:15]
	v_mfma_f32_16x16x32_bf16 v[56:59], v[168:171], v[196:199], v[56:59]
	v_mfma_f32_16x16x32_bf16 v[48:51], v[188:191], v[196:199], v[48:51]
	v_mfma_f32_16x16x32_bf16 v[40:43], v[168:171], v[204:207], v[40:43]
	v_mfma_f32_16x16x32_bf16 v[32:35], v[188:191], v[204:207], v[32:35]
	v_mfma_f32_16x16x32_bf16 v[24:27], v[168:171], v[212:215], v[24:27]
	v_mfma_f32_16x16x32_bf16 v[16:19], v[188:191], v[212:215], v[16:19]
	v_mfma_f32_16x16x32_bf16 v[8:11], v[168:171], v[220:223], v[8:11]
	v_mfma_f32_16x16x32_bf16 v[4:7], v[188:191], v[220:223], v[4:7]
	v_mfma_f32_16x16x32_bf16 v[56:59], v[184:187], v[200:203], v[56:59]
	v_mfma_f32_16x16x32_bf16 v[48:51], v[192:195], v[200:203], v[48:51]
	v_mfma_f32_16x16x32_bf16 v[40:43], v[184:187], v[208:211], v[40:43]
	v_mfma_f32_16x16x32_bf16 v[32:35], v[192:195], v[208:211], v[32:35]
	v_mfma_f32_16x16x32_bf16 v[24:27], v[184:187], v[216:219], v[24:27]
	v_mfma_f32_16x16x32_bf16 v[16:19], v[192:195], v[216:219], v[16:19]
	v_mfma_f32_16x16x32_bf16 v[8:11], v[184:187], v[224:227], v[8:11]
	v_mfma_f32_16x16x32_bf16 v[4:7], v[192:195], v[224:227], v[4:7]
	s_barrier
	s_add_i32 s54, s54, 2
	s_add_u32 s52, s52, 0x100
	s_addc_u32 s53, s53, 0
	s_add_u32 s38, s38, 0x100
	s_addc_u32 s39, s39, 0
	s_cmp_gt_u32 s54, 29
	s_cbranch_scc0 .LBB0_86
	s_and_b64 vcc, exec, s[16:17]
	s_cbranch_vccz .LBB0_89
	s_barrier

; template <class Epi, class Sched, bool ALIGN_EPI = false, bool SP2 = false>
; __device__ __forceinline__ void gemm_phase(PG8_LAS unsigned char* lds, const Gemm g, const Sched& S, const Epi& E) {
;     ...
;         const bool has_next = S.next(ui + 1, nxt);
;         const char* nA = has_next ? (const char*)g.A + (size_t)nxt.pm * tstep : cA; const char* nB = has_next ? (const char*)g.Bt + (size_t)nxt.pn * tstep : cB;
;         for (int t = 0; t < nt; t += 2) {
;             const bool last = (t == nt - 2);
;             const char* a1 = cA + (size_t)(t + 1) * kstep;
;             const char* a2 = last ? nA : cA + (size_t)(t + 2) * kstep; const char* b2 = last ? nB : cB + (size_t)(t + 2) * kstep;
;     ...
; #pragma unroll
;         for (int a = 0; a < 2; ++a)
; #pragma unroll
;             for (int b = 0; b < 2; ++b)
; #pragma unroll
;                 for (int m = 0; m < 4; ++m)
; #pragma unroll
;                     for (int n = 0; n < 2; ++n) acc[a][b][m][n] = (f32x4){0.f, 0.f, 0.f, 0.f};
.LBB0_406:
	s_ashr_i32 s51, s50, 31
	s_lshl_b64 s[16:17], s[50:51], 20
	s_add_u32 s52, s19, s16
	s_addc_u32 s53, s20, s17
	s_and_b64 s[16:17], s[40:41], exec
	s_cselect_b32 s23, s53, s15
	s_cselect_b32 s24, s52, s14
	s_ashr_i32 s49, s48, 31
	s_lshl_b64 s[16:17], s[48:49], 20
	s_add_u32 s54, s26, s16
	s_addc_u32 s55, s27, s17
	s_and_b64 s[16:17], s[40:41], exec
	s_cselect_b32 s25, s55, s1
	s_cselect_b32 s49, s54, s0
	s_add_u32 s51, s0, 0x100
	s_addc_u32 s57, s1, 0
	s_add_u32 s0, s14, 0x80080
	v_mov_b32_e32 v4, 0
	s_addc_u32 s1, s15, 0
	s_mov_b32 s58, -2
	v_mov_b32_e32 v5, v4
	v_mov_b32_e32 v6, v4
	v_mov_b32_e32 v7, v4
	v_mov_b32_e32 v8, v4
	v_mov_b32_e32 v9, v4
	v_mov_b32_e32 v10, v4
	v_mov_b32_e32 v11, v4
	v_mov_b32_e32 v12, v4
	v_mov_b32_e32 v13, v4
	v_mov_b32_e32 v14, v4
	v_mov_b32_e32 v15, v4
	v_mov_b32_e32 v16, v4
	v_mov_b32_e32 v17, v4
	v_mov_b32_e32 v18, v4
	v_mov_b32_e32 v19, v4
	v_mov_b32_e32 v20, v4
	v_mov_b32_e32 v21, v4
	v_mov_b32_e32 v22, v4
	v_mov_b32_e32 v23, v4
	v_mov_b32_e32 v24, v4
	v_mov_b32_e32 v25, v4
	v_mov_b32_e32 v26, v4
	v_mov_b32_e32 v27, v4
	s_waitcnt vmcnt(0)
	v_mov_b32_e32 v28, v4
	v_mov_b32_e32 v29, v4
	v_mov_b32_e32 v30, v4
	v_mov_b32_e32 v31, v4
	v_mov_b32_e32 v32, v4
	v_mov_b32_e32 v33, v4
	v_mov_b32_e32 v34, v4
	v_mov_b32_e32 v35, v4
	v_mov_b32_e32 v68, v4
	v_mov_b32_e32 v69, v4
	v_mov_b32_e32 v70, v4
	v_mov_b32_e32 v71, v4
	v_mov_b32_e32 v72, v4
	v_mov_b32_e32 v73, v4
	v_mov_b32_e32 v74, v4
	v_mov_b32_e32 v75, v4
	v_mov_b32_e32 v76, v4
	v_mov_b32_e32 v77, v4
	v_mov_b32_e32 v78, v4
	v_mov_b32_e32 v79, v4
	v_mov_b32_e32 v80, v4
	v_mov_b32_e32 v81, v4
	v_mov_b32_e32 v82, v4
	v_mov_b32_e32 v83, v4
	v_mov_b32_e32 v84, v4
	v_mov_b32_e32 v85, v4
	v_mov_b32_e32 v86, v4
	v_mov_b32_e32 v87, v4
	v_mov_b32_e32 v88, v4
	v_mov_b32_e32 v89, v4
	v_mov_b32_e32 v90, v4
	v_mov_b32_e32 v91, v4
	v_mov_b32_e32 v92, v4
	v_mov_b32_e32 v93, v4
	v_mov_b32_e32 v94, v4
	v_mov_b32_e32 v95, v4
	v_mov_b32_e32 v96, v4
	v_mov_b32_e32 v97, v4
	v_mov_b32_e32 v98, v4
	v_mov_b32_e32 v99, v4
	v_mov_b32_e32 v36, v4
	v_mov_b32_e32 v37, v4
	v_mov_b32_e32 v38, v4
	v_mov_b32_e32 v39, v4
	v_mov_b32_e32 v40, v4
	v_mov_b32_e32 v41, v4
	v_mov_b32_e32 v42, v4
	v_mov_b32_e32 v43, v4
	v_mov_b32_e32 v44, v4
	v_mov_b32_e32 v45, v4
	v_mov_b32_e32 v46, v4
	v_mov_b32_e32 v47, v4
	v_mov_b32_e32 v48, v4
	v_mov_b32_e32 v49, v4
	v_mov_b32_e32 v50, v4
	v_mov_b32_e32 v51, v4
	v_mov_b32_e32 v52, v4
	v_mov_b32_e32 v53, v4
	v_mov_b32_e32 v54, v4
	v_mov_b32_e32 v55, v4
	v_mov_b32_e32 v56, v4
	v_mov_b32_e32 v57, v4
	v_mov_b32_e32 v58, v4
	v_mov_b32_e32 v59, v4
	v_mov_b32_e32 v60, v4
	v_mov_b32_e32 v61, v4
	v_mov_b32_e32 v62, v4
	v_mov_b32_e32 v63, v4
	v_mov_b32_e32 v64, v4
	v_mov_b32_e32 v65, v4
	v_mov_b32_e32 v66, v4
	v_mov_b32_e32 v67, v4
	v_mov_b32_e32 v108, v4
	v_mov_b32_e32 v109, v4
	v_mov_b32_e32 v110, v4
	v_mov_b32_e32 v111, v4
	v_mov_b32_e32 v112, v4
	v_mov_b32_e32 v113, v4
	v_mov_b32_e32 v114, v4
	v_mov_b32_e32 v115, v4
	v_mov_b32_e32 v116, v4
	v_mov_b32_e32 v117, v4
	v_mov_b32_e32 v118, v4
	v_mov_b32_e32 v119, v4
	v_mov_b32_e32 v120, v4
	v_mov_b32_e32 v121, v4
	v_mov_b32_e32 v122, v4
	v_mov_b32_e32 v123, v4
	v_mov_b32_e32 v124, v4
	v_mov_b32_e32 v125, v4
	v_mov_b32_e32 v126, v4
	v_mov_b32_e32 v127, v4
	v_mov_b32_e32 v128, v4
	v_mov_b32_e32 v129, v4
	v_mov_b32_e32 v130, v4
	v_mov_b32_e32 v131, v4
	v_mov_b32_e32 v132, v4
	v_mov_b32_e32 v133, v4
	v_mov_b32_e32 v134, v4
	v_mov_b32_e32 v135, v4
	v_mov_b32_e32 v136, v4
	v_mov_b32_e32 v137, v4
	v_mov_b32_e32 v138, v4
	v_mov_b32_e32 v139, v4
	v_readfirstlane_b32 s101, v172
	s_nop 3
	s_cmp_ge_u32 s101, 0x100
	s_cbranch_scc1 .Lprio_hi_407
	s_setprio 0
	s_branch .Lprio_done_407

; #define PG8_STAGE(bufoff, gbase, voff) do { _Pragma("unroll") for (int _i = 0; _i < 2; ++_i) \
;         __builtin_amdgcn_global_load_lds((const unsigned*)((const char*)(gbase) + (voff)[_i]), (PG8_LAS unsigned*)(lds + (bufoff) + ldsw + _i * 8192), 16, 0, 0); } while (0)
; #define PG8_LDA(dst, b, h) do { _Pragma("unroll") for (int m = 0; m < 4; ++m) _Pragma("unroll") for (int k = 0; k < 2; ++k) dst[m][k] = *(const PG8_LAS bf16x8*)(lds + PG8_SA(b, h) + aoff + m * 2048 + k * 1024); } while (0)
; #define PG8_LDB(dst, b, h) do { _Pragma("unroll") for (int n = 0; n < 2; ++n) _Pragma("unroll") for (int k = 0; k < 2; ++k) dst[n][k] = *(const PG8_LAS bf16x8*)(lds + PG8_SB(b, h) + boff + n * 2048 + k * 1024); } while (0)
; #define PG8_MMA(ai, bj, At, Bt) do { __builtin_amdgcn_s_setprio(1); _Pragma("unroll") for (int m = 0; m < 4; ++m) _Pragma("unroll") for (int n = 0; n < 2; ++n) _Pragma("unroll") for (int k = 0; k < 2; ++k) \
;         acc[ai][bj][m][n] = __builtin_amdgcn_mfma_f32_16x16x32_bf16(Bt[n][k], At[m][k], acc[ai][bj][m][n], 0, 0, 0); __builtin_amdgcn_s_setprio(0); } while (0)
; #define PG8_WAIT_V(n) asm volatile("s_waitcnt vmcnt(" #n ")" ::: "memory")
; #define PG8_BAR __builtin_amdgcn_s_barrier()
; template <class Epi, class Sched, bool ALIGN_EPI = false, bool SP2 = false>
; __device__ __forceinline__ void gemm_phase(PG8_LAS unsigned char* lds, const Gemm g, const Sched& S, const Epi& E) {
;     ...
;         for (int t = 0; t < nt; t += 2) {
;             const bool last = (t == nt - 2);
;             const char* a1 = cA + (size_t)(t + 1) * kstep;
;             const char* a2 = last ? nA : cA + (size_t)(t + 2) * kstep; const char* b2 = last ? nB : cB + (size_t)(t + 2) * kstep;
;             const char* a3 = a2 + kstep; const char* b3 = b2 + kstep;
;             if (last && has_next) S.a_ready(nxt);
;             if constexpr (SP2) {
;             PG8_LDB(B0, 0, 0); PG8_LDB(B1, 0, 1); PG8_SCHED; PG8_LDA(At, 0, 0); PG8_STAGE(PG8_SA(1, 1), a1 + hstep, voffA);
;             PG8_WAIT_V(8); PG8_WAIT_L(0); PG8_BAR; PG8_MMA(0, 0, At, B0); PG8_MMA(0, 1, At, B1); PG8_BAR; PG8_SCHED;
;             PG8_LDA(At, 0, 1); PG8_STAGE(PG8_SB(0, 0), b2, voffB); PG8_STAGE(PG8_SB(0, 1), b2 + hstep, voffB); PG8_STAGE(PG8_SA(0, 0), a2, voffA);
;             PG8_WAIT_V(8); PG8_WAIT_L(0); PG8_BAR; PG8_MMA(1, 0, At, B0); PG8_MMA(1, 1, At, B1); PG8_BAR; PG8_SCHED;
.Lprio_done_407:
.LBB0_407:
	s_add_u32 s14, s0, 0xfff80080
	s_addc_u32 s15, s1, -1
	s_add_i32 s59, 0, 0x10000
	s_cmp_eq_u32 s58, 28
	s_cselect_b32 s17, s23, s15
	s_cselect_b32 s16, s24, s14
	s_cselect_b32 s15, s25, s57
	s_cselect_b32 s14, s49, s51
	s_add_i32 s62, 0, 0x14000
	v_add_u32_e32 v154, s59, v171
	v_add_u32_e32 v185, s62, v171
	ds_read_b128 v[100:103], v154
	ds_read_b128 v[104:107], v154 offset:1024
	ds_read_b128 v[140:143], v154 offset:2048
	ds_read_b128 v[154:157], v154 offset:3072
	ds_read_b128 v[158:161], v185
	ds_read_b128 v[162:165], v185 offset:1024
	ds_read_b128 v[166:169], v185 offset:2048
	ds_read_b128 v[186:189], v185 offset:3072
	v_lshl_add_u64 v[222:223], s[0:1], 0, v[152:153]
	s_add_i32 m0, s29, 0xc000
	ds_read_b128 v[190:193], v184
	ds_read_b128 v[194:197], v184 offset:1024
	ds_read_b128 v[198:201], v184 offset:2048
	ds_read_b128 v[202:205], v184 offset:3072
	ds_read_b128 v[206:209], v184 offset:4096
	ds_read_b128 v[210:213], v184 offset:5120
	ds_read_b128 v[214:217], v184 offset:6144
	ds_read_b128 v[218:221], v184 offset:7168
	global_load_lds_dwordx4 v[222:223], off
	v_lshl_add_u64 v[222:223], s[0:1], 0, v[150:151]
	s_add_i32 m0, s29, 0xe000
	s_nop 0
	global_load_lds_dwordx4 v[222:223], off
	s_waitcnt vmcnt(8)
	s_waitcnt lgkmcnt(0)
	s_barrier
	s_waitcnt lgkmcnt(0)
	v_mfma_f32_16x16x32_bf16 v[136:139], v[100:103], v[190:193], v[136:139]
	v_mfma_f32_16x16x32_bf16 v[132:135], v[140:143], v[190:193], v[132:135]
	v_mfma_f32_16x16x32_bf16 v[128:131], v[100:103], v[198:201], v[128:131]
	v_mfma_f32_16x16x32_bf16 v[124:127], v[140:143], v[198:201], v[124:127]
	v_mfma_f32_16x16x32_bf16 v[120:123], v[100:103], v[206:209], v[120:123]
	v_mfma_f32_16x16x32_bf16 v[116:119], v[140:143], v[206:209], v[116:119]
	v_mfma_f32_16x16x32_bf16 v[112:115], v[100:103], v[214:217], v[112:115]
	v_mfma_f32_16x16x32_bf16 v[108:111], v[140:143], v[214:217], v[108:111]
	v_mfma_f32_16x16x32_bf16 v[136:139], v[104:107], v[194:197], v[136:139]
	v_mfma_f32_16x16x32_bf16 v[132:135], v[154:157], v[194:197], v[132:135]
	v_mfma_f32_16x16x32_bf16 v[128:131], v[104:107], v[202:205], v[128:131]
	v_mfma_f32_16x16x32_bf16 v[124:127], v[154:157], v[202:205], v[124:127]
	v_mfma_f32_16x16x32_bf16 v[120:123], v[104:107], v[210:213], v[120:123]
	v_mfma_f32_16x16x32_bf16 v[116:119], v[154:157], v[210:213], v[116:119]
	v_mfma_f32_16x16x32_bf16 v[112:115], v[104:107], v[218:221], v[112:115]
	v_mfma_f32_16x16x32_bf16 v[108:111], v[154:157], v[218:221], v[108:111]
	v_mfma_f32_16x16x32_bf16 v[64:67], v[158:161], v[190:193], v[64:67]
	v_mfma_f32_16x16x32_bf16 v[60:63], v[166:169], v[190:193], v[60:63]
	v_mfma_f32_16x16x32_bf16 v[56:59], v[158:161], v[198:201], v[56:59]
	v_mfma_f32_16x16x32_bf16 v[52:55], v[166:169], v[198:201], v[52:55]
	v_mfma_f32_16x16x32_bf16 v[48:51], v[158:161], v[206:209], v[48:51]
	v_mfma_f32_16x16x32_bf16 v[44:47], v[166:169], v[206:209], v[44:47]
	v_mfma_f32_16x16x32_bf16 v[40:43], v[158:161], v[214:217], v[40:43]
	v_mfma_f32_16x16x32_bf16 v[36:39], v[166:169], v[214:217], v[36:39]
	v_mfma_f32_16x16x32_bf16 v[64:67], v[162:165], v[194:197], v[64:67]
	v_mfma_f32_16x16x32_bf16 v[60:63], v[186:189], v[194:197], v[60:63]
	v_mfma_f32_16x16x32_bf16 v[56:59], v[162:165], v[202:205], v[56:59]
	v_mfma_f32_16x16x32_bf16 v[52:55], v[186:189], v[202:205], v[52:55]
	v_mfma_f32_16x16x32_bf16 v[48:51], v[162:165], v[210:213], v[48:51]
	v_mfma_f32_16x16x32_bf16 v[44:47], v[186:189], v[210:213], v[44:47]
	v_mfma_f32_16x16x32_bf16 v[40:43], v[162:165], v[218:221], v[40:43]
	v_mfma_f32_16x16x32_bf16 v[36:39], v[186:189], v[218:221], v[36:39]
	s_barrier
	s_add_i32 s59, s59, s28
	v_lshl_add_u64 v[222:223], s[14:15], 0, v[174:175]
	s_mov_b32 m0, s59
	ds_read_b128 v[190:193], v184 offset:16384
	ds_read_b128 v[194:197], v184 offset:17408
	ds_read_b128 v[198:201], v184 offset:18432
	ds_read_b128 v[202:205], v184 offset:19456
	ds_read_b128 v[206:209], v184 offset:20480
	ds_read_b128 v[210:213], v184 offset:21504
	ds_read_b128 v[214:217], v184 offset:22528
	ds_read_b128 v[218:221], v184 offset:23552
	global_load_lds_dwordx4 v[222:223], off
	s_add_i32 m0, s59, 0x2000
	s_add_u32 s60, s14, 0x80000
	v_lshl_add_u64 v[224:225], s[14:15], 0, v[144:145]
	s_addc_u32 s61, s15, 0
	s_add_i32 s59, s62, s28
	global_load_lds_dwordx4 v[224:225], off
	v_lshl_add_u64 v[226:227], s[60:61], 0, v[174:175]
	s_mov_b32 m0, s59
	v_lshl_add_u64 v[228:229], s[16:17], 0, v[146:147]
	global_load_lds_dwordx4 v[226:227], off
	v_lshl_add_u64 v[226:227], s[60:61], 0, v[144:145]
	s_add_i32 m0, s59, 0x2000
	s_nop 0
	global_load_lds_dwordx4 v[226:227], off
	v_lshl_add_u64 v[226:227], s[16:17], 0, v[148:149]
	s_mov_b32 m0, s29
	s_nop 0
	global_load_lds_dwordx4 v[226:227], off
	s_mov_b32 m0, s30
	s_nop 0
	global_load_lds_dwordx4 v[228:229], off
	s_waitcnt vmcnt(8)
	s_waitcnt lgkmcnt(0)
	s_barrier
; #define PG8_STAGE(bufoff, gbase, voff) do { _Pragma("unroll") for (int _i = 0; _i < 2; ++_i) \
;         __builtin_amdgcn_global_load_lds((const unsigned*)((const char*)(gbase) + (voff)[_i]), (PG8_LAS unsigned*)(lds + (bufoff) + ldsw + _i * 8192), 16, 0, 0); } while (0)
; #define PG8_LDA(dst, b, h) do { _Pragma("unroll") for (int m = 0; m < 4; ++m) _Pragma("unroll") for (int k = 0; k < 2; ++k) dst[m][k] = *(const PG8_LAS bf16x8*)(lds + PG8_SA(b, h) + aoff + m * 2048 + k * 1024); } while (0)
; #define PG8_LDB(dst, b, h) do { _Pragma("unroll") for (int n = 0; n < 2; ++n) _Pragma("unroll") for (int k = 0; k < 2; ++k) dst[n][k] = *(const PG8_LAS bf16x8*)(lds + PG8_SB(b, h) + boff + n * 2048 + k * 1024); } while (0)
; #define PG8_MMA(ai, bj, At, Bt) do { __builtin_amdgcn_s_setprio(1); _Pragma("unroll") for (int m = 0; m < 4; ++m) _Pragma("unroll") for (int n = 0; n < 2; ++n) _Pragma("unroll") for (int k = 0; k < 2; ++k) \
;         acc[ai][bj][m][n] = __builtin_amdgcn_mfma_f32_16x16x32_bf16(Bt[n][k], At[m][k], acc[ai][bj][m][n], 0, 0, 0); __builtin_amdgcn_s_setprio(0); } while (0)
; #define PG8_WAIT_V(n) asm volatile("s_waitcnt vmcnt(" #n ")" ::: "memory")
; #define PG8_WAIT_L(n) asm volatile("s_waitcnt lgkmcnt(" #n ")" ::: "memory")
; #define PG8_BAR __builtin_amdgcn_s_barrier()
; #define PG8_SCHED __builtin_amdgcn_sched_barrier(0)
; template <class Epi, class Sched, bool ALIGN_EPI = false, bool SP2 = false>
; __device__ __forceinline__ void gemm_phase(PG8_LAS unsigned char* lds, const Gemm g, const Sched& S, const Epi& E) {
;     ...
;             PG8_WAIT_V(8); PG8_WAIT_L(0); PG8_BAR; PG8_MMA(1, 0, At, B0); PG8_MMA(1, 1, At, B1); PG8_BAR; PG8_SCHED;
;             PG8_LDB(B0, 1, 0); PG8_LDB(B1, 1, 1); PG8_SCHED; PG8_LDA(At, 1, 0); PG8_STAGE(PG8_SA(0, 1), a2 + hstep, voffA);
;             PG8_WAIT_V(8); PG8_WAIT_L(0); PG8_BAR; PG8_MMA(0, 0, At, B0); PG8_MMA(0, 1, At, B1); PG8_BAR; PG8_SCHED;
	s_waitcnt lgkmcnt(0)
	v_mfma_f32_16x16x32_bf16 v[96:99], v[100:103], v[190:193], v[96:99]
	v_mfma_f32_16x16x32_bf16 v[92:95], v[140:143], v[190:193], v[92:95]
	v_mfma_f32_16x16x32_bf16 v[88:91], v[100:103], v[198:201], v[88:91]
	v_mfma_f32_16x16x32_bf16 v[84:87], v[140:143], v[198:201], v[84:87]
	v_mfma_f32_16x16x32_bf16 v[80:83], v[100:103], v[206:209], v[80:83]
	v_mfma_f32_16x16x32_bf16 v[76:79], v[140:143], v[206:209], v[76:79]
	v_mfma_f32_16x16x32_bf16 v[72:75], v[100:103], v[214:217], v[72:75]
	v_mfma_f32_16x16x32_bf16 v[68:71], v[140:143], v[214:217], v[68:71]
	v_mfma_f32_16x16x32_bf16 v[96:99], v[104:107], v[194:197], v[96:99]
	v_mfma_f32_16x16x32_bf16 v[92:95], v[154:157], v[194:197], v[92:95]
	v_mfma_f32_16x16x32_bf16 v[88:91], v[104:107], v[202:205], v[88:91]
	v_mfma_f32_16x16x32_bf16 v[84:87], v[154:157], v[202:205], v[84:87]
	v_mfma_f32_16x16x32_bf16 v[80:83], v[104:107], v[210:213], v[80:83]
	v_mfma_f32_16x16x32_bf16 v[76:79], v[154:157], v[210:213], v[76:79]
	v_mfma_f32_16x16x32_bf16 v[72:75], v[104:107], v[218:221], v[72:75]
	v_mfma_f32_16x16x32_bf16 v[68:71], v[154:157], v[218:221], v[68:71]
	v_mfma_f32_16x16x32_bf16 v[32:35], v[158:161], v[190:193], v[32:35]
	v_mfma_f32_16x16x32_bf16 v[28:31], v[166:169], v[190:193], v[28:31]
	v_mfma_f32_16x16x32_bf16 v[24:27], v[158:161], v[198:201], v[24:27]
	v_mfma_f32_16x16x32_bf16 v[20:23], v[166:169], v[198:201], v[20:23]
	v_mfma_f32_16x16x32_bf16 v[16:19], v[158:161], v[206:209], v[16:19]
	v_mfma_f32_16x16x32_bf16 v[12:15], v[166:169], v[206:209], v[12:15]
	v_mfma_f32_16x16x32_bf16 v[8:11], v[158:161], v[214:217], v[8:11]
	v_mfma_f32_16x16x32_bf16 v[4:7], v[166:169], v[214:217], v[4:7]
	v_mfma_f32_16x16x32_bf16 v[32:35], v[162:165], v[194:197], v[32:35]
	v_mfma_f32_16x16x32_bf16 v[28:31], v[186:189], v[194:197], v[28:31]
	v_mfma_f32_16x16x32_bf16 v[24:27], v[162:165], v[202:205], v[24:27]
	v_mfma_f32_16x16x32_bf16 v[20:23], v[186:189], v[202:205], v[20:23]
	v_mfma_f32_16x16x32_bf16 v[16:19], v[162:165], v[210:213], v[16:19]
	v_mfma_f32_16x16x32_bf16 v[12:15], v[186:189], v[210:213], v[12:15]
	v_mfma_f32_16x16x32_bf16 v[8:11], v[162:165], v[218:221], v[8:11]
	v_mfma_f32_16x16x32_bf16 v[4:7], v[186:189], v[218:221], v[4:7]
	s_barrier
	s_add_i32 s59, 0, 0x18000
	s_add_i32 s60, 0, 0x1c000
	v_add_u32_e32 v154, s59, v171
	v_add_u32_e32 v185, s60, v171
	ds_read_b128 v[100:103], v154
	ds_read_b128 v[104:107], v154 offset:1024
	ds_read_b128 v[140:143], v154 offset:2048
	ds_read_b128 v[154:157], v154 offset:3072
	ds_read_b128 v[158:161], v185
	ds_read_b128 v[162:165], v185 offset:1024
	ds_read_b128 v[166:169], v185 offset:2048
	ds_read_b128 v[186:189], v185 offset:3072
	s_add_u32 s16, s16, 0x80000
	s_addc_u32 s17, s17, 0
	s_mov_b32 m0, s31
	v_lshl_add_u64 v[230:231], s[16:17], 0, v[148:149]
	ds_read_b128 v[190:193], v184 offset:32768
	ds_read_b128 v[194:197], v184 offset:33792
	ds_read_b128 v[198:201], v184 offset:34816
	ds_read_b128 v[202:205], v184 offset:35840
	ds_read_b128 v[206:209], v184 offset:36864
	ds_read_b128 v[210:213], v184 offset:37888
	ds_read_b128 v[214:217], v184 offset:38912
	ds_read_b128 v[218:221], v184 offset:39936
	global_load_lds_dwordx4 v[230:231], off
	v_lshl_add_u64 v[230:231], s[16:17], 0, v[146:147]
	s_mov_b32 m0, s34
	s_nop 0
	global_load_lds_dwordx4 v[230:231], off
	s_waitcnt vmcnt(8)
	s_waitcnt lgkmcnt(0)
	s_barrier
	s_waitcnt lgkmcnt(0)
	v_mfma_f32_16x16x32_bf16 v[136:139], v[100:103], v[190:193], v[136:139]
	v_mfma_f32_16x16x32_bf16 v[132:135], v[140:143], v[190:193], v[132:135]
	v_mfma_f32_16x16x32_bf16 v[128:131], v[100:103], v[198:201], v[128:131]
	v_mfma_f32_16x16x32_bf16 v[124:127], v[140:143], v[198:201], v[124:127]
	v_mfma_f32_16x16x32_bf16 v[120:123], v[100:103], v[206:209], v[120:123]
	v_mfma_f32_16x16x32_bf16 v[116:119], v[140:143], v[206:209], v[116:119]
	v_mfma_f32_16x16x32_bf16 v[112:115], v[100:103], v[214:217], v[112:115]
	v_mfma_f32_16x16x32_bf16 v[108:111], v[140:143], v[214:217], v[108:111]
	v_mfma_f32_16x16x32_bf16 v[136:139], v[104:107], v[194:197], v[136:139]
	v_mfma_f32_16x16x32_bf16 v[132:135], v[154:157], v[194:197], v[132:135]
	v_mfma_f32_16x16x32_bf16 v[128:131], v[104:107], v[202:205], v[128:131]
	v_mfma_f32_16x16x32_bf16 v[124:127], v[154:157], v[202:205], v[124:127]
	v_mfma_f32_16x16x32_bf16 v[120:123], v[104:107], v[210:213], v[120:123]
	v_mfma_f32_16x16x32_bf16 v[116:119], v[154:157], v[210:213], v[116:119]
	v_mfma_f32_16x16x32_bf16 v[112:115], v[104:107], v[218:221], v[112:115]
	v_mfma_f32_16x16x32_bf16 v[108:111], v[154:157], v[218:221], v[108:111]
	v_mfma_f32_16x16x32_bf16 v[64:67], v[158:161], v[190:193], v[64:67]
	v_mfma_f32_16x16x32_bf16 v[60:63], v[166:169], v[190:193], v[60:63]
	v_mfma_f32_16x16x32_bf16 v[56:59], v[158:161], v[198:201], v[56:59]
	v_mfma_f32_16x16x32_bf16 v[52:55], v[166:169], v[198:201], v[52:55]
	v_mfma_f32_16x16x32_bf16 v[48:51], v[158:161], v[206:209], v[48:51]
	v_mfma_f32_16x16x32_bf16 v[44:47], v[166:169], v[206:209], v[44:47]
	v_mfma_f32_16x16x32_bf16 v[40:43], v[158:161], v[214:217], v[40:43]
	v_mfma_f32_16x16x32_bf16 v[36:39], v[166:169], v[214:217], v[36:39]
	v_mfma_f32_16x16x32_bf16 v[64:67], v[162:165], v[194:197], v[64:67]
	v_mfma_f32_16x16x32_bf16 v[60:63], v[186:189], v[194:197], v[60:63]
	v_mfma_f32_16x16x32_bf16 v[56:59], v[162:165], v[202:205], v[56:59]
	v_mfma_f32_16x16x32_bf16 v[52:55], v[186:189], v[202:205], v[52:55]
	v_mfma_f32_16x16x32_bf16 v[48:51], v[162:165], v[210:213], v[48:51]
	v_mfma_f32_16x16x32_bf16 v[44:47], v[186:189], v[210:213], v[44:47]
	v_mfma_f32_16x16x32_bf16 v[40:43], v[162:165], v[218:221], v[40:43]
	v_mfma_f32_16x16x32_bf16 v[36:39], v[186:189], v[218:221], v[36:39]
	s_barrier
; #define PG8_STAGE(bufoff, gbase, voff) do { _Pragma("unroll") for (int _i = 0; _i < 2; ++_i) \
;         __builtin_amdgcn_global_load_lds((const unsigned*)((const char*)(gbase) + (voff)[_i]), (PG8_LAS unsigned*)(lds + (bufoff) + ldsw + _i * 8192), 16, 0, 0); } while (0)
; #define PG8_LDA(dst, b, h) do { _Pragma("unroll") for (int m = 0; m < 4; ++m) _Pragma("unroll") for (int k = 0; k < 2; ++k) dst[m][k] = *(const PG8_LAS bf16x8*)(lds + PG8_SA(b, h) + aoff + m * 2048 + k * 1024); } while (0)
; #define PG8_MMA(ai, bj, At, Bt) do { __builtin_amdgcn_s_setprio(1); _Pragma("unroll") for (int m = 0; m < 4; ++m) _Pragma("unroll") for (int n = 0; n < 2; ++n) _Pragma("unroll") for (int k = 0; k < 2; ++k) \
;         acc[ai][bj][m][n] = __builtin_amdgcn_mfma_f32_16x16x32_bf16(Bt[n][k], At[m][k], acc[ai][bj][m][n], 0, 0, 0); __builtin_amdgcn_s_setprio(0); } while (0)
; #define PG8_WAIT_V(n) asm volatile("s_waitcnt vmcnt(" #n ")" ::: "memory")
; #define PG8_WAIT_L(n) asm volatile("s_waitcnt lgkmcnt(" #n ")" ::: "memory")
; #define PG8_BAR __builtin_amdgcn_s_barrier()
; #define PG8_SCHED __builtin_amdgcn_sched_barrier(0)
; template <class Epi, class Sched, bool ALIGN_EPI = false, bool SP2 = false>
; __device__ __forceinline__ void gemm_phase(PG8_LAS unsigned char* lds, const Gemm g, const Sched& S, const Epi& E) {
;     ...
;         for (int t = 0; t < nt; t += 2) {
;     ...
;             PG8_LDA(At, 1, 1); PG8_STAGE(PG8_SB(1, 0), b3, voffB); PG8_STAGE(PG8_SB(1, 1), b3 + hstep, voffB); PG8_STAGE(PG8_SA(1, 0), a3, voffA);
;             PG8_WAIT_V(8); PG8_WAIT_L(0); PG8_BAR; PG8_MMA(1, 0, At, B0); PG8_MMA(1, 1, At, B1); PG8_BAR; PG8_SCHED;
	s_add_i32 s16, s59, s28
	v_lshl_add_u64 v[222:223], v[222:223], 0, s[10:11]
	s_mov_b32 m0, s16
	ds_read_b128 v[190:193], v184 offset:49152
	ds_read_b128 v[194:197], v184 offset:50176
	ds_read_b128 v[198:201], v184 offset:51200
	ds_read_b128 v[202:205], v184 offset:52224
	ds_read_b128 v[206:209], v184 offset:53248
	ds_read_b128 v[210:213], v184 offset:54272
	ds_read_b128 v[214:217], v184 offset:55296
	ds_read_b128 v[218:221], v184 offset:56320
	global_load_lds_dwordx4 v[222:223], off
	s_add_i32 m0, s16, 0x2000
	s_add_u32 s14, s14, 0x80080
	v_lshl_add_u64 v[222:223], v[224:225], 0, s[10:11]
	s_addc_u32 s15, s15, 0
	s_add_i32 s16, s60, s28
	global_load_lds_dwordx4 v[222:223], off
	v_lshl_add_u64 v[222:223], s[14:15], 0, v[174:175]
	s_mov_b32 m0, s16
	s_nop 0
	global_load_lds_dwordx4 v[222:223], off
	v_lshl_add_u64 v[222:223], s[14:15], 0, v[144:145]
	s_add_i32 m0, s16, 0x2000
	s_nop 0
	global_load_lds_dwordx4 v[222:223], off
	v_lshl_add_u64 v[222:223], v[226:227], 0, s[10:11]
	s_mov_b32 m0, s35
	s_nop 0
	global_load_lds_dwordx4 v[222:223], off
	v_lshl_add_u64 v[222:223], v[228:229], 0, s[10:11]
	s_mov_b32 m0, s38
	s_nop 0
	global_load_lds_dwordx4 v[222:223], off
	s_waitcnt vmcnt(8)
	s_waitcnt lgkmcnt(0)
	s_barrier
	s_waitcnt lgkmcnt(0)
	v_mfma_f32_16x16x32_bf16 v[96:99], v[100:103], v[190:193], v[96:99]
	v_mfma_f32_16x16x32_bf16 v[92:95], v[140:143], v[190:193], v[92:95]
	v_mfma_f32_16x16x32_bf16 v[88:91], v[100:103], v[198:201], v[88:91]
	v_mfma_f32_16x16x32_bf16 v[84:87], v[140:143], v[198:201], v[84:87]
	v_mfma_f32_16x16x32_bf16 v[80:83], v[100:103], v[206:209], v[80:83]
	v_mfma_f32_16x16x32_bf16 v[76:79], v[140:143], v[206:209], v[76:79]
	v_mfma_f32_16x16x32_bf16 v[72:75], v[100:103], v[214:217], v[72:75]
	v_mfma_f32_16x16x32_bf16 v[68:71], v[140:143], v[214:217], v[68:71]
	v_mfma_f32_16x16x32_bf16 v[96:99], v[104:107], v[194:197], v[96:99]
	v_mfma_f32_16x16x32_bf16 v[92:95], v[154:157], v[194:197], v[92:95]
	v_mfma_f32_16x16x32_bf16 v[88:91], v[104:107], v[202:205], v[88:91]
	v_mfma_f32_16x16x32_bf16 v[84:87], v[154:157], v[202:205], v[84:87]
	v_mfma_f32_16x16x32_bf16 v[80:83], v[104:107], v[210:213], v[80:83]
	v_mfma_f32_16x16x32_bf16 v[76:79], v[154:157], v[210:213], v[76:79]
	v_mfma_f32_16x16x32_bf16 v[72:75], v[104:107], v[218:221], v[72:75]
	v_mfma_f32_16x16x32_bf16 v[68:71], v[154:157], v[218:221], v[68:71]
	v_mfma_f32_16x16x32_bf16 v[32:35], v[158:161], v[190:193], v[32:35]
	v_mfma_f32_16x16x32_bf16 v[28:31], v[166:169], v[190:193], v[28:31]
	v_mfma_f32_16x16x32_bf16 v[24:27], v[158:161], v[198:201], v[24:27]
	v_mfma_f32_16x16x32_bf16 v[20:23], v[166:169], v[198:201], v[20:23]
	v_mfma_f32_16x16x32_bf16 v[16:19], v[158:161], v[206:209], v[16:19]
	v_mfma_f32_16x16x32_bf16 v[12:15], v[166:169], v[206:209], v[12:15]
	v_mfma_f32_16x16x32_bf16 v[8:11], v[158:161], v[214:217], v[8:11]
	v_mfma_f32_16x16x32_bf16 v[4:7], v[166:169], v[214:217], v[4:7]
	v_mfma_f32_16x16x32_bf16 v[32:35], v[162:165], v[194:197], v[32:35]
	v_mfma_f32_16x16x32_bf16 v[28:31], v[186:189], v[194:197], v[28:31]
	v_mfma_f32_16x16x32_bf16 v[24:27], v[162:165], v[202:205], v[24:27]
	v_mfma_f32_16x16x32_bf16 v[20:23], v[186:189], v[202:205], v[20:23]
	v_mfma_f32_16x16x32_bf16 v[16:19], v[162:165], v[210:213], v[16:19]
	v_mfma_f32_16x16x32_bf16 v[12:15], v[186:189], v[210:213], v[12:15]
	v_mfma_f32_16x16x32_bf16 v[8:11], v[162:165], v[218:221], v[8:11]
	v_mfma_f32_16x16x32_bf16 v[4:7], v[186:189], v[218:221], v[4:7]
	s_barrier
	s_add_i32 s58, s58, 2
	s_add_u32 s51, s51, 0x100
	s_addc_u32 s57, s57, 0
	s_add_u32 s0, s0, 0x100
	s_addc_u32 s1, s1, 0
	s_cmp_gt_u32 s58, 29
	s_cbranch_scc0 .LBB0_407
	s_and_b64 vcc, exec, s[46:47]
	s_cbranch_vccz .LBB0_410
	s_barrier

; template <class Epi, class Sched, bool ALIGN_EPI = false, bool SP2 = false>
; __device__ __forceinline__ void gemm_phase(PG8_LAS unsigned char* lds, const Gemm g, const Sched& S, const Epi& E) {
;     ...
;         const bool has_next = S.next(ui + 1, nxt);
;         const char* nA = has_next ? (const char*)g.A + (size_t)nxt.pm * tstep : cA; const char* nB = has_next ? (const char*)g.Bt + (size_t)nxt.pn * tstep : cB;
;         for (int t = 0; t < nt; t += 2) {
;             const bool last = (t == nt - 2);
;             const char* a1 = cA + (size_t)(t + 1) * kstep;
;             const char* a2 = last ? nA : cA + (size_t)(t + 2) * kstep; const char* b2 = last ? nB : cB + (size_t)(t + 2) * kstep;
;     ...
; #pragma unroll
;         for (int a = 0; a < 2; ++a)
; #pragma unroll
;             for (int b = 0; b < 2; ++b)
; #pragma unroll
;                 for (int m = 0; m < 4; ++m)
; #pragma unroll
;                     for (int n = 0; n < 2; ++n) acc[a][b][m][n] = (f32x4){0.f, 0.f, 0.f, 0.f};
.LBB0_484:
	s_ashr_i32 s53, s52, 31
	s_lshl_b64 s[16:17], s[52:53], 21
	s_add_u32 s54, s19, s16
	s_addc_u32 s55, s20, s17
	s_and_b64 s[16:17], s[40:41], exec
	s_cselect_b32 s23, s55, s15
	s_cselect_b32 s24, s54, s14
	s_ashr_i32 s51, s50, 31
	s_lshl_b64 s[16:17], s[50:51], 21
	s_add_u32 s56, s26, s16
	s_addc_u32 s57, s27, s17
	s_and_b64 s[16:17], s[40:41], exec
	s_cselect_b32 s25, s57, s1
	s_cselect_b32 s51, s56, s0
	s_add_u32 s53, s0, 0x100
	s_addc_u32 s59, s1, 0
	s_add_u32 s0, s14, 0x100080
	v_mov_b32_e32 v4, 0
	s_addc_u32 s1, s15, 0
	s_mov_b32 s60, -2
	v_mov_b32_e32 v5, v4
	v_mov_b32_e32 v6, v4
	v_mov_b32_e32 v7, v4
	v_mov_b32_e32 v8, v4
	v_mov_b32_e32 v9, v4
	v_mov_b32_e32 v10, v4
	v_mov_b32_e32 v11, v4
	v_mov_b32_e32 v12, v4
	v_mov_b32_e32 v13, v4
	v_mov_b32_e32 v14, v4
	v_mov_b32_e32 v15, v4
	v_mov_b32_e32 v16, v4
	v_mov_b32_e32 v17, v4
	v_mov_b32_e32 v18, v4
	v_mov_b32_e32 v19, v4
	v_mov_b32_e32 v20, v4
	v_mov_b32_e32 v21, v4
	v_mov_b32_e32 v22, v4
	v_mov_b32_e32 v23, v4
	v_mov_b32_e32 v24, v4
	v_mov_b32_e32 v25, v4
	v_mov_b32_e32 v26, v4
	v_mov_b32_e32 v27, v4
	s_waitcnt vmcnt(0)
	v_mov_b32_e32 v28, v4
	v_mov_b32_e32 v29, v4
	v_mov_b32_e32 v30, v4
	v_mov_b32_e32 v31, v4
	v_mov_b32_e32 v32, v4
	v_mov_b32_e32 v33, v4
	v_mov_b32_e32 v34, v4
	v_mov_b32_e32 v35, v4
	v_mov_b32_e32 v68, v4
	v_mov_b32_e32 v69, v4
	v_mov_b32_e32 v70, v4
	v_mov_b32_e32 v71, v4
	v_mov_b32_e32 v72, v4
	v_mov_b32_e32 v73, v4
	v_mov_b32_e32 v74, v4
	v_mov_b32_e32 v75, v4
	v_mov_b32_e32 v76, v4
	v_mov_b32_e32 v77, v4
	v_mov_b32_e32 v78, v4
	v_mov_b32_e32 v79, v4
	v_mov_b32_e32 v80, v4
	v_mov_b32_e32 v81, v4
	v_mov_b32_e32 v82, v4
	v_mov_b32_e32 v83, v4
	v_mov_b32_e32 v84, v4
	v_mov_b32_e32 v85, v4
	v_mov_b32_e32 v86, v4
	v_mov_b32_e32 v87, v4
	v_mov_b32_e32 v88, v4
	v_mov_b32_e32 v89, v4
	v_mov_b32_e32 v90, v4
	v_mov_b32_e32 v91, v4
	v_mov_b32_e32 v92, v4
	v_mov_b32_e32 v93, v4
	v_mov_b32_e32 v94, v4
	v_mov_b32_e32 v95, v4
	v_mov_b32_e32 v96, v4
	v_mov_b32_e32 v97, v4
	v_mov_b32_e32 v98, v4
	v_mov_b32_e32 v99, v4
	v_mov_b32_e32 v36, v4
	v_mov_b32_e32 v37, v4
	v_mov_b32_e32 v38, v4
	v_mov_b32_e32 v39, v4
	v_mov_b32_e32 v40, v4
	v_mov_b32_e32 v41, v4
	v_mov_b32_e32 v42, v4
	v_mov_b32_e32 v43, v4
	v_mov_b32_e32 v44, v4
	v_mov_b32_e32 v45, v4
	v_mov_b32_e32 v46, v4
	v_mov_b32_e32 v47, v4
	v_mov_b32_e32 v48, v4
	v_mov_b32_e32 v49, v4
	v_mov_b32_e32 v50, v4
	v_mov_b32_e32 v51, v4
	v_mov_b32_e32 v52, v4
	v_mov_b32_e32 v53, v4
	v_mov_b32_e32 v54, v4
	v_mov_b32_e32 v55, v4
	v_mov_b32_e32 v56, v4
	v_mov_b32_e32 v57, v4
	v_mov_b32_e32 v58, v4
	v_mov_b32_e32 v59, v4
	v_mov_b32_e32 v60, v4
	v_mov_b32_e32 v61, v4
	v_mov_b32_e32 v62, v4
	v_mov_b32_e32 v63, v4
	v_mov_b32_e32 v64, v4
	v_mov_b32_e32 v65, v4
	v_mov_b32_e32 v66, v4
	v_mov_b32_e32 v67, v4
	v_mov_b32_e32 v108, v4
	v_mov_b32_e32 v109, v4
	v_mov_b32_e32 v110, v4
	v_mov_b32_e32 v111, v4
	v_mov_b32_e32 v112, v4
	v_mov_b32_e32 v113, v4
	v_mov_b32_e32 v114, v4
	v_mov_b32_e32 v115, v4
	v_mov_b32_e32 v116, v4
	v_mov_b32_e32 v117, v4
	v_mov_b32_e32 v118, v4
	v_mov_b32_e32 v119, v4
	v_mov_b32_e32 v120, v4
	v_mov_b32_e32 v121, v4
	v_mov_b32_e32 v122, v4
	v_mov_b32_e32 v123, v4
	v_mov_b32_e32 v124, v4
	v_mov_b32_e32 v125, v4
	v_mov_b32_e32 v126, v4
	v_mov_b32_e32 v127, v4
	v_mov_b32_e32 v128, v4
	v_mov_b32_e32 v129, v4
	v_mov_b32_e32 v130, v4
	v_mov_b32_e32 v131, v4
	v_mov_b32_e32 v132, v4
	v_mov_b32_e32 v133, v4
	v_mov_b32_e32 v134, v4
	v_mov_b32_e32 v135, v4
	v_mov_b32_e32 v136, v4
	v_mov_b32_e32 v137, v4
	v_mov_b32_e32 v138, v4
	v_mov_b32_e32 v139, v4
	v_readfirstlane_b32 s101, v172
	s_nop 3
	s_cmp_ge_u32 s101, 0x100
	s_cbranch_scc1 .Lprio_hi_485
	s_setprio 0
	s_branch .Lprio_done_485

; #define PG8_STAGE(bufoff, gbase, voff) do { _Pragma("unroll") for (int _i = 0; _i < 2; ++_i) \
;         __builtin_amdgcn_global_load_lds((const unsigned*)((const char*)(gbase) + (voff)[_i]), (PG8_LAS unsigned*)(lds + (bufoff) + ldsw + _i * 8192), 16, 0, 0); } while (0)
; #define PG8_LDA(dst, b, h) do { _Pragma("unroll") for (int m = 0; m < 4; ++m) _Pragma("unroll") for (int k = 0; k < 2; ++k) dst[m][k] = *(const PG8_LAS bf16x8*)(lds + PG8_SA(b, h) + aoff + m * 2048 + k * 1024); } while (0)
; #define PG8_LDB(dst, b, h) do { _Pragma("unroll") for (int n = 0; n < 2; ++n) _Pragma("unroll") for (int k = 0; k < 2; ++k) dst[n][k] = *(const PG8_LAS bf16x8*)(lds + PG8_SB(b, h) + boff + n * 2048 + k * 1024); } while (0)
; #define PG8_MMA(ai, bj, At, Bt) do { __builtin_amdgcn_s_setprio(1); _Pragma("unroll") for (int m = 0; m < 4; ++m) _Pragma("unroll") for (int n = 0; n < 2; ++n) _Pragma("unroll") for (int k = 0; k < 2; ++k) \
;         acc[ai][bj][m][n] = __builtin_amdgcn_mfma_f32_16x16x32_bf16(Bt[n][k], At[m][k], acc[ai][bj][m][n], 0, 0, 0); __builtin_amdgcn_s_setprio(0); } while (0)
; #define PG8_WAIT_V(n) asm volatile("s_waitcnt vmcnt(" #n ")" ::: "memory")
; #define PG8_BAR __builtin_amdgcn_s_barrier()
; template <class Epi, class Sched, bool ALIGN_EPI = false, bool SP2 = false>
; __device__ __forceinline__ void gemm_phase(PG8_LAS unsigned char* lds, const Gemm g, const Sched& S, const Epi& E) {
;     ...
;         for (int t = 0; t < nt; t += 2) {
;             const bool last = (t == nt - 2);
;             const char* a1 = cA + (size_t)(t + 1) * kstep;
;             const char* a2 = last ? nA : cA + (size_t)(t + 2) * kstep; const char* b2 = last ? nB : cB + (size_t)(t + 2) * kstep;
;             const char* a3 = a2 + kstep; const char* b3 = b2 + kstep;
;             if (last && has_next) S.a_ready(nxt);
;             if constexpr (SP2) {
;             PG8_LDB(B0, 0, 0); PG8_LDB(B1, 0, 1); PG8_SCHED; PG8_LDA(At, 0, 0); PG8_STAGE(PG8_SA(1, 1), a1 + hstep, voffA);
;             PG8_WAIT_V(8); PG8_WAIT_L(0); PG8_BAR; PG8_MMA(0, 0, At, B0); PG8_MMA(0, 1, At, B1); PG8_BAR; PG8_SCHED;
;             PG8_LDA(At, 0, 1); PG8_STAGE(PG8_SB(0, 0), b2, voffB); PG8_STAGE(PG8_SB(0, 1), b2 + hstep, voffB); PG8_STAGE(PG8_SA(0, 0), a2, voffA);
;             PG8_WAIT_V(8); PG8_WAIT_L(0); PG8_BAR; PG8_MMA(1, 0, At, B0); PG8_MMA(1, 1, At, B1); PG8_BAR; PG8_SCHED;
.Lprio_done_485:
.LBB0_485:
	s_add_u32 s14, s0, 0xfff00080
	s_addc_u32 s15, s1, -1
	s_add_i32 s61, 0, 0x10000
	s_cmp_eq_u32 s60, 60
	s_cselect_b32 s17, s23, s15
	s_cselect_b32 s16, s24, s14
	s_cselect_b32 s15, s25, s59
	s_cselect_b32 s14, s51, s53
	s_add_i32 s64, 0, 0x14000
	v_add_u32_e32 v144, s61, v188
	v_add_u32_e32 v170, s64, v188
	ds_read_b128 v[100:103], v144
	ds_read_b128 v[104:107], v144 offset:1024
	ds_read_b128 v[140:143], v144 offset:2048
	ds_read_b128 v[144:147], v144 offset:3072
	ds_read_b128 v[158:161], v170
	ds_read_b128 v[162:165], v170 offset:1024
	ds_read_b128 v[166:169], v170 offset:2048
	ds_read_b128 v[184:187], v170 offset:3072
	v_lshl_add_u64 v[170:171], s[0:1], 0, v[156:157]
	s_add_i32 m0, s29, 0xc000
	ds_read_b128 v[192:195], v190
	ds_read_b128 v[196:199], v190 offset:1024
	ds_read_b128 v[200:203], v190 offset:2048
	ds_read_b128 v[204:207], v190 offset:3072
	ds_read_b128 v[208:211], v190 offset:4096
	ds_read_b128 v[212:215], v190 offset:5120
	ds_read_b128 v[216:219], v190 offset:6144
	ds_read_b128 v[220:223], v190 offset:7168
	global_load_lds_dwordx4 v[170:171], off
	v_lshl_add_u64 v[170:171], s[0:1], 0, v[154:155]
	s_add_i32 m0, s29, 0xe000
	s_nop 0
	global_load_lds_dwordx4 v[170:171], off
	s_waitcnt vmcnt(8)
	s_waitcnt lgkmcnt(0)
	s_barrier
	s_waitcnt lgkmcnt(0)
	v_mfma_f32_16x16x32_bf16 v[136:139], v[100:103], v[192:195], v[136:139]
	v_mfma_f32_16x16x32_bf16 v[132:135], v[140:143], v[192:195], v[132:135]
	v_mfma_f32_16x16x32_bf16 v[128:131], v[100:103], v[200:203], v[128:131]
	v_mfma_f32_16x16x32_bf16 v[124:127], v[140:143], v[200:203], v[124:127]
	v_mfma_f32_16x16x32_bf16 v[120:123], v[100:103], v[208:211], v[120:123]
	v_mfma_f32_16x16x32_bf16 v[116:119], v[140:143], v[208:211], v[116:119]
	v_mfma_f32_16x16x32_bf16 v[112:115], v[100:103], v[216:219], v[112:115]
	v_mfma_f32_16x16x32_bf16 v[108:111], v[140:143], v[216:219], v[108:111]
	v_mfma_f32_16x16x32_bf16 v[136:139], v[104:107], v[196:199], v[136:139]
	v_mfma_f32_16x16x32_bf16 v[132:135], v[144:147], v[196:199], v[132:135]
	v_mfma_f32_16x16x32_bf16 v[128:131], v[104:107], v[204:207], v[128:131]
	v_mfma_f32_16x16x32_bf16 v[124:127], v[144:147], v[204:207], v[124:127]
	v_mfma_f32_16x16x32_bf16 v[120:123], v[104:107], v[212:215], v[120:123]
	v_mfma_f32_16x16x32_bf16 v[116:119], v[144:147], v[212:215], v[116:119]
	v_mfma_f32_16x16x32_bf16 v[112:115], v[104:107], v[220:223], v[112:115]
	v_mfma_f32_16x16x32_bf16 v[108:111], v[144:147], v[220:223], v[108:111]
	v_mfma_f32_16x16x32_bf16 v[64:67], v[158:161], v[192:195], v[64:67]
	v_mfma_f32_16x16x32_bf16 v[60:63], v[166:169], v[192:195], v[60:63]
	v_mfma_f32_16x16x32_bf16 v[56:59], v[158:161], v[200:203], v[56:59]
	v_mfma_f32_16x16x32_bf16 v[52:55], v[166:169], v[200:203], v[52:55]
	v_mfma_f32_16x16x32_bf16 v[48:51], v[158:161], v[208:211], v[48:51]
	v_mfma_f32_16x16x32_bf16 v[44:47], v[166:169], v[208:211], v[44:47]
	v_mfma_f32_16x16x32_bf16 v[40:43], v[158:161], v[216:219], v[40:43]
	v_mfma_f32_16x16x32_bf16 v[36:39], v[166:169], v[216:219], v[36:39]
	v_mfma_f32_16x16x32_bf16 v[64:67], v[162:165], v[196:199], v[64:67]
	v_mfma_f32_16x16x32_bf16 v[60:63], v[184:187], v[196:199], v[60:63]
	v_mfma_f32_16x16x32_bf16 v[56:59], v[162:165], v[204:207], v[56:59]
	v_mfma_f32_16x16x32_bf16 v[52:55], v[184:187], v[204:207], v[52:55]
	v_mfma_f32_16x16x32_bf16 v[48:51], v[162:165], v[212:215], v[48:51]
	v_mfma_f32_16x16x32_bf16 v[44:47], v[184:187], v[212:215], v[44:47]
	v_mfma_f32_16x16x32_bf16 v[40:43], v[162:165], v[220:223], v[40:43]
	v_mfma_f32_16x16x32_bf16 v[36:39], v[184:187], v[220:223], v[36:39]
	s_barrier
	s_add_i32 s61, s61, s28
	v_lshl_add_u64 v[170:171], s[14:15], 0, v[174:175]
	s_mov_b32 m0, s61
	ds_read_b128 v[192:195], v190 offset:16384
	ds_read_b128 v[196:199], v190 offset:17408
	ds_read_b128 v[200:203], v190 offset:18432
	ds_read_b128 v[204:207], v190 offset:19456
	ds_read_b128 v[208:211], v190 offset:20480
	ds_read_b128 v[212:215], v190 offset:21504
	ds_read_b128 v[216:219], v190 offset:22528
	ds_read_b128 v[220:223], v190 offset:23552
	global_load_lds_dwordx4 v[170:171], off
	s_add_i32 m0, s61, 0x2000
	s_add_u32 s62, s14, 0x100000
	v_lshl_add_u64 v[224:225], s[14:15], 0, v[148:149]
	s_addc_u32 s63, s15, 0
	s_add_i32 s61, s64, s28
	global_load_lds_dwordx4 v[224:225], off
	v_lshl_add_u64 v[226:227], s[62:63], 0, v[174:175]
	s_mov_b32 m0, s61
	v_lshl_add_u64 v[228:229], s[16:17], 0, v[150:151]
	global_load_lds_dwordx4 v[226:227], off
	v_lshl_add_u64 v[226:227], s[62:63], 0, v[148:149]
	s_add_i32 m0, s61, 0x2000
	s_nop 0
	global_load_lds_dwordx4 v[226:227], off
	v_lshl_add_u64 v[226:227], s[16:17], 0, v[152:153]
	s_mov_b32 m0, s29
	s_nop 0
	global_load_lds_dwordx4 v[226:227], off
	s_mov_b32 m0, s30
	s_nop 0
	global_load_lds_dwordx4 v[228:229], off
	s_waitcnt vmcnt(8)
	s_waitcnt lgkmcnt(0)
	s_barrier
; #define PG8_STAGE(bufoff, gbase, voff) do { _Pragma("unroll") for (int _i = 0; _i < 2; ++_i) \
;         __builtin_amdgcn_global_load_lds((const unsigned*)((const char*)(gbase) + (voff)[_i]), (PG8_LAS unsigned*)(lds + (bufoff) + ldsw + _i * 8192), 16, 0, 0); } while (0)
; #define PG8_LDA(dst, b, h) do { _Pragma("unroll") for (int m = 0; m < 4; ++m) _Pragma("unroll") for (int k = 0; k < 2; ++k) dst[m][k] = *(const PG8_LAS bf16x8*)(lds + PG8_SA(b, h) + aoff + m * 2048 + k * 1024); } while (0)
; #define PG8_LDB(dst, b, h) do { _Pragma("unroll") for (int n = 0; n < 2; ++n) _Pragma("unroll") for (int k = 0; k < 2; ++k) dst[n][k] = *(const PG8_LAS bf16x8*)(lds + PG8_SB(b, h) + boff + n * 2048 + k * 1024); } while (0)
; #define PG8_MMA(ai, bj, At, Bt) do { __builtin_amdgcn_s_setprio(1); _Pragma("unroll") for (int m = 0; m < 4; ++m) _Pragma("unroll") for (int n = 0; n < 2; ++n) _Pragma("unroll") for (int k = 0; k < 2; ++k) \
;         acc[ai][bj][m][n] = __builtin_amdgcn_mfma_f32_16x16x32_bf16(Bt[n][k], At[m][k], acc[ai][bj][m][n], 0, 0, 0); __builtin_amdgcn_s_setprio(0); } while (0)
; #define PG8_WAIT_V(n) asm volatile("s_waitcnt vmcnt(" #n ")" ::: "memory")
; #define PG8_WAIT_L(n) asm volatile("s_waitcnt lgkmcnt(" #n ")" ::: "memory")
; #define PG8_BAR __builtin_amdgcn_s_barrier()
; #define PG8_SCHED __builtin_amdgcn_sched_barrier(0)
; template <class Epi, class Sched, bool ALIGN_EPI = false, bool SP2 = false>
; __device__ __forceinline__ void gemm_phase(PG8_LAS unsigned char* lds, const Gemm g, const Sched& S, const Epi& E) {
;     ...
;             PG8_WAIT_V(8); PG8_WAIT_L(0); PG8_BAR; PG8_MMA(1, 0, At, B0); PG8_MMA(1, 1, At, B1); PG8_BAR; PG8_SCHED;
;             PG8_LDB(B0, 1, 0); PG8_LDB(B1, 1, 1); PG8_SCHED; PG8_LDA(At, 1, 0); PG8_STAGE(PG8_SA(0, 1), a2 + hstep, voffA);
;             PG8_WAIT_V(8); PG8_WAIT_L(0); PG8_BAR; PG8_MMA(0, 0, At, B0); PG8_MMA(0, 1, At, B1); PG8_BAR; PG8_SCHED;
	s_waitcnt lgkmcnt(0)
	v_mfma_f32_16x16x32_bf16 v[96:99], v[100:103], v[192:195], v[96:99]
	v_mfma_f32_16x16x32_bf16 v[92:95], v[140:143], v[192:195], v[92:95]
	v_mfma_f32_16x16x32_bf16 v[88:91], v[100:103], v[200:203], v[88:91]
	v_mfma_f32_16x16x32_bf16 v[84:87], v[140:143], v[200:203], v[84:87]
	v_mfma_f32_16x16x32_bf16 v[80:83], v[100:103], v[208:211], v[80:83]
	v_mfma_f32_16x16x32_bf16 v[76:79], v[140:143], v[208:211], v[76:79]
	v_mfma_f32_16x16x32_bf16 v[72:75], v[100:103], v[216:219], v[72:75]
	v_mfma_f32_16x16x32_bf16 v[68:71], v[140:143], v[216:219], v[68:71]
	v_mfma_f32_16x16x32_bf16 v[96:99], v[104:107], v[196:199], v[96:99]
	v_mfma_f32_16x16x32_bf16 v[92:95], v[144:147], v[196:199], v[92:95]
	v_mfma_f32_16x16x32_bf16 v[88:91], v[104:107], v[204:207], v[88:91]
	v_mfma_f32_16x16x32_bf16 v[84:87], v[144:147], v[204:207], v[84:87]
	v_mfma_f32_16x16x32_bf16 v[80:83], v[104:107], v[212:215], v[80:83]
	v_mfma_f32_16x16x32_bf16 v[76:79], v[144:147], v[212:215], v[76:79]
	v_mfma_f32_16x16x32_bf16 v[72:75], v[104:107], v[220:223], v[72:75]
	v_mfma_f32_16x16x32_bf16 v[68:71], v[144:147], v[220:223], v[68:71]
	v_mfma_f32_16x16x32_bf16 v[32:35], v[158:161], v[192:195], v[32:35]
	v_mfma_f32_16x16x32_bf16 v[28:31], v[166:169], v[192:195], v[28:31]
	v_mfma_f32_16x16x32_bf16 v[24:27], v[158:161], v[200:203], v[24:27]
	v_mfma_f32_16x16x32_bf16 v[20:23], v[166:169], v[200:203], v[20:23]
	v_mfma_f32_16x16x32_bf16 v[16:19], v[158:161], v[208:211], v[16:19]
	v_mfma_f32_16x16x32_bf16 v[12:15], v[166:169], v[208:211], v[12:15]
	v_mfma_f32_16x16x32_bf16 v[8:11], v[158:161], v[216:219], v[8:11]
	v_mfma_f32_16x16x32_bf16 v[4:7], v[166:169], v[216:219], v[4:7]
	v_mfma_f32_16x16x32_bf16 v[32:35], v[162:165], v[196:199], v[32:35]
	v_mfma_f32_16x16x32_bf16 v[28:31], v[184:187], v[196:199], v[28:31]
	v_mfma_f32_16x16x32_bf16 v[24:27], v[162:165], v[204:207], v[24:27]
	v_mfma_f32_16x16x32_bf16 v[20:23], v[184:187], v[204:207], v[20:23]
	v_mfma_f32_16x16x32_bf16 v[16:19], v[162:165], v[212:215], v[16:19]
	v_mfma_f32_16x16x32_bf16 v[12:15], v[184:187], v[212:215], v[12:15]
	v_mfma_f32_16x16x32_bf16 v[8:11], v[162:165], v[220:223], v[8:11]
	v_mfma_f32_16x16x32_bf16 v[4:7], v[184:187], v[220:223], v[4:7]
	s_barrier
	s_add_i32 s61, 0, 0x18000
	s_add_i32 s62, 0, 0x1c000
	v_add_u32_e32 v144, s61, v188
	v_add_u32_e32 v184, s62, v188
	ds_read_b128 v[100:103], v144
	ds_read_b128 v[104:107], v144 offset:1024
	ds_read_b128 v[140:143], v144 offset:2048
	ds_read_b128 v[144:147], v144 offset:3072
	ds_read_b128 v[158:161], v184
	ds_read_b128 v[162:165], v184 offset:1024
	ds_read_b128 v[166:169], v184 offset:2048
	ds_read_b128 v[184:187], v184 offset:3072
	s_add_u32 s16, s16, 0x100000
	s_addc_u32 s17, s17, 0
	s_mov_b32 m0, s31
	v_lshl_add_u64 v[230:231], s[16:17], 0, v[152:153]
	ds_read_b128 v[192:195], v190 offset:32768
	ds_read_b128 v[196:199], v190 offset:33792
	ds_read_b128 v[200:203], v190 offset:34816
	ds_read_b128 v[204:207], v190 offset:35840
	ds_read_b128 v[208:211], v190 offset:36864
	ds_read_b128 v[212:215], v190 offset:37888
	ds_read_b128 v[216:219], v190 offset:38912
	ds_read_b128 v[220:223], v190 offset:39936
	global_load_lds_dwordx4 v[230:231], off
	v_lshl_add_u64 v[230:231], s[16:17], 0, v[150:151]
	s_mov_b32 m0, s34
	s_nop 0
	global_load_lds_dwordx4 v[230:231], off
	s_waitcnt vmcnt(8)
	s_waitcnt lgkmcnt(0)
	s_barrier
	s_waitcnt lgkmcnt(0)
	v_mfma_f32_16x16x32_bf16 v[136:139], v[100:103], v[192:195], v[136:139]
	v_mfma_f32_16x16x32_bf16 v[132:135], v[140:143], v[192:195], v[132:135]
	v_mfma_f32_16x16x32_bf16 v[128:131], v[100:103], v[200:203], v[128:131]
	v_mfma_f32_16x16x32_bf16 v[124:127], v[140:143], v[200:203], v[124:127]
	v_mfma_f32_16x16x32_bf16 v[120:123], v[100:103], v[208:211], v[120:123]
	v_mfma_f32_16x16x32_bf16 v[116:119], v[140:143], v[208:211], v[116:119]
	v_mfma_f32_16x16x32_bf16 v[112:115], v[100:103], v[216:219], v[112:115]
	v_mfma_f32_16x16x32_bf16 v[108:111], v[140:143], v[216:219], v[108:111]
	v_mfma_f32_16x16x32_bf16 v[136:139], v[104:107], v[196:199], v[136:139]
	v_mfma_f32_16x16x32_bf16 v[132:135], v[144:147], v[196:199], v[132:135]
	v_mfma_f32_16x16x32_bf16 v[128:131], v[104:107], v[204:207], v[128:131]
	v_mfma_f32_16x16x32_bf16 v[124:127], v[144:147], v[204:207], v[124:127]
	v_mfma_f32_16x16x32_bf16 v[120:123], v[104:107], v[212:215], v[120:123]
	v_mfma_f32_16x16x32_bf16 v[116:119], v[144:147], v[212:215], v[116:119]
	v_mfma_f32_16x16x32_bf16 v[112:115], v[104:107], v[220:223], v[112:115]
	v_mfma_f32_16x16x32_bf16 v[108:111], v[144:147], v[220:223], v[108:111]
	v_mfma_f32_16x16x32_bf16 v[64:67], v[158:161], v[192:195], v[64:67]
	v_mfma_f32_16x16x32_bf16 v[60:63], v[166:169], v[192:195], v[60:63]
	v_mfma_f32_16x16x32_bf16 v[56:59], v[158:161], v[200:203], v[56:59]
	v_mfma_f32_16x16x32_bf16 v[52:55], v[166:169], v[200:203], v[52:55]
	v_mfma_f32_16x16x32_bf16 v[48:51], v[158:161], v[208:211], v[48:51]
	v_mfma_f32_16x16x32_bf16 v[44:47], v[166:169], v[208:211], v[44:47]
	v_mfma_f32_16x16x32_bf16 v[40:43], v[158:161], v[216:219], v[40:43]
	v_mfma_f32_16x16x32_bf16 v[36:39], v[166:169], v[216:219], v[36:39]
	v_mfma_f32_16x16x32_bf16 v[64:67], v[162:165], v[196:199], v[64:67]
	v_mfma_f32_16x16x32_bf16 v[60:63], v[184:187], v[196:199], v[60:63]
	v_mfma_f32_16x16x32_bf16 v[56:59], v[162:165], v[204:207], v[56:59]
	v_mfma_f32_16x16x32_bf16 v[52:55], v[184:187], v[204:207], v[52:55]
	v_mfma_f32_16x16x32_bf16 v[48:51], v[162:165], v[212:215], v[48:51]
	v_mfma_f32_16x16x32_bf16 v[44:47], v[184:187], v[212:215], v[44:47]
	v_mfma_f32_16x16x32_bf16 v[40:43], v[162:165], v[220:223], v[40:43]
	v_mfma_f32_16x16x32_bf16 v[36:39], v[184:187], v[220:223], v[36:39]
	s_barrier
; #define PG8_STAGE(bufoff, gbase, voff) do { _Pragma("unroll") for (int _i = 0; _i < 2; ++_i) \
;         __builtin_amdgcn_global_load_lds((const unsigned*)((const char*)(gbase) + (voff)[_i]), (PG8_LAS unsigned*)(lds + (bufoff) + ldsw + _i * 8192), 16, 0, 0); } while (0)
; #define PG8_LDA(dst, b, h) do { _Pragma("unroll") for (int m = 0; m < 4; ++m) _Pragma("unroll") for (int k = 0; k < 2; ++k) dst[m][k] = *(const PG8_LAS bf16x8*)(lds + PG8_SA(b, h) + aoff + m * 2048 + k * 1024); } while (0)
; #define PG8_MMA(ai, bj, At, Bt) do { __builtin_amdgcn_s_setprio(1); _Pragma("unroll") for (int m = 0; m < 4; ++m) _Pragma("unroll") for (int n = 0; n < 2; ++n) _Pragma("unroll") for (int k = 0; k < 2; ++k) \
;         acc[ai][bj][m][n] = __builtin_amdgcn_mfma_f32_16x16x32_bf16(Bt[n][k], At[m][k], acc[ai][bj][m][n], 0, 0, 0); __builtin_amdgcn_s_setprio(0); } while (0)
; #define PG8_WAIT_V(n) asm volatile("s_waitcnt vmcnt(" #n ")" ::: "memory")
; #define PG8_WAIT_L(n) asm volatile("s_waitcnt lgkmcnt(" #n ")" ::: "memory")
; #define PG8_BAR __builtin_amdgcn_s_barrier()
; #define PG8_SCHED __builtin_amdgcn_sched_barrier(0)
; template <class Epi, class Sched, bool ALIGN_EPI = false, bool SP2 = false>
; __device__ __forceinline__ void gemm_phase(PG8_LAS unsigned char* lds, const Gemm g, const Sched& S, const Epi& E) {
;     ...
;         for (int t = 0; t < nt; t += 2) {
;     ...
;             PG8_LDA(At, 1, 1); PG8_STAGE(PG8_SB(1, 0), b3, voffB); PG8_STAGE(PG8_SB(1, 1), b3 + hstep, voffB); PG8_STAGE(PG8_SA(1, 0), a3, voffA);
;             PG8_WAIT_V(8); PG8_WAIT_L(0); PG8_BAR; PG8_MMA(1, 0, At, B0); PG8_MMA(1, 1, At, B1); PG8_BAR; PG8_SCHED;
	s_add_i32 s16, s61, s28
	v_lshl_add_u64 v[170:171], v[170:171], 0, s[10:11]
	s_mov_b32 m0, s16
	ds_read_b128 v[192:195], v190 offset:49152
	ds_read_b128 v[196:199], v190 offset:50176
	ds_read_b128 v[200:203], v190 offset:51200
	ds_read_b128 v[204:207], v190 offset:52224
	ds_read_b128 v[208:211], v190 offset:53248
	ds_read_b128 v[212:215], v190 offset:54272
	ds_read_b128 v[216:219], v190 offset:55296
	ds_read_b128 v[220:223], v190 offset:56320
	global_load_lds_dwordx4 v[170:171], off
	s_add_i32 m0, s16, 0x2000
	s_add_u32 s14, s14, 0x100080
	v_lshl_add_u64 v[170:171], v[224:225], 0, s[10:11]
	s_addc_u32 s15, s15, 0
	s_add_i32 s16, s62, s28
	global_load_lds_dwordx4 v[170:171], off
	v_lshl_add_u64 v[170:171], s[14:15], 0, v[174:175]
	s_mov_b32 m0, s16
	s_nop 0
	global_load_lds_dwordx4 v[170:171], off
	v_lshl_add_u64 v[170:171], s[14:15], 0, v[148:149]
	s_add_i32 m0, s16, 0x2000
	s_nop 0
	global_load_lds_dwordx4 v[170:171], off
	v_lshl_add_u64 v[170:171], v[226:227], 0, s[10:11]
	s_mov_b32 m0, s35
	s_nop 0
	global_load_lds_dwordx4 v[170:171], off
	v_lshl_add_u64 v[170:171], v[228:229], 0, s[10:11]
	s_mov_b32 m0, s38
	s_nop 0
	global_load_lds_dwordx4 v[170:171], off
	s_waitcnt vmcnt(8)
	s_waitcnt lgkmcnt(0)
	s_barrier
	s_waitcnt lgkmcnt(0)
	v_mfma_f32_16x16x32_bf16 v[96:99], v[100:103], v[192:195], v[96:99]
	v_mfma_f32_16x16x32_bf16 v[92:95], v[140:143], v[192:195], v[92:95]
	v_mfma_f32_16x16x32_bf16 v[88:91], v[100:103], v[200:203], v[88:91]
	v_mfma_f32_16x16x32_bf16 v[84:87], v[140:143], v[200:203], v[84:87]
	v_mfma_f32_16x16x32_bf16 v[80:83], v[100:103], v[208:211], v[80:83]
	v_mfma_f32_16x16x32_bf16 v[76:79], v[140:143], v[208:211], v[76:79]
	v_mfma_f32_16x16x32_bf16 v[72:75], v[100:103], v[216:219], v[72:75]
	v_mfma_f32_16x16x32_bf16 v[68:71], v[140:143], v[216:219], v[68:71]
	v_mfma_f32_16x16x32_bf16 v[96:99], v[104:107], v[196:199], v[96:99]
	v_mfma_f32_16x16x32_bf16 v[92:95], v[144:147], v[196:199], v[92:95]
	v_mfma_f32_16x16x32_bf16 v[88:91], v[104:107], v[204:207], v[88:91]
	v_mfma_f32_16x16x32_bf16 v[84:87], v[144:147], v[204:207], v[84:87]
	v_mfma_f32_16x16x32_bf16 v[80:83], v[104:107], v[212:215], v[80:83]
	v_mfma_f32_16x16x32_bf16 v[76:79], v[144:147], v[212:215], v[76:79]
	v_mfma_f32_16x16x32_bf16 v[72:75], v[104:107], v[220:223], v[72:75]
	v_mfma_f32_16x16x32_bf16 v[68:71], v[144:147], v[220:223], v[68:71]
	v_mfma_f32_16x16x32_bf16 v[32:35], v[158:161], v[192:195], v[32:35]
	v_mfma_f32_16x16x32_bf16 v[28:31], v[166:169], v[192:195], v[28:31]
	v_mfma_f32_16x16x32_bf16 v[24:27], v[158:161], v[200:203], v[24:27]
	v_mfma_f32_16x16x32_bf16 v[20:23], v[166:169], v[200:203], v[20:23]
	v_mfma_f32_16x16x32_bf16 v[16:19], v[158:161], v[208:211], v[16:19]
	v_mfma_f32_16x16x32_bf16 v[12:15], v[166:169], v[208:211], v[12:15]
	v_mfma_f32_16x16x32_bf16 v[8:11], v[158:161], v[216:219], v[8:11]
	v_mfma_f32_16x16x32_bf16 v[4:7], v[166:169], v[216:219], v[4:7]
	v_mfma_f32_16x16x32_bf16 v[32:35], v[162:165], v[196:199], v[32:35]
	v_mfma_f32_16x16x32_bf16 v[28:31], v[184:187], v[196:199], v[28:31]
	v_mfma_f32_16x16x32_bf16 v[24:27], v[162:165], v[204:207], v[24:27]
	v_mfma_f32_16x16x32_bf16 v[20:23], v[184:187], v[204:207], v[20:23]
	v_mfma_f32_16x16x32_bf16 v[16:19], v[162:165], v[212:215], v[16:19]
	v_mfma_f32_16x16x32_bf16 v[12:15], v[184:187], v[212:215], v[12:15]
	v_mfma_f32_16x16x32_bf16 v[8:11], v[162:165], v[220:223], v[8:11]
	v_mfma_f32_16x16x32_bf16 v[4:7], v[184:187], v[220:223], v[4:7]
	s_barrier
	s_add_i32 s60, s60, 2
	s_add_u32 s53, s53, 0x100
	s_addc_u32 s59, s59, 0
	s_add_u32 s0, s0, 0x100
	s_addc_u32 s1, s1, 0
	s_cmp_gt_u32 s60, 61
	s_cbranch_scc0 .LBB0_485
	s_and_b64 vcc, exec, s[48:49]
	s_cbranch_vccz .LBB0_488
	s_barrier

; template <class Epi, class Sched, bool ALIGN_EPI = false, bool SP2 = false>
; __device__ __forceinline__ void gemm_phase(PG8_LAS unsigned char* lds, const Gemm g, const Sched& S, const Epi& E) {
;     ...
;         const bool has_next = S.next(ui + 1, nxt);
;         const char* nA = has_next ? (const char*)g.A + (size_t)nxt.pm * tstep : cA; const char* nB = has_next ? (const char*)g.Bt + (size_t)nxt.pn * tstep : cB;
;         for (int t = 0; t < nt; t += 2) {
;             const bool last = (t == nt - 2);
;             const char* a1 = cA + (size_t)(t + 1) * kstep;
;             const char* a2 = last ? nA : cA + (size_t)(t + 2) * kstep; const char* b2 = last ? nB : cB + (size_t)(t + 2) * kstep;
;     ...
; #pragma unroll
;         for (int a = 0; a < 2; ++a)
; #pragma unroll
;             for (int b = 0; b < 2; ++b)
; #pragma unroll
;                 for (int m = 0; m < 4; ++m)
; #pragma unroll
;                     for (int n = 0; n < 2; ++n) acc[a][b][m][n] = (f32x4){0.f, 0.f, 0.f, 0.f};
.LBB0_562:
	s_ashr_i32 s39, s38, 31
	s_lshl_b64 s[26:27], s[38:39], 20
	s_add_u32 s44, s22, s26
	s_addc_u32 s45, s23, s27
	s_and_b64 s[26:27], s[42:43], exec
	s_cselect_b32 s39, s45, s19
	s_cselect_b32 s59, s44, s18
	s_ashr_i32 s37, s36, 31
	s_lshl_b64 s[26:27], s[36:37], 20
	s_add_u32 s46, s24, s26
	s_addc_u32 s47, s25, s27
	s_and_b64 s[26:27], s[42:43], exec
	s_cselect_b32 s37, s47, s1
	s_cselect_b32 s60, s46, s0
	s_add_u32 s61, s0, 0x100
	s_addc_u32 s62, s1, 0
	s_add_u32 s0, s18, 0x80080
	v_mov_b32_e32 v4, 0
	s_addc_u32 s1, s19, 0
	s_mov_b32 s63, -2
	s_waitcnt lgkmcnt(0)
	v_mov_b32_e32 v5, v4
	v_mov_b32_e32 v6, v4
	v_mov_b32_e32 v7, v4
	v_mov_b32_e32 v8, v4
	v_mov_b32_e32 v9, v4
	v_mov_b32_e32 v10, v4
	v_mov_b32_e32 v11, v4
	v_mov_b32_e32 v20, v4
	v_mov_b32_e32 v21, v4
	v_mov_b32_e32 v22, v4
	v_mov_b32_e32 v23, v4
	v_mov_b32_e32 v24, v4
	v_mov_b32_e32 v25, v4
	v_mov_b32_e32 v26, v4
	v_mov_b32_e32 v27, v4
	s_waitcnt vmcnt(0)
	v_mov_b32_e32 v36, v4
	v_mov_b32_e32 v37, v4
	v_mov_b32_e32 v38, v4
	v_mov_b32_e32 v39, v4
	v_mov_b32_e32 v40, v4
	v_mov_b32_e32 v41, v4
	v_mov_b32_e32 v42, v4
	v_mov_b32_e32 v43, v4
	v_mov_b32_e32 v52, v4
	v_mov_b32_e32 v53, v4
	v_mov_b32_e32 v54, v4
	v_mov_b32_e32 v55, v4
	v_mov_b32_e32 v56, v4
	v_mov_b32_e32 v57, v4
	v_mov_b32_e32 v58, v4
	v_mov_b32_e32 v59, v4
	v_mov_b32_e32 v12, v4
	v_mov_b32_e32 v13, v4
	v_mov_b32_e32 v14, v4
	v_mov_b32_e32 v15, v4
	v_mov_b32_e32 v16, v4
	v_mov_b32_e32 v17, v4
	v_mov_b32_e32 v18, v4
	v_mov_b32_e32 v19, v4
	v_mov_b32_e32 v28, v4
	v_mov_b32_e32 v29, v4
	v_mov_b32_e32 v30, v4
	v_mov_b32_e32 v31, v4
	v_mov_b32_e32 v32, v4
	v_mov_b32_e32 v33, v4
	v_mov_b32_e32 v34, v4
	v_mov_b32_e32 v35, v4
	v_mov_b32_e32 v44, v4
	v_mov_b32_e32 v45, v4
	v_mov_b32_e32 v46, v4
	v_mov_b32_e32 v47, v4
	v_mov_b32_e32 v48, v4
	v_mov_b32_e32 v49, v4
	v_mov_b32_e32 v50, v4
	v_mov_b32_e32 v51, v4
	v_mov_b32_e32 v60, v4
	v_mov_b32_e32 v61, v4
	v_mov_b32_e32 v62, v4
	v_mov_b32_e32 v63, v4
	v_mov_b32_e32 v64, v4
	v_mov_b32_e32 v65, v4
	v_mov_b32_e32 v66, v4
	v_mov_b32_e32 v67, v4
	v_mov_b32_e32 v68, v4
	v_mov_b32_e32 v69, v4
	v_mov_b32_e32 v70, v4
	v_mov_b32_e32 v71, v4
	v_mov_b32_e32 v72, v4
	v_mov_b32_e32 v73, v4
	v_mov_b32_e32 v74, v4
	v_mov_b32_e32 v75, v4
	v_mov_b32_e32 v84, v4
	v_mov_b32_e32 v85, v4
	v_mov_b32_e32 v86, v4
	v_mov_b32_e32 v87, v4
	v_mov_b32_e32 v88, v4
	v_mov_b32_e32 v89, v4
	v_mov_b32_e32 v90, v4
	v_mov_b32_e32 v91, v4
	v_mov_b32_e32 v100, v4
	v_mov_b32_e32 v101, v4
	v_mov_b32_e32 v102, v4
	v_mov_b32_e32 v103, v4
	v_mov_b32_e32 v104, v4
	v_mov_b32_e32 v105, v4
	v_mov_b32_e32 v106, v4
	v_mov_b32_e32 v107, v4
	v_mov_b32_e32 v116, v4
	v_mov_b32_e32 v117, v4
	v_mov_b32_e32 v118, v4
	v_mov_b32_e32 v119, v4
	v_mov_b32_e32 v120, v4
	v_mov_b32_e32 v121, v4
	v_mov_b32_e32 v122, v4
	v_mov_b32_e32 v123, v4
	v_mov_b32_e32 v76, v4
	v_mov_b32_e32 v77, v4
	v_mov_b32_e32 v78, v4
	v_mov_b32_e32 v79, v4
	v_mov_b32_e32 v80, v4
	v_mov_b32_e32 v81, v4
	v_mov_b32_e32 v82, v4
	v_mov_b32_e32 v83, v4
	v_mov_b32_e32 v92, v4
	v_mov_b32_e32 v93, v4
	v_mov_b32_e32 v94, v4
	v_mov_b32_e32 v95, v4
	v_mov_b32_e32 v96, v4
	v_mov_b32_e32 v97, v4
	v_mov_b32_e32 v98, v4
	v_mov_b32_e32 v99, v4
	v_mov_b32_e32 v108, v4
	v_mov_b32_e32 v109, v4
	v_mov_b32_e32 v110, v4
	v_mov_b32_e32 v111, v4
	v_mov_b32_e32 v112, v4
	v_mov_b32_e32 v113, v4
	v_mov_b32_e32 v114, v4
	v_mov_b32_e32 v115, v4
	v_mov_b32_e32 v124, v4
	v_mov_b32_e32 v125, v4
	v_mov_b32_e32 v126, v4
	v_mov_b32_e32 v127, v4
	v_mov_b32_e32 v128, v4
	v_mov_b32_e32 v129, v4
	v_mov_b32_e32 v130, v4
	v_mov_b32_e32 v131, v4
	v_readfirstlane_b32 s101, v172
	s_nop 3
	s_cmp_ge_u32 s101, 0x100
	s_cbranch_scc1 .Lprio_hi_563
	s_setprio 0
	s_branch .Lprio_done_563

; #define PG8_STAGE(bufoff, gbase, voff) do { _Pragma("unroll") for (int _i = 0; _i < 2; ++_i) \
;         __builtin_amdgcn_global_load_lds((const unsigned*)((const char*)(gbase) + (voff)[_i]), (PG8_LAS unsigned*)(lds + (bufoff) + ldsw + _i * 8192), 16, 0, 0); } while (0)
; #define PG8_LDA(dst, b, h) do { _Pragma("unroll") for (int m = 0; m < 4; ++m) _Pragma("unroll") for (int k = 0; k < 2; ++k) dst[m][k] = *(const PG8_LAS bf16x8*)(lds + PG8_SA(b, h) + aoff + m * 2048 + k * 1024); } while (0)
; #define PG8_LDB(dst, b, h) do { _Pragma("unroll") for (int n = 0; n < 2; ++n) _Pragma("unroll") for (int k = 0; k < 2; ++k) dst[n][k] = *(const PG8_LAS bf16x8*)(lds + PG8_SB(b, h) + boff + n * 2048 + k * 1024); } while (0)
; #define PG8_MMA(ai, bj, At, Bt) do { __builtin_amdgcn_s_setprio(1); _Pragma("unroll") for (int m = 0; m < 4; ++m) _Pragma("unroll") for (int n = 0; n < 2; ++n) _Pragma("unroll") for (int k = 0; k < 2; ++k) \
;         acc[ai][bj][m][n] = __builtin_amdgcn_mfma_f32_16x16x32_bf16(Bt[n][k], At[m][k], acc[ai][bj][m][n], 0, 0, 0); __builtin_amdgcn_s_setprio(0); } while (0)
; #define PG8_WAIT_V(n) asm volatile("s_waitcnt vmcnt(" #n ")" ::: "memory")
; #define PG8_BAR __builtin_amdgcn_s_barrier()
; template <class Epi, class Sched, bool ALIGN_EPI = false, bool SP2 = false>
; __device__ __forceinline__ void gemm_phase(PG8_LAS unsigned char* lds, const Gemm g, const Sched& S, const Epi& E) {
;     ...
;         for (int t = 0; t < nt; t += 2) {
;             const bool last = (t == nt - 2);
;             const char* a1 = cA + (size_t)(t + 1) * kstep;
;             const char* a2 = last ? nA : cA + (size_t)(t + 2) * kstep; const char* b2 = last ? nB : cB + (size_t)(t + 2) * kstep;
;             const char* a3 = a2 + kstep; const char* b3 = b2 + kstep;
;             if (last && has_next) S.a_ready(nxt);
;             if constexpr (SP2) {
;             PG8_LDB(B0, 0, 0); PG8_LDB(B1, 0, 1); PG8_SCHED; PG8_LDA(At, 0, 0); PG8_STAGE(PG8_SA(1, 1), a1 + hstep, voffA);
;             PG8_WAIT_V(8); PG8_WAIT_L(0); PG8_BAR; PG8_MMA(0, 0, At, B0); PG8_MMA(0, 1, At, B1); PG8_BAR; PG8_SCHED;
;             PG8_LDA(At, 0, 1); PG8_STAGE(PG8_SB(0, 0), b2, voffB); PG8_STAGE(PG8_SB(0, 1), b2 + hstep, voffB); PG8_STAGE(PG8_SA(0, 0), a2, voffA);
;             PG8_WAIT_V(8); PG8_WAIT_L(0); PG8_BAR; PG8_MMA(1, 0, At, B0); PG8_MMA(1, 1, At, B1); PG8_BAR; PG8_SCHED;
.Lprio_done_563:
.LBB0_563:
	s_add_u32 s18, s0, 0xfff80080
	s_addc_u32 s19, s1, -1
	s_add_i32 s64, 0, 0x10000
	s_cmp_eq_u32 s63, 28
	s_cselect_b32 s27, s39, s19
	s_cselect_b32 s26, s59, s18
	s_cselect_b32 s19, s37, s62
	s_cselect_b32 s18, s60, s61
	s_add_i32 s66, 0, 0x14000
	v_add_u32_e32 v144, s64, v167
	v_add_u32_e32 v170, s66, v167
	ds_read_b128 v[132:135], v144
	ds_read_b128 v[136:139], v144 offset:1024
	ds_read_b128 v[140:143], v144 offset:2048
	ds_read_b128 v[144:147], v144 offset:3072
	ds_read_b128 v[158:161], v170
	ds_read_b128 v[162:165], v170 offset:1024
	ds_read_b128 v[184:187], v170 offset:2048
	ds_read_b128 v[188:191], v170 offset:3072
	v_lshl_add_u64 v[170:171], s[0:1], 0, v[156:157]
	s_add_i32 m0, s49, 0xc000
	ds_read_b128 v[192:195], v169
	ds_read_b128 v[196:199], v169 offset:1024
	ds_read_b128 v[200:203], v169 offset:2048
	ds_read_b128 v[204:207], v169 offset:3072
	ds_read_b128 v[208:211], v169 offset:4096
	ds_read_b128 v[212:215], v169 offset:5120
	ds_read_b128 v[216:219], v169 offset:6144
	ds_read_b128 v[220:223], v169 offset:7168
	global_load_lds_dwordx4 v[170:171], off
	v_lshl_add_u64 v[170:171], s[0:1], 0, v[154:155]
	s_add_i32 m0, s49, 0xe000
	s_nop 0
	global_load_lds_dwordx4 v[170:171], off
	s_waitcnt vmcnt(8)
	s_waitcnt lgkmcnt(0)
	s_barrier
	s_waitcnt lgkmcnt(0)
	v_mfma_f32_16x16x32_bf16 v[128:131], v[132:135], v[192:195], v[128:131]
	v_mfma_f32_16x16x32_bf16 v[124:127], v[140:143], v[192:195], v[124:127]
	v_mfma_f32_16x16x32_bf16 v[112:115], v[132:135], v[200:203], v[112:115]
	v_mfma_f32_16x16x32_bf16 v[108:111], v[140:143], v[200:203], v[108:111]
	v_mfma_f32_16x16x32_bf16 v[96:99], v[132:135], v[208:211], v[96:99]
	v_mfma_f32_16x16x32_bf16 v[92:95], v[140:143], v[208:211], v[92:95]
	v_mfma_f32_16x16x32_bf16 v[80:83], v[132:135], v[216:219], v[80:83]
	v_mfma_f32_16x16x32_bf16 v[76:79], v[140:143], v[216:219], v[76:79]
	v_mfma_f32_16x16x32_bf16 v[128:131], v[136:139], v[196:199], v[128:131]
	v_mfma_f32_16x16x32_bf16 v[124:127], v[144:147], v[196:199], v[124:127]
	v_mfma_f32_16x16x32_bf16 v[112:115], v[136:139], v[204:207], v[112:115]
	v_mfma_f32_16x16x32_bf16 v[108:111], v[144:147], v[204:207], v[108:111]
	v_mfma_f32_16x16x32_bf16 v[96:99], v[136:139], v[212:215], v[96:99]
	v_mfma_f32_16x16x32_bf16 v[92:95], v[144:147], v[212:215], v[92:95]
	v_mfma_f32_16x16x32_bf16 v[80:83], v[136:139], v[220:223], v[80:83]
	v_mfma_f32_16x16x32_bf16 v[76:79], v[144:147], v[220:223], v[76:79]
	v_mfma_f32_16x16x32_bf16 v[120:123], v[158:161], v[192:195], v[120:123]
	v_mfma_f32_16x16x32_bf16 v[116:119], v[184:187], v[192:195], v[116:119]
	v_mfma_f32_16x16x32_bf16 v[104:107], v[158:161], v[200:203], v[104:107]
	v_mfma_f32_16x16x32_bf16 v[100:103], v[184:187], v[200:203], v[100:103]
	v_mfma_f32_16x16x32_bf16 v[88:91], v[158:161], v[208:211], v[88:91]
	v_mfma_f32_16x16x32_bf16 v[84:87], v[184:187], v[208:211], v[84:87]
	v_mfma_f32_16x16x32_bf16 v[72:75], v[158:161], v[216:219], v[72:75]
	v_mfma_f32_16x16x32_bf16 v[68:71], v[184:187], v[216:219], v[68:71]
	v_mfma_f32_16x16x32_bf16 v[120:123], v[162:165], v[196:199], v[120:123]
	v_mfma_f32_16x16x32_bf16 v[116:119], v[188:191], v[196:199], v[116:119]
	v_mfma_f32_16x16x32_bf16 v[104:107], v[162:165], v[204:207], v[104:107]
	v_mfma_f32_16x16x32_bf16 v[100:103], v[188:191], v[204:207], v[100:103]
	v_mfma_f32_16x16x32_bf16 v[88:91], v[162:165], v[212:215], v[88:91]
	v_mfma_f32_16x16x32_bf16 v[84:87], v[188:191], v[212:215], v[84:87]
	v_mfma_f32_16x16x32_bf16 v[72:75], v[162:165], v[220:223], v[72:75]
	v_mfma_f32_16x16x32_bf16 v[68:71], v[188:191], v[220:223], v[68:71]
	s_barrier
	s_add_i32 s64, s64, s48
	v_lshl_add_u64 v[170:171], s[18:19], 0, v[174:175]
	s_mov_b32 m0, s64
	ds_read_b128 v[192:195], v169 offset:16384
	ds_read_b128 v[196:199], v169 offset:17408
	ds_read_b128 v[200:203], v169 offset:18432
	ds_read_b128 v[204:207], v169 offset:19456
	ds_read_b128 v[208:211], v169 offset:20480
	ds_read_b128 v[212:215], v169 offset:21504
	ds_read_b128 v[216:219], v169 offset:22528
	ds_read_b128 v[220:223], v169 offset:23552
	global_load_lds_dwordx4 v[170:171], off
	s_add_i32 m0, s64, 0x2000
	s_add_u32 s64, s18, 0x80000
	v_lshl_add_u64 v[224:225], s[18:19], 0, v[148:149]
	s_addc_u32 s65, s19, 0
	s_add_i32 s66, s66, s48
	global_load_lds_dwordx4 v[224:225], off
	v_lshl_add_u64 v[226:227], s[64:65], 0, v[174:175]
	s_mov_b32 m0, s66
	v_lshl_add_u64 v[228:229], s[26:27], 0, v[150:151]
	global_load_lds_dwordx4 v[226:227], off
	v_lshl_add_u64 v[226:227], s[64:65], 0, v[148:149]
	s_add_i32 m0, s66, 0x2000
	s_nop 0
	global_load_lds_dwordx4 v[226:227], off
	v_lshl_add_u64 v[226:227], s[26:27], 0, v[152:153]
	s_mov_b32 m0, s49
	s_nop 0
	global_load_lds_dwordx4 v[226:227], off
	s_mov_b32 m0, s50
	s_nop 0
	global_load_lds_dwordx4 v[228:229], off
	s_waitcnt vmcnt(8)
	s_waitcnt lgkmcnt(0)
	s_barrier
; #define PG8_STAGE(bufoff, gbase, voff) do { _Pragma("unroll") for (int _i = 0; _i < 2; ++_i) \
;         __builtin_amdgcn_global_load_lds((const unsigned*)((const char*)(gbase) + (voff)[_i]), (PG8_LAS unsigned*)(lds + (bufoff) + ldsw + _i * 8192), 16, 0, 0); } while (0)
; #define PG8_LDA(dst, b, h) do { _Pragma("unroll") for (int m = 0; m < 4; ++m) _Pragma("unroll") for (int k = 0; k < 2; ++k) dst[m][k] = *(const PG8_LAS bf16x8*)(lds + PG8_SA(b, h) + aoff + m * 2048 + k * 1024); } while (0)
; #define PG8_LDB(dst, b, h) do { _Pragma("unroll") for (int n = 0; n < 2; ++n) _Pragma("unroll") for (int k = 0; k < 2; ++k) dst[n][k] = *(const PG8_LAS bf16x8*)(lds + PG8_SB(b, h) + boff + n * 2048 + k * 1024); } while (0)
; #define PG8_MMA(ai, bj, At, Bt) do { __builtin_amdgcn_s_setprio(1); _Pragma("unroll") for (int m = 0; m < 4; ++m) _Pragma("unroll") for (int n = 0; n < 2; ++n) _Pragma("unroll") for (int k = 0; k < 2; ++k) \
;         acc[ai][bj][m][n] = __builtin_amdgcn_mfma_f32_16x16x32_bf16(Bt[n][k], At[m][k], acc[ai][bj][m][n], 0, 0, 0); __builtin_amdgcn_s_setprio(0); } while (0)
; #define PG8_WAIT_V(n) asm volatile("s_waitcnt vmcnt(" #n ")" ::: "memory")
; #define PG8_WAIT_L(n) asm volatile("s_waitcnt lgkmcnt(" #n ")" ::: "memory")
; #define PG8_BAR __builtin_amdgcn_s_barrier()
; #define PG8_SCHED __builtin_amdgcn_sched_barrier(0)
; template <class Epi, class Sched, bool ALIGN_EPI = false, bool SP2 = false>
; __device__ __forceinline__ void gemm_phase(PG8_LAS unsigned char* lds, const Gemm g, const Sched& S, const Epi& E) {
;     ...
;             PG8_WAIT_V(8); PG8_WAIT_L(0); PG8_BAR; PG8_MMA(1, 0, At, B0); PG8_MMA(1, 1, At, B1); PG8_BAR; PG8_SCHED;
;             PG8_LDB(B0, 1, 0); PG8_LDB(B1, 1, 1); PG8_SCHED; PG8_LDA(At, 1, 0); PG8_STAGE(PG8_SA(0, 1), a2 + hstep, voffA);
;             PG8_WAIT_V(8); PG8_WAIT_L(0); PG8_BAR; PG8_MMA(0, 0, At, B0); PG8_MMA(0, 1, At, B1); PG8_BAR; PG8_SCHED;
	s_waitcnt lgkmcnt(0)
	v_mfma_f32_16x16x32_bf16 v[64:67], v[132:135], v[192:195], v[64:67]
	v_mfma_f32_16x16x32_bf16 v[60:63], v[140:143], v[192:195], v[60:63]
	v_mfma_f32_16x16x32_bf16 v[48:51], v[132:135], v[200:203], v[48:51]
	v_mfma_f32_16x16x32_bf16 v[44:47], v[140:143], v[200:203], v[44:47]
	v_mfma_f32_16x16x32_bf16 v[32:35], v[132:135], v[208:211], v[32:35]
	v_mfma_f32_16x16x32_bf16 v[28:31], v[140:143], v[208:211], v[28:31]
	v_mfma_f32_16x16x32_bf16 v[16:19], v[132:135], v[216:219], v[16:19]
	v_mfma_f32_16x16x32_bf16 v[12:15], v[140:143], v[216:219], v[12:15]
	v_mfma_f32_16x16x32_bf16 v[64:67], v[136:139], v[196:199], v[64:67]
	v_mfma_f32_16x16x32_bf16 v[60:63], v[144:147], v[196:199], v[60:63]
	v_mfma_f32_16x16x32_bf16 v[48:51], v[136:139], v[204:207], v[48:51]
	v_mfma_f32_16x16x32_bf16 v[44:47], v[144:147], v[204:207], v[44:47]
	v_mfma_f32_16x16x32_bf16 v[32:35], v[136:139], v[212:215], v[32:35]
	v_mfma_f32_16x16x32_bf16 v[28:31], v[144:147], v[212:215], v[28:31]
	v_mfma_f32_16x16x32_bf16 v[16:19], v[136:139], v[220:223], v[16:19]
	v_mfma_f32_16x16x32_bf16 v[12:15], v[144:147], v[220:223], v[12:15]
	v_mfma_f32_16x16x32_bf16 v[56:59], v[158:161], v[192:195], v[56:59]
	v_mfma_f32_16x16x32_bf16 v[52:55], v[184:187], v[192:195], v[52:55]
	v_mfma_f32_16x16x32_bf16 v[40:43], v[158:161], v[200:203], v[40:43]
	v_mfma_f32_16x16x32_bf16 v[36:39], v[184:187], v[200:203], v[36:39]
	v_mfma_f32_16x16x32_bf16 v[24:27], v[158:161], v[208:211], v[24:27]
	v_mfma_f32_16x16x32_bf16 v[20:23], v[184:187], v[208:211], v[20:23]
	v_mfma_f32_16x16x32_bf16 v[8:11], v[158:161], v[216:219], v[8:11]
	v_mfma_f32_16x16x32_bf16 v[4:7], v[184:187], v[216:219], v[4:7]
	v_mfma_f32_16x16x32_bf16 v[56:59], v[162:165], v[196:199], v[56:59]
	v_mfma_f32_16x16x32_bf16 v[52:55], v[188:191], v[196:199], v[52:55]
	v_mfma_f32_16x16x32_bf16 v[40:43], v[162:165], v[204:207], v[40:43]
	v_mfma_f32_16x16x32_bf16 v[36:39], v[188:191], v[204:207], v[36:39]
	v_mfma_f32_16x16x32_bf16 v[24:27], v[162:165], v[212:215], v[24:27]
	v_mfma_f32_16x16x32_bf16 v[20:23], v[188:191], v[212:215], v[20:23]
	v_mfma_f32_16x16x32_bf16 v[8:11], v[162:165], v[220:223], v[8:11]
	v_mfma_f32_16x16x32_bf16 v[4:7], v[188:191], v[220:223], v[4:7]
	s_barrier
	s_add_i32 s64, 0, 0x18000
	s_add_i32 s65, 0, 0x1c000
	v_add_u32_e32 v144, s64, v167
	v_add_u32_e32 v179, s65, v167
	ds_read_b128 v[132:135], v144
	ds_read_b128 v[136:139], v144 offset:1024
	ds_read_b128 v[140:143], v144 offset:2048
	ds_read_b128 v[144:147], v144 offset:3072
	ds_read_b128 v[158:161], v179
	ds_read_b128 v[162:165], v179 offset:1024
	ds_read_b128 v[184:187], v179 offset:2048
	ds_read_b128 v[188:191], v179 offset:3072
	s_add_u32 s26, s26, 0x80000
	s_addc_u32 s27, s27, 0
	s_mov_b32 m0, s51
	v_lshl_add_u64 v[230:231], s[26:27], 0, v[152:153]
	ds_read_b128 v[192:195], v169 offset:32768
	ds_read_b128 v[196:199], v169 offset:33792
	ds_read_b128 v[200:203], v169 offset:34816
	ds_read_b128 v[204:207], v169 offset:35840
	ds_read_b128 v[208:211], v169 offset:36864
	ds_read_b128 v[212:215], v169 offset:37888
	ds_read_b128 v[216:219], v169 offset:38912
	ds_read_b128 v[220:223], v169 offset:39936
	global_load_lds_dwordx4 v[230:231], off
	v_lshl_add_u64 v[230:231], s[26:27], 0, v[150:151]
	s_mov_b32 m0, s52
	s_nop 0
	global_load_lds_dwordx4 v[230:231], off
	s_waitcnt vmcnt(8)
	s_waitcnt lgkmcnt(0)
	s_barrier
	s_waitcnt lgkmcnt(0)
	v_mfma_f32_16x16x32_bf16 v[128:131], v[132:135], v[192:195], v[128:131]
	v_mfma_f32_16x16x32_bf16 v[124:127], v[140:143], v[192:195], v[124:127]
	v_mfma_f32_16x16x32_bf16 v[112:115], v[132:135], v[200:203], v[112:115]
	v_mfma_f32_16x16x32_bf16 v[108:111], v[140:143], v[200:203], v[108:111]
	v_mfma_f32_16x16x32_bf16 v[96:99], v[132:135], v[208:211], v[96:99]
	v_mfma_f32_16x16x32_bf16 v[92:95], v[140:143], v[208:211], v[92:95]
	v_mfma_f32_16x16x32_bf16 v[80:83], v[132:135], v[216:219], v[80:83]
	v_mfma_f32_16x16x32_bf16 v[76:79], v[140:143], v[216:219], v[76:79]
	v_mfma_f32_16x16x32_bf16 v[128:131], v[136:139], v[196:199], v[128:131]
	v_mfma_f32_16x16x32_bf16 v[124:127], v[144:147], v[196:199], v[124:127]
	v_mfma_f32_16x16x32_bf16 v[112:115], v[136:139], v[204:207], v[112:115]
	v_mfma_f32_16x16x32_bf16 v[108:111], v[144:147], v[204:207], v[108:111]
	v_mfma_f32_16x16x32_bf16 v[96:99], v[136:139], v[212:215], v[96:99]
	v_mfma_f32_16x16x32_bf16 v[92:95], v[144:147], v[212:215], v[92:95]
	v_mfma_f32_16x16x32_bf16 v[80:83], v[136:139], v[220:223], v[80:83]
	v_mfma_f32_16x16x32_bf16 v[76:79], v[144:147], v[220:223], v[76:79]
	v_mfma_f32_16x16x32_bf16 v[120:123], v[158:161], v[192:195], v[120:123]
	v_mfma_f32_16x16x32_bf16 v[116:119], v[184:187], v[192:195], v[116:119]
	v_mfma_f32_16x16x32_bf16 v[104:107], v[158:161], v[200:203], v[104:107]
	v_mfma_f32_16x16x32_bf16 v[100:103], v[184:187], v[200:203], v[100:103]
	v_mfma_f32_16x16x32_bf16 v[88:91], v[158:161], v[208:211], v[88:91]
	v_mfma_f32_16x16x32_bf16 v[84:87], v[184:187], v[208:211], v[84:87]
	v_mfma_f32_16x16x32_bf16 v[72:75], v[158:161], v[216:219], v[72:75]
	v_mfma_f32_16x16x32_bf16 v[68:71], v[184:187], v[216:219], v[68:71]
	v_mfma_f32_16x16x32_bf16 v[120:123], v[162:165], v[196:199], v[120:123]
	v_mfma_f32_16x16x32_bf16 v[116:119], v[188:191], v[196:199], v[116:119]
	v_mfma_f32_16x16x32_bf16 v[104:107], v[162:165], v[204:207], v[104:107]
	v_mfma_f32_16x16x32_bf16 v[100:103], v[188:191], v[204:207], v[100:103]
	v_mfma_f32_16x16x32_bf16 v[88:91], v[162:165], v[212:215], v[88:91]
	v_mfma_f32_16x16x32_bf16 v[84:87], v[188:191], v[212:215], v[84:87]
	v_mfma_f32_16x16x32_bf16 v[72:75], v[162:165], v[220:223], v[72:75]
	v_mfma_f32_16x16x32_bf16 v[68:71], v[188:191], v[220:223], v[68:71]
	s_barrier
; #define PG8_STAGE(bufoff, gbase, voff) do { _Pragma("unroll") for (int _i = 0; _i < 2; ++_i) \
;         __builtin_amdgcn_global_load_lds((const unsigned*)((const char*)(gbase) + (voff)[_i]), (PG8_LAS unsigned*)(lds + (bufoff) + ldsw + _i * 8192), 16, 0, 0); } while (0)
; #define PG8_LDA(dst, b, h) do { _Pragma("unroll") for (int m = 0; m < 4; ++m) _Pragma("unroll") for (int k = 0; k < 2; ++k) dst[m][k] = *(const PG8_LAS bf16x8*)(lds + PG8_SA(b, h) + aoff + m * 2048 + k * 1024); } while (0)
; #define PG8_MMA(ai, bj, At, Bt) do { __builtin_amdgcn_s_setprio(1); _Pragma("unroll") for (int m = 0; m < 4; ++m) _Pragma("unroll") for (int n = 0; n < 2; ++n) _Pragma("unroll") for (int k = 0; k < 2; ++k) \
;         acc[ai][bj][m][n] = __builtin_amdgcn_mfma_f32_16x16x32_bf16(Bt[n][k], At[m][k], acc[ai][bj][m][n], 0, 0, 0); __builtin_amdgcn_s_setprio(0); } while (0)
; #define PG8_WAIT_V(n) asm volatile("s_waitcnt vmcnt(" #n ")" ::: "memory")
; #define PG8_WAIT_L(n) asm volatile("s_waitcnt lgkmcnt(" #n ")" ::: "memory")
; #define PG8_BAR __builtin_amdgcn_s_barrier()
; #define PG8_SCHED __builtin_amdgcn_sched_barrier(0)
; template <class Epi, class Sched, bool ALIGN_EPI = false, bool SP2 = false>
; __device__ __forceinline__ void gemm_phase(PG8_LAS unsigned char* lds, const Gemm g, const Sched& S, const Epi& E) {
;     ...
;             PG8_LDA(At, 1, 1); PG8_STAGE(PG8_SB(1, 0), b3, voffB); PG8_STAGE(PG8_SB(1, 1), b3 + hstep, voffB); PG8_STAGE(PG8_SA(1, 0), a3, voffA);
;             PG8_WAIT_V(8); PG8_WAIT_L(0); PG8_BAR; PG8_MMA(1, 0, At, B0); PG8_MMA(1, 1, At, B1); PG8_BAR; PG8_SCHED;
	s_add_i32 s26, s64, s48
	v_lshl_add_u64 v[170:171], v[170:171], 0, s[10:11]
	s_mov_b32 m0, s26
	ds_read_b128 v[192:195], v169 offset:49152
	ds_read_b128 v[196:199], v169 offset:50176
	ds_read_b128 v[200:203], v169 offset:51200
	ds_read_b128 v[204:207], v169 offset:52224
	ds_read_b128 v[208:211], v169 offset:53248
	ds_read_b128 v[212:215], v169 offset:54272
	ds_read_b128 v[216:219], v169 offset:55296
	ds_read_b128 v[220:223], v169 offset:56320
	global_load_lds_dwordx4 v[170:171], off
	s_add_i32 m0, s26, 0x2000
	s_add_u32 s18, s18, 0x80080
	v_lshl_add_u64 v[170:171], v[224:225], 0, s[10:11]
	s_addc_u32 s19, s19, 0
	s_add_i32 s26, s65, s48
	global_load_lds_dwordx4 v[170:171], off
	v_lshl_add_u64 v[170:171], s[18:19], 0, v[174:175]
	s_mov_b32 m0, s26
	s_nop 0
	global_load_lds_dwordx4 v[170:171], off
	v_lshl_add_u64 v[170:171], s[18:19], 0, v[148:149]
	s_add_i32 m0, s26, 0x2000
	s_nop 0
	global_load_lds_dwordx4 v[170:171], off
	v_lshl_add_u64 v[170:171], v[226:227], 0, s[10:11]
	s_mov_b32 m0, s54
	s_nop 0
	global_load_lds_dwordx4 v[170:171], off
	v_lshl_add_u64 v[170:171], v[228:229], 0, s[10:11]
	s_mov_b32 m0, s55
	s_nop 0
	global_load_lds_dwordx4 v[170:171], off
	s_waitcnt vmcnt(8)
	s_waitcnt lgkmcnt(0)
	s_barrier
	s_waitcnt lgkmcnt(0)
	v_mfma_f32_16x16x32_bf16 v[64:67], v[132:135], v[192:195], v[64:67]
	v_mfma_f32_16x16x32_bf16 v[60:63], v[140:143], v[192:195], v[60:63]
	v_mfma_f32_16x16x32_bf16 v[48:51], v[132:135], v[200:203], v[48:51]
	v_mfma_f32_16x16x32_bf16 v[44:47], v[140:143], v[200:203], v[44:47]
	v_mfma_f32_16x16x32_bf16 v[32:35], v[132:135], v[208:211], v[32:35]
	v_mfma_f32_16x16x32_bf16 v[28:31], v[140:143], v[208:211], v[28:31]
	v_mfma_f32_16x16x32_bf16 v[16:19], v[132:135], v[216:219], v[16:19]
	v_mfma_f32_16x16x32_bf16 v[12:15], v[140:143], v[216:219], v[12:15]
	v_mfma_f32_16x16x32_bf16 v[64:67], v[136:139], v[196:199], v[64:67]
	v_mfma_f32_16x16x32_bf16 v[60:63], v[144:147], v[196:199], v[60:63]
	v_mfma_f32_16x16x32_bf16 v[48:51], v[136:139], v[204:207], v[48:51]
	v_mfma_f32_16x16x32_bf16 v[44:47], v[144:147], v[204:207], v[44:47]
	v_mfma_f32_16x16x32_bf16 v[32:35], v[136:139], v[212:215], v[32:35]
	v_mfma_f32_16x16x32_bf16 v[28:31], v[144:147], v[212:215], v[28:31]
	v_mfma_f32_16x16x32_bf16 v[16:19], v[136:139], v[220:223], v[16:19]
	v_mfma_f32_16x16x32_bf16 v[12:15], v[144:147], v[220:223], v[12:15]
	v_mfma_f32_16x16x32_bf16 v[56:59], v[158:161], v[192:195], v[56:59]
	v_mfma_f32_16x16x32_bf16 v[52:55], v[184:187], v[192:195], v[52:55]
	v_mfma_f32_16x16x32_bf16 v[40:43], v[158:161], v[200:203], v[40:43]
	v_mfma_f32_16x16x32_bf16 v[36:39], v[184:187], v[200:203], v[36:39]
	v_mfma_f32_16x16x32_bf16 v[24:27], v[158:161], v[208:211], v[24:27]
	v_mfma_f32_16x16x32_bf16 v[20:23], v[184:187], v[208:211], v[20:23]
	v_mfma_f32_16x16x32_bf16 v[8:11], v[158:161], v[216:219], v[8:11]
	v_mfma_f32_16x16x32_bf16 v[4:7], v[184:187], v[216:219], v[4:7]
	v_mfma_f32_16x16x32_bf16 v[56:59], v[162:165], v[196:199], v[56:59]
	v_mfma_f32_16x16x32_bf16 v[52:55], v[188:191], v[196:199], v[52:55]
	v_mfma_f32_16x16x32_bf16 v[40:43], v[162:165], v[204:207], v[40:43]
	v_mfma_f32_16x16x32_bf16 v[36:39], v[188:191], v[204:207], v[36:39]
	v_mfma_f32_16x16x32_bf16 v[24:27], v[162:165], v[212:215], v[24:27]
	v_mfma_f32_16x16x32_bf16 v[20:23], v[188:191], v[212:215], v[20:23]
	v_mfma_f32_16x16x32_bf16 v[8:11], v[162:165], v[220:223], v[8:11]
	v_mfma_f32_16x16x32_bf16 v[4:7], v[188:191], v[220:223], v[4:7]
	s_barrier
	s_add_i32 s63, s63, 2
	s_add_u32 s61, s61, 0x100
	s_addc_u32 s62, s62, 0
	s_add_u32 s0, s0, 0x100
	s_addc_u32 s1, s1, 0
	s_cmp_gt_u32 s63, 29
	s_cbranch_scc0 .LBB0_563
	s_and_b64 vcc, exec, s[34:35]
	s_cbranch_vccz .LBB0_566
	s_barrier

; template <class Epi, class Sched, bool ALIGN_EPI = false, bool SP2 = false>
; __device__ __forceinline__ void gemm_phase(PG8_LAS unsigned char* lds, const Gemm g, const Sched& S, const Epi& E) {
;     ...
;         const bool has_next = S.next(ui + 1, nxt);
;         const char* nA = has_next ? (const char*)g.A + (size_t)nxt.pm * tstep : cA; const char* nB = has_next ? (const char*)g.Bt + (size_t)nxt.pn * tstep : cB;
;         for (int t = 0; t < nt; t += 2) {
;             const bool last = (t == nt - 2);
;             const char* a1 = cA + (size_t)(t + 1) * kstep;
;             const char* a2 = last ? nA : cA + (size_t)(t + 2) * kstep; const char* b2 = last ? nB : cB + (size_t)(t + 2) * kstep;
;     ...
;         for (int a = 0; a < 2; ++a)
; #pragma unroll
;             for (int b = 0; b < 2; ++b)
; #pragma unroll
;                 for (int m = 0; m < 4; ++m)
; #pragma unroll
;                     for (int n = 0; n < 2; ++n) acc[a][b][m][n] = (f32x4){0.f, 0.f, 0.f, 0.f};
.LBB0_659:
	s_ashr_i32 s65, s64, 31
	s_lshl_b64 s[16:17], s[64:65], 20
	s_add_u32 s66, s19, s16
	s_addc_u32 s67, s20, s17
	s_and_b64 s[16:17], s[40:41], exec
	s_cselect_b32 s23, s67, s15
	s_cselect_b32 s24, s66, s14
	s_ashr_i32 s63, s62, 31
	s_lshl_b64 s[16:17], s[62:63], 20
	s_add_u32 s68, s26, s16
	s_addc_u32 s69, s27, s17
	s_and_b64 s[16:17], s[40:41], exec
	s_cselect_b32 s25, s69, s1
	s_cselect_b32 s42, s68, s0
	s_add_u32 s43, s0, 0x100
	s_addc_u32 s44, s1, 0
	s_add_u32 s0, s14, 0x80080
	v_mov_b32_e32 v4, 0
	s_addc_u32 s1, s15, 0
	s_mov_b32 s45, -2
	v_mov_b32_e32 v5, v4
	v_mov_b32_e32 v6, v4
	v_mov_b32_e32 v7, v4
	v_mov_b32_e32 v8, v4
	v_mov_b32_e32 v9, v4
	v_mov_b32_e32 v10, v4
	v_mov_b32_e32 v11, v4
	v_mov_b32_e32 v12, v4
	v_mov_b32_e32 v13, v4
	v_mov_b32_e32 v14, v4
	v_mov_b32_e32 v15, v4
	v_mov_b32_e32 v16, v4
	v_mov_b32_e32 v17, v4
	v_mov_b32_e32 v18, v4
	v_mov_b32_e32 v19, v4
	v_mov_b32_e32 v20, v4
	v_mov_b32_e32 v21, v4
	v_mov_b32_e32 v22, v4
	v_mov_b32_e32 v23, v4
	v_mov_b32_e32 v24, v4
	v_mov_b32_e32 v25, v4
	v_mov_b32_e32 v26, v4
	v_mov_b32_e32 v27, v4
	s_waitcnt vmcnt(0)
	v_mov_b32_e32 v28, v4
	v_mov_b32_e32 v29, v4
	v_mov_b32_e32 v30, v4
	v_mov_b32_e32 v31, v4
	v_mov_b32_e32 v32, v4
	v_mov_b32_e32 v33, v4
	v_mov_b32_e32 v34, v4
	v_mov_b32_e32 v35, v4
	v_mov_b32_e32 v88, v4
	v_mov_b32_e32 v89, v4
	v_mov_b32_e32 v90, v4
	v_mov_b32_e32 v91, v4
	v_mov_b32_e32 v92, v4
	v_mov_b32_e32 v93, v4
	v_mov_b32_e32 v94, v4
	v_mov_b32_e32 v95, v4
	v_mov_b32_e32 v52, v4
	v_mov_b32_e32 v53, v4
	v_mov_b32_e32 v54, v4
	v_mov_b32_e32 v55, v4
	v_mov_b32_e32 v56, v4
	v_mov_b32_e32 v57, v4
	v_mov_b32_e32 v58, v4
	v_mov_b32_e32 v59, v4
	v_mov_b32_e32 v60, v4
	v_mov_b32_e32 v61, v4
	v_mov_b32_e32 v62, v4
	v_mov_b32_e32 v63, v4
	v_mov_b32_e32 v64, v4
	v_mov_b32_e32 v65, v4
	v_mov_b32_e32 v66, v4
	v_mov_b32_e32 v67, v4
	v_mov_b32_e32 v68, v4
	v_mov_b32_e32 v69, v4
	v_mov_b32_e32 v70, v4
	v_mov_b32_e32 v71, v4
	v_mov_b32_e32 v72, v4
	v_mov_b32_e32 v73, v4
	v_mov_b32_e32 v74, v4
	v_mov_b32_e32 v75, v4
	v_mov_b32_e32 v100, v4
	v_mov_b32_e32 v101, v4
	v_mov_b32_e32 v102, v4
	v_mov_b32_e32 v103, v4
	v_mov_b32_e32 v104, v4
	v_mov_b32_e32 v105, v4
	v_mov_b32_e32 v106, v4
	v_mov_b32_e32 v107, v4
	v_mov_b32_e32 v108, v4
	v_mov_b32_e32 v109, v4
	v_mov_b32_e32 v110, v4
	v_mov_b32_e32 v111, v4
	v_mov_b32_e32 v112, v4
	v_mov_b32_e32 v113, v4
	v_mov_b32_e32 v114, v4
	v_mov_b32_e32 v115, v4
	v_mov_b32_e32 v116, v4
	v_mov_b32_e32 v117, v4
	v_mov_b32_e32 v118, v4
	v_mov_b32_e32 v119, v4
	v_mov_b32_e32 v120, v4
	v_mov_b32_e32 v121, v4
	v_mov_b32_e32 v122, v4
	v_mov_b32_e32 v123, v4
	v_mov_b32_e32 v140, v4
	v_mov_b32_e32 v141, v4
	v_mov_b32_e32 v142, v4
	v_mov_b32_e32 v143, v4
	v_mov_b32_e32 v144, v4
	v_mov_b32_e32 v145, v4
	v_mov_b32_e32 v146, v4
	v_mov_b32_e32 v147, v4
	v_mov_b32_e32 v156, v4
	v_mov_b32_e32 v157, v4
	v_mov_b32_e32 v158, v4
	v_mov_b32_e32 v159, v4
	v_mov_b32_e32 v160, v4
	v_mov_b32_e32 v161, v4
	v_mov_b32_e32 v162, v4
	v_mov_b32_e32 v163, v4
	v_mov_b32_e32 v124, v4
	v_mov_b32_e32 v125, v4
	v_mov_b32_e32 v126, v4
	v_mov_b32_e32 v127, v4
	v_mov_b32_e32 v128, v4
	v_mov_b32_e32 v129, v4
	v_mov_b32_e32 v130, v4
	v_mov_b32_e32 v131, v4
	v_mov_b32_e32 v132, v4
	v_mov_b32_e32 v133, v4
	v_mov_b32_e32 v134, v4
	v_mov_b32_e32 v135, v4
	v_mov_b32_e32 v136, v4
	v_mov_b32_e32 v137, v4
	v_mov_b32_e32 v138, v4
	v_mov_b32_e32 v139, v4
	v_mov_b32_e32 v148, v4
	v_mov_b32_e32 v149, v4
	v_mov_b32_e32 v150, v4
	v_mov_b32_e32 v151, v4
	v_mov_b32_e32 v152, v4
	v_mov_b32_e32 v153, v4
	v_mov_b32_e32 v154, v4
	v_mov_b32_e32 v155, v4
	v_readfirstlane_b32 s101, v172
	s_nop 3
	s_cmp_ge_u32 s101, 0x100
	s_cbranch_scc1 .Lprio_hi_660
	s_setprio 0
	s_branch .Lprio_done_660

; #define PG8_STAGE(bufoff, gbase, voff) do { _Pragma("unroll") for (int _i = 0; _i < 2; ++_i) \
;         __builtin_amdgcn_global_load_lds((const unsigned*)((const char*)(gbase) + (voff)[_i]), (PG8_LAS unsigned*)(lds + (bufoff) + ldsw + _i * 8192), 16, 0, 0); } while (0)
; #define PG8_LDA(dst, b, h) do { _Pragma("unroll") for (int m = 0; m < 4; ++m) _Pragma("unroll") for (int k = 0; k < 2; ++k) dst[m][k] = *(const PG8_LAS bf16x8*)(lds + PG8_SA(b, h) + aoff + m * 2048 + k * 1024); } while (0)
; #define PG8_LDB(dst, b, h) do { _Pragma("unroll") for (int n = 0; n < 2; ++n) _Pragma("unroll") for (int k = 0; k < 2; ++k) dst[n][k] = *(const PG8_LAS bf16x8*)(lds + PG8_SB(b, h) + boff + n * 2048 + k * 1024); } while (0)
; #define PG8_MMA(ai, bj, At, Bt) do { __builtin_amdgcn_s_setprio(1); _Pragma("unroll") for (int m = 0; m < 4; ++m) _Pragma("unroll") for (int n = 0; n < 2; ++n) _Pragma("unroll") for (int k = 0; k < 2; ++k) \
;         acc[ai][bj][m][n] = __builtin_amdgcn_mfma_f32_16x16x32_bf16(Bt[n][k], At[m][k], acc[ai][bj][m][n], 0, 0, 0); __builtin_amdgcn_s_setprio(0); } while (0)
; #define PG8_WAIT_V(n) asm volatile("s_waitcnt vmcnt(" #n ")" ::: "memory")
; #define PG8_WAIT_L(n) asm volatile("s_waitcnt lgkmcnt(" #n ")" ::: "memory")
; #define PG8_BAR __builtin_amdgcn_s_barrier()
; #define PG8_SCHED __builtin_amdgcn_sched_barrier(0)
; template <class Epi, class Sched, bool ALIGN_EPI = false, bool SP2 = false>
; __device__ __forceinline__ void gemm_phase(PG8_LAS unsigned char* lds, const Gemm g, const Sched& S, const Epi& E) {
;     ...
;             PG8_LDB(B0, 0, 0); PG8_LDB(B1, 0, 1); PG8_SCHED; PG8_LDA(At, 0, 0); PG8_STAGE(PG8_SA(1, 1), a1 + hstep, voffA);
;             PG8_WAIT_V(8); PG8_WAIT_L(0); PG8_BAR; PG8_MMA(0, 0, At, B0); PG8_MMA(0, 1, At, B1); PG8_BAR; PG8_SCHED;
;             PG8_LDA(At, 0, 1); PG8_STAGE(PG8_SB(0, 0), b2, voffB); PG8_STAGE(PG8_SB(0, 1), b2 + hstep, voffB); PG8_STAGE(PG8_SA(0, 0), a2, voffA);
;             PG8_WAIT_V(8); PG8_WAIT_L(0); PG8_BAR; PG8_MMA(1, 0, At, B0); PG8_MMA(1, 1, At, B1); PG8_BAR; PG8_SCHED;
.Lprio_done_660:
.LBB0_660:
	s_add_u32 s14, s0, 0xfff80080
	s_addc_u32 s15, s1, -1
	s_add_i32 s46, 0, 0x10000
	s_cmp_eq_u32 s45, 28
	s_cselect_b32 s17, s23, s15
	s_cselect_b32 s16, s24, s14
	s_cselect_b32 s15, s25, s44
	s_cselect_b32 s14, s42, s43
	s_add_i32 s63, 0, 0x14000
	v_add_u32_e32 v48, s46, v243
	v_add_u32_e32 v96, s63, v243
	ds_read_b128 v[36:39], v48
	ds_read_b128 v[40:43], v48 offset:1024
	ds_read_b128 v[44:47], v48 offset:2048
	ds_read_b128 v[48:51], v48 offset:3072
	ds_read_b128 v[76:79], v96
	ds_read_b128 v[80:83], v96 offset:1024
	ds_read_b128 v[84:87], v96 offset:2048
	ds_read_b128 v[96:99], v96 offset:3072
	v_lshl_add_u64 v[224:225], s[0:1], 0, v[198:199]
	s_add_i32 m0, s29, 0xc000
	ds_read_b128 v[164:167], v249
	ds_read_b128 v[168:171], v249 offset:1024
	ds_read_b128 v[200:203], v249 offset:2048
	ds_read_b128 v[204:207], v249 offset:3072
	ds_read_b128 v[208:211], v249 offset:4096
	ds_read_b128 v[212:215], v249 offset:5120
	ds_read_b128 v[216:219], v249 offset:6144
	ds_read_b128 v[220:223], v249 offset:7168
	global_load_lds_dwordx4 v[224:225], off
	v_lshl_add_u64 v[224:225], s[0:1], 0, v[196:197]
	s_add_i32 m0, s29, 0xe000
	s_nop 0
	global_load_lds_dwordx4 v[224:225], off
	s_waitcnt vmcnt(8)
	s_waitcnt lgkmcnt(0)
	s_barrier
	s_waitcnt lgkmcnt(0)
	v_mfma_f32_16x16x32_bf16 v[152:155], v[36:39], v[164:167], v[152:155]
	v_mfma_f32_16x16x32_bf16 v[148:151], v[44:47], v[164:167], v[148:151]
	v_mfma_f32_16x16x32_bf16 v[136:139], v[36:39], v[200:203], v[136:139]
	v_mfma_f32_16x16x32_bf16 v[132:135], v[44:47], v[200:203], v[132:135]
	v_mfma_f32_16x16x32_bf16 v[128:131], v[36:39], v[208:211], v[128:131]
	v_mfma_f32_16x16x32_bf16 v[124:127], v[44:47], v[208:211], v[124:127]
	v_mfma_f32_16x16x32_bf16 v[160:163], v[36:39], v[216:219], v[160:163]
	v_mfma_f32_16x16x32_bf16 v[156:159], v[44:47], v[216:219], v[156:159]
	v_mfma_f32_16x16x32_bf16 v[152:155], v[40:43], v[168:171], v[152:155]
	v_mfma_f32_16x16x32_bf16 v[148:151], v[48:51], v[168:171], v[148:151]
	v_mfma_f32_16x16x32_bf16 v[136:139], v[40:43], v[204:207], v[136:139]
	v_mfma_f32_16x16x32_bf16 v[132:135], v[48:51], v[204:207], v[132:135]
	v_mfma_f32_16x16x32_bf16 v[128:131], v[40:43], v[212:215], v[128:131]
	v_mfma_f32_16x16x32_bf16 v[124:127], v[48:51], v[212:215], v[124:127]
	v_mfma_f32_16x16x32_bf16 v[160:163], v[40:43], v[220:223], v[160:163]
	v_mfma_f32_16x16x32_bf16 v[156:159], v[48:51], v[220:223], v[156:159]
	v_mfma_f32_16x16x32_bf16 v[144:147], v[76:79], v[164:167], v[144:147]
	v_mfma_f32_16x16x32_bf16 v[140:143], v[84:87], v[164:167], v[140:143]
	v_mfma_f32_16x16x32_bf16 v[120:123], v[76:79], v[200:203], v[120:123]
	v_mfma_f32_16x16x32_bf16 v[116:119], v[84:87], v[200:203], v[116:119]
	v_mfma_f32_16x16x32_bf16 v[112:115], v[76:79], v[208:211], v[112:115]
	v_mfma_f32_16x16x32_bf16 v[108:111], v[84:87], v[208:211], v[108:111]
	v_mfma_f32_16x16x32_bf16 v[104:107], v[76:79], v[216:219], v[104:107]
	v_mfma_f32_16x16x32_bf16 v[100:103], v[84:87], v[216:219], v[100:103]
	v_mfma_f32_16x16x32_bf16 v[144:147], v[80:83], v[168:171], v[144:147]
	v_mfma_f32_16x16x32_bf16 v[140:143], v[96:99], v[168:171], v[140:143]
	v_mfma_f32_16x16x32_bf16 v[120:123], v[80:83], v[204:207], v[120:123]
	v_mfma_f32_16x16x32_bf16 v[116:119], v[96:99], v[204:207], v[116:119]
	v_mfma_f32_16x16x32_bf16 v[112:115], v[80:83], v[212:215], v[112:115]
	v_mfma_f32_16x16x32_bf16 v[108:111], v[96:99], v[212:215], v[108:111]
	v_mfma_f32_16x16x32_bf16 v[104:107], v[80:83], v[220:223], v[104:107]
	v_mfma_f32_16x16x32_bf16 v[100:103], v[96:99], v[220:223], v[100:103]
	s_barrier
	s_add_i32 s46, s46, s28
	v_lshl_add_u64 v[232:233], s[14:15], 0, v[188:189]
	s_mov_b32 m0, s46
	ds_read_b128 v[164:167], v249 offset:16384
	ds_read_b128 v[168:171], v249 offset:17408
	ds_read_b128 v[200:203], v249 offset:18432
	ds_read_b128 v[204:207], v249 offset:19456
	ds_read_b128 v[208:211], v249 offset:20480
	ds_read_b128 v[212:215], v249 offset:21504
	ds_read_b128 v[216:219], v249 offset:22528
	ds_read_b128 v[220:223], v249 offset:23552
	global_load_lds_dwordx4 v[232:233], off
	s_add_i32 m0, s46, 0x2000
	s_add_u32 s46, s14, 0x80000
	v_lshl_add_u64 v[234:235], s[14:15], 0, v[184:185]
	s_addc_u32 s47, s15, 0
	s_add_i32 s63, s63, s28
	global_load_lds_dwordx4 v[234:235], off
	v_lshl_add_u64 v[224:225], s[46:47], 0, v[188:189]
	s_mov_b32 m0, s63
	v_lshl_add_u64 v[236:237], s[16:17], 0, v[190:191]
	global_load_lds_dwordx4 v[224:225], off
	v_lshl_add_u64 v[224:225], s[46:47], 0, v[184:185]
	s_add_i32 m0, s63, 0x2000
	v_lshl_add_u64 v[250:251], s[16:17], 0, v[186:187]
	global_load_lds_dwordx4 v[224:225], off
	s_mov_b32 m0, s29
	s_nop 0
	global_load_lds_dwordx4 v[236:237], off
	s_mov_b32 m0, s30
	s_nop 0
	global_load_lds_dwordx4 v[250:251], off
	s_waitcnt vmcnt(8)
	s_waitcnt lgkmcnt(0)
	s_barrier
; #define PG8_STAGE(bufoff, gbase, voff) do { _Pragma("unroll") for (int _i = 0; _i < 2; ++_i) \
;         __builtin_amdgcn_global_load_lds((const unsigned*)((const char*)(gbase) + (voff)[_i]), (PG8_LAS unsigned*)(lds + (bufoff) + ldsw + _i * 8192), 16, 0, 0); } while (0)
; #define PG8_LDA(dst, b, h) do { _Pragma("unroll") for (int m = 0; m < 4; ++m) _Pragma("unroll") for (int k = 0; k < 2; ++k) dst[m][k] = *(const PG8_LAS bf16x8*)(lds + PG8_SA(b, h) + aoff + m * 2048 + k * 1024); } while (0)
; #define PG8_LDB(dst, b, h) do { _Pragma("unroll") for (int n = 0; n < 2; ++n) _Pragma("unroll") for (int k = 0; k < 2; ++k) dst[n][k] = *(const PG8_LAS bf16x8*)(lds + PG8_SB(b, h) + boff + n * 2048 + k * 1024); } while (0)
; #define PG8_MMA(ai, bj, At, Bt) do { __builtin_amdgcn_s_setprio(1); _Pragma("unroll") for (int m = 0; m < 4; ++m) _Pragma("unroll") for (int n = 0; n < 2; ++n) _Pragma("unroll") for (int k = 0; k < 2; ++k) \
;         acc[ai][bj][m][n] = __builtin_amdgcn_mfma_f32_16x16x32_bf16(Bt[n][k], At[m][k], acc[ai][bj][m][n], 0, 0, 0); __builtin_amdgcn_s_setprio(0); } while (0)
; #define PG8_WAIT_V(n) asm volatile("s_waitcnt vmcnt(" #n ")" ::: "memory")
; #define PG8_WAIT_L(n) asm volatile("s_waitcnt lgkmcnt(" #n ")" ::: "memory")
; #define PG8_BAR __builtin_amdgcn_s_barrier()
; #define PG8_SCHED __builtin_amdgcn_sched_barrier(0)
; template <class Epi, class Sched, bool ALIGN_EPI = false, bool SP2 = false>
; __device__ __forceinline__ void gemm_phase(PG8_LAS unsigned char* lds, const Gemm g, const Sched& S, const Epi& E) {
;     ...
;             PG8_WAIT_V(8); PG8_WAIT_L(0); PG8_BAR; PG8_MMA(1, 0, At, B0); PG8_MMA(1, 1, At, B1); PG8_BAR; PG8_SCHED;
;             PG8_LDB(B0, 1, 0); PG8_LDB(B1, 1, 1); PG8_SCHED; PG8_LDA(At, 1, 0); PG8_STAGE(PG8_SA(0, 1), a2 + hstep, voffA);
;             PG8_WAIT_V(8); PG8_WAIT_L(0); PG8_BAR; PG8_MMA(0, 0, At, B0); PG8_MMA(0, 1, At, B1); PG8_BAR; PG8_SCHED;
	s_waitcnt lgkmcnt(0)
	v_mfma_f32_16x16x32_bf16 v[72:75], v[36:39], v[164:167], v[72:75]
	v_mfma_f32_16x16x32_bf16 v[68:71], v[44:47], v[164:167], v[68:71]
	v_mfma_f32_16x16x32_bf16 v[64:67], v[36:39], v[200:203], v[64:67]
	v_mfma_f32_16x16x32_bf16 v[60:63], v[44:47], v[200:203], v[60:63]
	v_mfma_f32_16x16x32_bf16 v[56:59], v[36:39], v[208:211], v[56:59]
	v_mfma_f32_16x16x32_bf16 v[52:55], v[44:47], v[208:211], v[52:55]
	v_mfma_f32_16x16x32_bf16 v[36:39], v[36:39], v[216:219], v[92:95]
	v_mfma_f32_16x16x32_bf16 v[72:75], v[40:43], v[168:171], v[72:75]
	v_mfma_f32_16x16x32_bf16 v[68:71], v[48:51], v[168:171], v[68:71]
	v_mfma_f32_16x16x32_bf16 v[64:67], v[40:43], v[204:207], v[64:67]
	v_mfma_f32_16x16x32_bf16 v[60:63], v[48:51], v[204:207], v[60:63]
	v_mfma_f32_16x16x32_bf16 v[56:59], v[40:43], v[212:215], v[56:59]
	v_mfma_f32_16x16x32_bf16 v[52:55], v[48:51], v[212:215], v[52:55]
	v_mfma_f32_16x16x32_bf16 v[36:39], v[40:43], v[220:223], v[36:39]
	v_mfma_f32_16x16x32_bf16 v[40:43], v[44:47], v[216:219], v[88:91]
	v_mfma_f32_16x16x32_bf16 v[40:43], v[48:51], v[220:223], v[40:43]
	v_mfma_f32_16x16x32_bf16 v[32:35], v[76:79], v[164:167], v[32:35]
	v_mfma_f32_16x16x32_bf16 v[28:31], v[84:87], v[164:167], v[28:31]
	v_mfma_f32_16x16x32_bf16 v[24:27], v[76:79], v[200:203], v[24:27]
	v_mfma_f32_16x16x32_bf16 v[20:23], v[84:87], v[200:203], v[20:23]
	v_mfma_f32_16x16x32_bf16 v[16:19], v[76:79], v[208:211], v[16:19]
	v_mfma_f32_16x16x32_bf16 v[12:15], v[84:87], v[208:211], v[12:15]
	v_mfma_f32_16x16x32_bf16 v[8:11], v[76:79], v[216:219], v[8:11]
	v_mfma_f32_16x16x32_bf16 v[4:7], v[84:87], v[216:219], v[4:7]
	v_mfma_f32_16x16x32_bf16 v[32:35], v[80:83], v[168:171], v[32:35]
	v_mfma_f32_16x16x32_bf16 v[28:31], v[96:99], v[168:171], v[28:31]
	v_mfma_f32_16x16x32_bf16 v[24:27], v[80:83], v[204:207], v[24:27]
	v_mfma_f32_16x16x32_bf16 v[20:23], v[96:99], v[204:207], v[20:23]
	v_mfma_f32_16x16x32_bf16 v[16:19], v[80:83], v[212:215], v[16:19]
	v_mfma_f32_16x16x32_bf16 v[12:15], v[96:99], v[212:215], v[12:15]
	v_mfma_f32_16x16x32_bf16 v[8:11], v[80:83], v[220:223], v[8:11]
	v_mfma_f32_16x16x32_bf16 v[4:7], v[96:99], v[220:223], v[4:7]
	s_barrier
	s_add_i32 s46, 0, 0x18000
	s_add_i32 s47, 0, 0x1c000
	v_add_u32_e32 v80, s46, v243
	v_add_u32_e32 v88, s47, v243
	ds_read_b128 v[44:47], v80
	ds_read_b128 v[48:51], v80 offset:1024
	ds_read_b128 v[76:79], v80 offset:2048
	ds_read_b128 v[80:83], v80 offset:3072
	ds_read_b128 v[84:87], v88
	ds_read_b128 v[96:99], v88 offset:1024
	ds_read_b128 v[164:167], v88 offset:2048
	ds_read_b128 v[168:171], v88 offset:3072
	s_add_u32 s16, s16, 0x80000
	s_addc_u32 s17, s17, 0
	s_mov_b32 m0, s31
	v_lshl_add_u64 v[224:225], s[16:17], 0, v[190:191]
	ds_read_b128 v[88:91], v249 offset:32768
	ds_read_b128 v[92:95], v249 offset:33792
	ds_read_b128 v[200:203], v249 offset:34816
	ds_read_b128 v[204:207], v249 offset:35840
	ds_read_b128 v[208:211], v249 offset:36864
	ds_read_b128 v[212:215], v249 offset:37888
	ds_read_b128 v[216:219], v249 offset:38912
	ds_read_b128 v[220:223], v249 offset:39936
	global_load_lds_dwordx4 v[224:225], off
	v_lshl_add_u64 v[224:225], s[16:17], 0, v[186:187]
	s_mov_b32 m0, s34
	s_nop 0
	global_load_lds_dwordx4 v[224:225], off
	s_waitcnt vmcnt(8)
	s_waitcnt lgkmcnt(0)
	s_barrier
	s_waitcnt lgkmcnt(0)
	v_mfma_f32_16x16x32_bf16 v[152:155], v[44:47], v[88:91], v[152:155]
	v_mfma_f32_16x16x32_bf16 v[148:151], v[76:79], v[88:91], v[148:151]
	v_mfma_f32_16x16x32_bf16 v[136:139], v[44:47], v[200:203], v[136:139]
	v_mfma_f32_16x16x32_bf16 v[132:135], v[76:79], v[200:203], v[132:135]
	v_mfma_f32_16x16x32_bf16 v[128:131], v[44:47], v[208:211], v[128:131]
	v_mfma_f32_16x16x32_bf16 v[124:127], v[76:79], v[208:211], v[124:127]
	v_mfma_f32_16x16x32_bf16 v[160:163], v[44:47], v[216:219], v[160:163]
	v_mfma_f32_16x16x32_bf16 v[156:159], v[76:79], v[216:219], v[156:159]
	v_mfma_f32_16x16x32_bf16 v[152:155], v[48:51], v[92:95], v[152:155]
	v_mfma_f32_16x16x32_bf16 v[148:151], v[80:83], v[92:95], v[148:151]
	v_mfma_f32_16x16x32_bf16 v[136:139], v[48:51], v[204:207], v[136:139]
	v_mfma_f32_16x16x32_bf16 v[132:135], v[80:83], v[204:207], v[132:135]
	v_mfma_f32_16x16x32_bf16 v[128:131], v[48:51], v[212:215], v[128:131]
	v_mfma_f32_16x16x32_bf16 v[124:127], v[80:83], v[212:215], v[124:127]
	v_mfma_f32_16x16x32_bf16 v[160:163], v[48:51], v[220:223], v[160:163]
	v_mfma_f32_16x16x32_bf16 v[156:159], v[80:83], v[220:223], v[156:159]
	v_mfma_f32_16x16x32_bf16 v[144:147], v[84:87], v[88:91], v[144:147]
	v_mfma_f32_16x16x32_bf16 v[88:91], v[164:167], v[88:91], v[140:143]
	v_mfma_f32_16x16x32_bf16 v[140:143], v[168:171], v[92:95], v[88:91]
	v_mfma_f32_16x16x32_bf16 v[88:91], v[84:87], v[200:203], v[120:123]
	v_mfma_f32_16x16x32_bf16 v[120:123], v[96:99], v[204:207], v[88:91]
	v_mfma_f32_16x16x32_bf16 v[88:91], v[164:167], v[200:203], v[116:119]
	v_mfma_f32_16x16x32_bf16 v[116:119], v[168:171], v[204:207], v[88:91]
	v_mfma_f32_16x16x32_bf16 v[88:91], v[84:87], v[208:211], v[112:115]
	v_mfma_f32_16x16x32_bf16 v[112:115], v[96:99], v[212:215], v[88:91]
	v_mfma_f32_16x16x32_bf16 v[88:91], v[164:167], v[208:211], v[108:111]
	v_mfma_f32_16x16x32_bf16 v[108:111], v[168:171], v[212:215], v[88:91]
	v_mfma_f32_16x16x32_bf16 v[88:91], v[84:87], v[216:219], v[104:107]
	v_mfma_f32_16x16x32_bf16 v[104:107], v[96:99], v[220:223], v[88:91]
	v_mfma_f32_16x16x32_bf16 v[88:91], v[164:167], v[216:219], v[100:103]
	v_mfma_f32_16x16x32_bf16 v[144:147], v[96:99], v[92:95], v[144:147]
	v_mfma_f32_16x16x32_bf16 v[100:103], v[168:171], v[220:223], v[88:91]
	s_barrier
; #define PG8_STAGE(bufoff, gbase, voff) do { _Pragma("unroll") for (int _i = 0; _i < 2; ++_i) \
;         __builtin_amdgcn_global_load_lds((const unsigned*)((const char*)(gbase) + (voff)[_i]), (PG8_LAS unsigned*)(lds + (bufoff) + ldsw + _i * 8192), 16, 0, 0); } while (0)
; #define PG8_LDA(dst, b, h) do { _Pragma("unroll") for (int m = 0; m < 4; ++m) _Pragma("unroll") for (int k = 0; k < 2; ++k) dst[m][k] = *(const PG8_LAS bf16x8*)(lds + PG8_SA(b, h) + aoff + m * 2048 + k * 1024); } while (0)
; #define PG8_MMA(ai, bj, At, Bt) do { __builtin_amdgcn_s_setprio(1); _Pragma("unroll") for (int m = 0; m < 4; ++m) _Pragma("unroll") for (int n = 0; n < 2; ++n) _Pragma("unroll") for (int k = 0; k < 2; ++k) \
;         acc[ai][bj][m][n] = __builtin_amdgcn_mfma_f32_16x16x32_bf16(Bt[n][k], At[m][k], acc[ai][bj][m][n], 0, 0, 0); __builtin_amdgcn_s_setprio(0); } while (0)
; #define PG8_WAIT_V(n) asm volatile("s_waitcnt vmcnt(" #n ")" ::: "memory")
; #define PG8_WAIT_L(n) asm volatile("s_waitcnt lgkmcnt(" #n ")" ::: "memory")
; #define PG8_BAR __builtin_amdgcn_s_barrier()
; #define PG8_SCHED __builtin_amdgcn_sched_barrier(0)
; template <class Epi, class Sched, bool ALIGN_EPI = false, bool SP2 = false>
; __device__ __forceinline__ void gemm_phase(PG8_LAS unsigned char* lds, const Gemm g, const Sched& S, const Epi& E) {
;     ...
;             PG8_LDA(At, 1, 1); PG8_STAGE(PG8_SB(1, 0), b3, voffB); PG8_STAGE(PG8_SB(1, 1), b3 + hstep, voffB); PG8_STAGE(PG8_SA(1, 0), a3, voffA);
;             PG8_WAIT_V(8); PG8_WAIT_L(0); PG8_BAR; PG8_MMA(1, 0, At, B0); PG8_MMA(1, 1, At, B1); PG8_BAR; PG8_SCHED;
	s_add_i32 s16, s46, s28
	s_nop 2
	v_lshl_add_u64 v[88:89], v[232:233], 0, s[10:11]
	s_mov_b32 m0, s16
	ds_read_b128 v[200:203], v249 offset:49152
	ds_read_b128 v[204:207], v249 offset:50176
	ds_read_b128 v[208:211], v249 offset:51200
	ds_read_b128 v[212:215], v249 offset:52224
	ds_read_b128 v[216:219], v249 offset:53248
	ds_read_b128 v[220:223], v249 offset:54272
	ds_read_b128 v[224:227], v249 offset:55296
	ds_read_b128 v[228:231], v249 offset:56320
	global_load_lds_dwordx4 v[88:89], off
	s_add_i32 m0, s16, 0x2000
	s_add_u32 s14, s14, 0x80080
	v_lshl_add_u64 v[88:89], v[234:235], 0, s[10:11]
	s_addc_u32 s15, s15, 0
	s_add_i32 s16, s47, s28
	global_load_lds_dwordx4 v[88:89], off
	v_lshl_add_u64 v[88:89], s[14:15], 0, v[188:189]
	s_mov_b32 m0, s16
	s_nop 0
	global_load_lds_dwordx4 v[88:89], off
	v_lshl_add_u64 v[88:89], s[14:15], 0, v[184:185]
	s_add_i32 m0, s16, 0x2000
	s_nop 0
	global_load_lds_dwordx4 v[88:89], off
	v_lshl_add_u64 v[88:89], v[236:237], 0, s[10:11]
	s_mov_b32 m0, s72
	s_nop 0
	global_load_lds_dwordx4 v[88:89], off
	v_lshl_add_u64 v[88:89], v[250:251], 0, s[10:11]
	s_mov_b32 m0, s73
	s_nop 0
	global_load_lds_dwordx4 v[88:89], off
	s_waitcnt vmcnt(8)
	s_waitcnt lgkmcnt(0)
	s_barrier
	s_waitcnt lgkmcnt(0)
	v_mfma_f32_16x16x32_bf16 v[36:39], v[44:47], v[224:227], v[36:39]
	v_mfma_f32_16x16x32_bf16 v[72:75], v[44:47], v[200:203], v[72:75]
	v_mfma_f32_16x16x32_bf16 v[68:71], v[76:79], v[200:203], v[68:71]
	v_mfma_f32_16x16x32_bf16 v[64:67], v[44:47], v[208:211], v[64:67]
	v_mfma_f32_16x16x32_bf16 v[60:63], v[76:79], v[208:211], v[60:63]
	v_mfma_f32_16x16x32_bf16 v[56:59], v[44:47], v[216:219], v[56:59]
	v_mfma_f32_16x16x32_bf16 v[52:55], v[76:79], v[216:219], v[52:55]
	v_mfma_f32_16x16x32_bf16 v[92:95], v[48:51], v[228:231], v[36:39]
	v_mfma_f32_16x16x32_bf16 v[36:39], v[76:79], v[224:227], v[40:43]
	v_mfma_f32_16x16x32_bf16 v[72:75], v[48:51], v[204:207], v[72:75]
	v_mfma_f32_16x16x32_bf16 v[68:71], v[80:83], v[204:207], v[68:71]
	v_mfma_f32_16x16x32_bf16 v[64:67], v[48:51], v[212:215], v[64:67]
	v_mfma_f32_16x16x32_bf16 v[60:63], v[80:83], v[212:215], v[60:63]
	v_mfma_f32_16x16x32_bf16 v[56:59], v[48:51], v[220:223], v[56:59]
	v_mfma_f32_16x16x32_bf16 v[52:55], v[80:83], v[220:223], v[52:55]
	v_mfma_f32_16x16x32_bf16 v[88:91], v[80:83], v[228:231], v[36:39]
	v_mfma_f32_16x16x32_bf16 v[32:35], v[84:87], v[200:203], v[32:35]
	v_mfma_f32_16x16x32_bf16 v[28:31], v[164:167], v[200:203], v[28:31]
	v_mfma_f32_16x16x32_bf16 v[24:27], v[84:87], v[208:211], v[24:27]
	v_mfma_f32_16x16x32_bf16 v[20:23], v[164:167], v[208:211], v[20:23]
	v_mfma_f32_16x16x32_bf16 v[16:19], v[84:87], v[216:219], v[16:19]
	v_mfma_f32_16x16x32_bf16 v[12:15], v[164:167], v[216:219], v[12:15]
	v_mfma_f32_16x16x32_bf16 v[8:11], v[84:87], v[224:227], v[8:11]
	v_mfma_f32_16x16x32_bf16 v[4:7], v[164:167], v[224:227], v[4:7]
	v_mfma_f32_16x16x32_bf16 v[32:35], v[96:99], v[204:207], v[32:35]
	v_mfma_f32_16x16x32_bf16 v[28:31], v[168:171], v[204:207], v[28:31]
	v_mfma_f32_16x16x32_bf16 v[24:27], v[96:99], v[212:215], v[24:27]
	v_mfma_f32_16x16x32_bf16 v[20:23], v[168:171], v[212:215], v[20:23]
	v_mfma_f32_16x16x32_bf16 v[16:19], v[96:99], v[220:223], v[16:19]
	v_mfma_f32_16x16x32_bf16 v[12:15], v[168:171], v[220:223], v[12:15]
	v_mfma_f32_16x16x32_bf16 v[8:11], v[96:99], v[228:231], v[8:11]
	v_mfma_f32_16x16x32_bf16 v[4:7], v[168:171], v[228:231], v[4:7]
	s_barrier
	s_add_i32 s45, s45, 2
	s_add_u32 s43, s43, 0x100
	s_addc_u32 s44, s44, 0
	s_add_u32 s0, s0, 0x100
	s_addc_u32 s1, s1, 0
	s_cmp_gt_u32 s45, 29
	s_cbranch_scc0 .LBB0_660
	s_and_b64 vcc, exec, s[52:53]
	s_cbranch_vccz .LBB0_663
	s_barrier

; template <class Epi, class Sched, bool ALIGN_EPI = false, bool SP2 = false>
; __device__ __forceinline__ void gemm_phase(PG8_LAS unsigned char* lds, const Gemm g, const Sched& S, const Epi& E) {
;     ...
;         for (int a = 0; a < 2; ++a)
; #pragma unroll
;             for (int b = 0; b < 2; ++b)
; #pragma unroll
;                 for (int m = 0; m < 4; ++m)
; #pragma unroll
;                     for (int n = 0; n < 2; ++n) acc[a][b][m][n] = (f32x4){0.f, 0.f, 0.f, 0.f};
.LBB0_821:
	s_add_u32 s23, s14, 0x100
	v_mov_b32_e32 v4, 0
	s_addc_u32 s24, s15, 0
	s_mov_b32 s25, -2
	s_waitcnt lgkmcnt(0)
	v_mov_b32_e32 v5, v4
	v_mov_b32_e32 v6, v4
	v_mov_b32_e32 v7, v4
	v_mov_b32_e32 v8, v4
	v_mov_b32_e32 v9, v4
	v_mov_b32_e32 v10, v4
	v_mov_b32_e32 v11, v4
	v_mov_b32_e32 v20, v4
	v_mov_b32_e32 v21, v4
	v_mov_b32_e32 v22, v4
	v_mov_b32_e32 v23, v4
	v_mov_b32_e32 v24, v4
	v_mov_b32_e32 v25, v4
	v_mov_b32_e32 v26, v4
	v_mov_b32_e32 v27, v4
	s_waitcnt vmcnt(0)
	v_mov_b32_e32 v36, v4
	v_mov_b32_e32 v37, v4
	v_mov_b32_e32 v38, v4
	v_mov_b32_e32 v39, v4
	v_mov_b32_e32 v40, v4
	v_mov_b32_e32 v41, v4
	v_mov_b32_e32 v42, v4
	v_mov_b32_e32 v43, v4
	v_mov_b32_e32 v52, v4
	v_mov_b32_e32 v53, v4
	v_mov_b32_e32 v54, v4
	v_mov_b32_e32 v55, v4
	v_mov_b32_e32 v56, v4
	v_mov_b32_e32 v57, v4
	v_mov_b32_e32 v58, v4
	v_mov_b32_e32 v59, v4
	v_mov_b32_e32 v12, v4
	v_mov_b32_e32 v13, v4
	v_mov_b32_e32 v14, v4
	v_mov_b32_e32 v15, v4
	v_mov_b32_e32 v16, v4
	v_mov_b32_e32 v17, v4
	v_mov_b32_e32 v18, v4
	v_mov_b32_e32 v19, v4
	v_mov_b32_e32 v28, v4
	v_mov_b32_e32 v29, v4
	v_mov_b32_e32 v30, v4
	v_mov_b32_e32 v31, v4
	v_mov_b32_e32 v32, v4
	v_mov_b32_e32 v33, v4
	v_mov_b32_e32 v34, v4
	v_mov_b32_e32 v35, v4
	v_mov_b32_e32 v44, v4
	v_mov_b32_e32 v45, v4
	v_mov_b32_e32 v46, v4
	v_mov_b32_e32 v47, v4
	v_mov_b32_e32 v48, v4
	v_mov_b32_e32 v49, v4
	v_mov_b32_e32 v50, v4
	v_mov_b32_e32 v51, v4
	v_mov_b32_e32 v60, v4
	v_mov_b32_e32 v61, v4
	v_mov_b32_e32 v62, v4
	v_mov_b32_e32 v63, v4
	v_mov_b32_e32 v64, v4
	v_mov_b32_e32 v65, v4
	v_mov_b32_e32 v66, v4
	v_mov_b32_e32 v67, v4
	v_mov_b32_e32 v68, v4
	v_mov_b32_e32 v69, v4
	v_mov_b32_e32 v70, v4
	v_mov_b32_e32 v71, v4
	v_mov_b32_e32 v72, v4
	v_mov_b32_e32 v73, v4
	v_mov_b32_e32 v74, v4
	v_mov_b32_e32 v75, v4
	v_mov_b32_e32 v84, v4
	v_mov_b32_e32 v85, v4
	v_mov_b32_e32 v86, v4
	v_mov_b32_e32 v87, v4
	v_mov_b32_e32 v88, v4
	v_mov_b32_e32 v89, v4
	v_mov_b32_e32 v90, v4
	v_mov_b32_e32 v91, v4
	v_mov_b32_e32 v100, v4
	v_mov_b32_e32 v101, v4
	v_mov_b32_e32 v102, v4
	v_mov_b32_e32 v103, v4
	v_mov_b32_e32 v104, v4
	v_mov_b32_e32 v105, v4
	v_mov_b32_e32 v106, v4
	v_mov_b32_e32 v107, v4
	v_mov_b32_e32 v124, v4
	v_mov_b32_e32 v125, v4
	v_mov_b32_e32 v126, v4
	v_mov_b32_e32 v127, v4
	v_mov_b32_e32 v128, v4
	v_mov_b32_e32 v129, v4
	v_mov_b32_e32 v130, v4
	v_mov_b32_e32 v131, v4
	v_mov_b32_e32 v76, v4
	v_mov_b32_e32 v77, v4
	v_mov_b32_e32 v78, v4
	v_mov_b32_e32 v79, v4
	v_mov_b32_e32 v80, v4
	v_mov_b32_e32 v81, v4
	v_mov_b32_e32 v82, v4
	v_mov_b32_e32 v83, v4
	v_mov_b32_e32 v92, v4
	v_mov_b32_e32 v93, v4
	v_mov_b32_e32 v94, v4
	v_mov_b32_e32 v95, v4
	v_mov_b32_e32 v96, v4
	v_mov_b32_e32 v97, v4
	v_mov_b32_e32 v98, v4
	v_mov_b32_e32 v99, v4
	v_mov_b32_e32 v108, v4
	v_mov_b32_e32 v109, v4
	v_mov_b32_e32 v110, v4
	v_mov_b32_e32 v111, v4
	v_mov_b32_e32 v112, v4
	v_mov_b32_e32 v113, v4
	v_mov_b32_e32 v114, v4
	v_mov_b32_e32 v115, v4
	v_mov_b32_e32 v132, v4
	v_mov_b32_e32 v133, v4
	v_mov_b32_e32 v134, v4
	v_mov_b32_e32 v135, v4
	v_mov_b32_e32 v136, v4
	v_mov_b32_e32 v137, v4
	v_mov_b32_e32 v138, v4
	v_mov_b32_e32 v139, v4
	v_readfirstlane_b32 s101, v172
	s_nop 3
	s_cmp_ge_u32 s101, 0x100
	s_cbranch_scc1 .Lprio_hi_822
	s_setprio 0
	s_branch .Lprio_done_822

; #define PG8_STAGE(bufoff, gbase, voff) do { _Pragma("unroll") for (int _i = 0; _i < 2; ++_i) \
;         __builtin_amdgcn_global_load_lds((const unsigned*)((const char*)(gbase) + (voff)[_i]), (PG8_LAS unsigned*)(lds + (bufoff) + ldsw + _i * 8192), 16, 0, 0); } while (0)
; #define PG8_LDA(dst, b, h) do { _Pragma("unroll") for (int m = 0; m < 4; ++m) _Pragma("unroll") for (int k = 0; k < 2; ++k) dst[m][k] = *(const PG8_LAS bf16x8*)(lds + PG8_SA(b, h) + aoff + m * 2048 + k * 1024); } while (0)
; #define PG8_LDB(dst, b, h) do { _Pragma("unroll") for (int n = 0; n < 2; ++n) _Pragma("unroll") for (int k = 0; k < 2; ++k) dst[n][k] = *(const PG8_LAS bf16x8*)(lds + PG8_SB(b, h) + boff + n * 2048 + k * 1024); } while (0)
; #define PG8_MMA(ai, bj, At, Bt) do { __builtin_amdgcn_s_setprio(1); _Pragma("unroll") for (int m = 0; m < 4; ++m) _Pragma("unroll") for (int n = 0; n < 2; ++n) _Pragma("unroll") for (int k = 0; k < 2; ++k) \
;         acc[ai][bj][m][n] = __builtin_amdgcn_mfma_f32_16x16x32_bf16(Bt[n][k], At[m][k], acc[ai][bj][m][n], 0, 0, 0); __builtin_amdgcn_s_setprio(0); } while (0)
; #define PG8_WAIT_V(n) asm volatile("s_waitcnt vmcnt(" #n ")" ::: "memory")
; #define PG8_WAIT_L(n) asm volatile("s_waitcnt lgkmcnt(" #n ")" ::: "memory")
; #define PG8_BAR __builtin_amdgcn_s_barrier()
; #define PG8_SCHED __builtin_amdgcn_sched_barrier(0)
; template <class Epi, class Sched, bool ALIGN_EPI = false, bool SP2 = false>
; __device__ __forceinline__ void gemm_phase(PG8_LAS unsigned char* lds, const Gemm g, const Sched& S, const Epi& E) {
;     ...
;             PG8_LDB(B0, 0, 0); PG8_LDB(B1, 0, 1); PG8_SCHED; PG8_LDA(At, 0, 0); PG8_STAGE(PG8_SA(1, 1), a1 + hstep, voffA);
;             PG8_WAIT_V(8); PG8_WAIT_L(0); PG8_BAR; PG8_MMA(0, 0, At, B0); PG8_MMA(0, 1, At, B1); PG8_BAR; PG8_SCHED;
;             PG8_LDA(At, 0, 1); PG8_STAGE(PG8_SB(0, 0), b2, voffB); PG8_STAGE(PG8_SB(0, 1), b2 + hstep, voffB); PG8_STAGE(PG8_SA(0, 0), a2, voffA);
;             PG8_WAIT_V(8); PG8_WAIT_L(0); PG8_BAR; PG8_MMA(1, 0, At, B0); PG8_MMA(1, 1, At, B1); PG8_BAR; PG8_SCHED;
.Lprio_done_822:
.LBB0_822:
	s_add_u32 s14, s0, 0x100
	s_addc_u32 s15, s1, 0
	s_add_i32 s60, 0, 0x10000
	s_cmpk_eq_i32 s25, 0x52
	s_cselect_b32 s19, s41, s15
	s_cselect_b32 s18, s40, s14
	s_cselect_b32 s17, s51, s24
	s_cselect_b32 s16, s50, s23
	s_add_i32 s61, 0, 0x14000
	v_add_u32_e32 v154, s60, v159
	v_add_u32_e32 v170, s61, v159
	ds_read_b128 v[116:119], v154
	ds_read_b128 v[120:123], v154 offset:1024
	ds_read_b128 v[150:153], v154 offset:2048
	ds_read_b128 v[154:157], v154 offset:3072
	ds_read_b128 v[162:165], v170
	ds_read_b128 v[166:169], v170 offset:1024
	ds_read_b128 v[184:187], v170 offset:2048
	ds_read_b128 v[188:191], v170 offset:3072
	v_lshl_add_u64 v[170:171], s[0:1], 0, v[148:149]
	s_add_i32 m0, s31, 0xc000
	ds_read_b128 v[192:195], v161
	ds_read_b128 v[196:199], v161 offset:1024
	ds_read_b128 v[200:203], v161 offset:2048
	ds_read_b128 v[204:207], v161 offset:3072
	ds_read_b128 v[208:211], v161 offset:4096
	ds_read_b128 v[212:215], v161 offset:5120
	ds_read_b128 v[216:219], v161 offset:6144
	ds_read_b128 v[220:223], v161 offset:7168
	global_load_lds_dwordx4 v[170:171], off
	v_lshl_add_u64 v[170:171], s[0:1], 0, v[146:147]
	s_add_i32 m0, s31, 0xe000
	s_nop 0
	global_load_lds_dwordx4 v[170:171], off
	s_waitcnt vmcnt(8)
	s_waitcnt lgkmcnt(0)
	s_barrier
	s_waitcnt lgkmcnt(0)
	v_mfma_f32_16x16x32_bf16 v[136:139], v[116:119], v[192:195], v[136:139]
	v_mfma_f32_16x16x32_bf16 v[132:135], v[150:153], v[192:195], v[132:135]
	v_mfma_f32_16x16x32_bf16 v[112:115], v[116:119], v[200:203], v[112:115]
	v_mfma_f32_16x16x32_bf16 v[108:111], v[150:153], v[200:203], v[108:111]
	v_mfma_f32_16x16x32_bf16 v[96:99], v[116:119], v[208:211], v[96:99]
	v_mfma_f32_16x16x32_bf16 v[92:95], v[150:153], v[208:211], v[92:95]
	v_mfma_f32_16x16x32_bf16 v[80:83], v[116:119], v[216:219], v[80:83]
	v_mfma_f32_16x16x32_bf16 v[76:79], v[150:153], v[216:219], v[76:79]
	v_mfma_f32_16x16x32_bf16 v[136:139], v[120:123], v[196:199], v[136:139]
	v_mfma_f32_16x16x32_bf16 v[132:135], v[154:157], v[196:199], v[132:135]
	v_mfma_f32_16x16x32_bf16 v[112:115], v[120:123], v[204:207], v[112:115]
	v_mfma_f32_16x16x32_bf16 v[108:111], v[154:157], v[204:207], v[108:111]
	v_mfma_f32_16x16x32_bf16 v[96:99], v[120:123], v[212:215], v[96:99]
	v_mfma_f32_16x16x32_bf16 v[92:95], v[154:157], v[212:215], v[92:95]
	v_mfma_f32_16x16x32_bf16 v[80:83], v[120:123], v[220:223], v[80:83]
	v_mfma_f32_16x16x32_bf16 v[76:79], v[154:157], v[220:223], v[76:79]
	v_mfma_f32_16x16x32_bf16 v[128:131], v[162:165], v[192:195], v[128:131]
	v_mfma_f32_16x16x32_bf16 v[124:127], v[184:187], v[192:195], v[124:127]
	v_mfma_f32_16x16x32_bf16 v[104:107], v[162:165], v[200:203], v[104:107]
	v_mfma_f32_16x16x32_bf16 v[100:103], v[184:187], v[200:203], v[100:103]
	v_mfma_f32_16x16x32_bf16 v[88:91], v[162:165], v[208:211], v[88:91]
	v_mfma_f32_16x16x32_bf16 v[84:87], v[184:187], v[208:211], v[84:87]
	v_mfma_f32_16x16x32_bf16 v[72:75], v[162:165], v[216:219], v[72:75]
	v_mfma_f32_16x16x32_bf16 v[68:71], v[184:187], v[216:219], v[68:71]
	v_mfma_f32_16x16x32_bf16 v[128:131], v[166:169], v[196:199], v[128:131]
	v_mfma_f32_16x16x32_bf16 v[124:127], v[188:191], v[196:199], v[124:127]
	v_mfma_f32_16x16x32_bf16 v[104:107], v[166:169], v[204:207], v[104:107]
	v_mfma_f32_16x16x32_bf16 v[100:103], v[188:191], v[204:207], v[100:103]
	v_mfma_f32_16x16x32_bf16 v[88:91], v[166:169], v[212:215], v[88:91]
	v_mfma_f32_16x16x32_bf16 v[84:87], v[188:191], v[212:215], v[84:87]
	v_mfma_f32_16x16x32_bf16 v[72:75], v[166:169], v[220:223], v[72:75]
	v_mfma_f32_16x16x32_bf16 v[68:71], v[188:191], v[220:223], v[68:71]
	s_barrier
	s_add_i32 s0, s60, s30
	v_lshl_add_u64 v[170:171], s[16:17], 0, v[174:175]
	s_mov_b32 m0, s0
	ds_read_b128 v[192:195], v161 offset:16384
	ds_read_b128 v[196:199], v161 offset:17408
	ds_read_b128 v[200:203], v161 offset:18432
	ds_read_b128 v[204:207], v161 offset:19456
	ds_read_b128 v[208:211], v161 offset:20480
	ds_read_b128 v[212:215], v161 offset:21504
	ds_read_b128 v[216:219], v161 offset:22528
	ds_read_b128 v[220:223], v161 offset:23552
	global_load_lds_dwordx4 v[170:171], off
	s_add_i32 m0, s0, 0x2000
	s_add_u32 s0, s16, 0x158000
	v_lshl_add_u64 v[224:225], s[16:17], 0, v[140:141]
	s_addc_u32 s1, s17, 0
	s_add_i32 s60, s61, s30
	global_load_lds_dwordx4 v[224:225], off
	v_lshl_add_u64 v[226:227], s[0:1], 0, v[174:175]
	s_mov_b32 m0, s60
	v_lshl_add_u64 v[228:229], s[18:19], 0, v[142:143]
	global_load_lds_dwordx4 v[226:227], off
	v_lshl_add_u64 v[226:227], s[0:1], 0, v[140:141]
	s_add_i32 m0, s60, 0x2000
	s_nop 0
	global_load_lds_dwordx4 v[226:227], off
	v_lshl_add_u64 v[226:227], s[18:19], 0, v[144:145]
	s_mov_b32 m0, s31
	s_nop 0
	global_load_lds_dwordx4 v[226:227], off
	s_mov_b32 m0, s34
	s_nop 0
	global_load_lds_dwordx4 v[228:229], off
	s_waitcnt vmcnt(8)
	s_waitcnt lgkmcnt(0)
	s_barrier
; #define PG8_STAGE(bufoff, gbase, voff) do { _Pragma("unroll") for (int _i = 0; _i < 2; ++_i) \
;         __builtin_amdgcn_global_load_lds((const unsigned*)((const char*)(gbase) + (voff)[_i]), (PG8_LAS unsigned*)(lds + (bufoff) + ldsw + _i * 8192), 16, 0, 0); } while (0)
; #define PG8_LDA(dst, b, h) do { _Pragma("unroll") for (int m = 0; m < 4; ++m) _Pragma("unroll") for (int k = 0; k < 2; ++k) dst[m][k] = *(const PG8_LAS bf16x8*)(lds + PG8_SA(b, h) + aoff + m * 2048 + k * 1024); } while (0)
; #define PG8_LDB(dst, b, h) do { _Pragma("unroll") for (int n = 0; n < 2; ++n) _Pragma("unroll") for (int k = 0; k < 2; ++k) dst[n][k] = *(const PG8_LAS bf16x8*)(lds + PG8_SB(b, h) + boff + n * 2048 + k * 1024); } while (0)
; #define PG8_MMA(ai, bj, At, Bt) do { __builtin_amdgcn_s_setprio(1); _Pragma("unroll") for (int m = 0; m < 4; ++m) _Pragma("unroll") for (int n = 0; n < 2; ++n) _Pragma("unroll") for (int k = 0; k < 2; ++k) \
;         acc[ai][bj][m][n] = __builtin_amdgcn_mfma_f32_16x16x32_bf16(Bt[n][k], At[m][k], acc[ai][bj][m][n], 0, 0, 0); __builtin_amdgcn_s_setprio(0); } while (0)
; #define PG8_WAIT_V(n) asm volatile("s_waitcnt vmcnt(" #n ")" ::: "memory")
; #define PG8_WAIT_L(n) asm volatile("s_waitcnt lgkmcnt(" #n ")" ::: "memory")
; #define PG8_BAR __builtin_amdgcn_s_barrier()
; #define PG8_SCHED __builtin_amdgcn_sched_barrier(0)
; template <class Epi, class Sched, bool ALIGN_EPI = false, bool SP2 = false>
; __device__ __forceinline__ void gemm_phase(PG8_LAS unsigned char* lds, const Gemm g, const Sched& S, const Epi& E) {
;     ...
;             PG8_WAIT_V(8); PG8_WAIT_L(0); PG8_BAR; PG8_MMA(1, 0, At, B0); PG8_MMA(1, 1, At, B1); PG8_BAR; PG8_SCHED;
;             PG8_LDB(B0, 1, 0); PG8_LDB(B1, 1, 1); PG8_SCHED; PG8_LDA(At, 1, 0); PG8_STAGE(PG8_SA(0, 1), a2 + hstep, voffA);
;             PG8_WAIT_V(8); PG8_WAIT_L(0); PG8_BAR; PG8_MMA(0, 0, At, B0); PG8_MMA(0, 1, At, B1); PG8_BAR; PG8_SCHED;
	s_waitcnt lgkmcnt(0)
	v_mfma_f32_16x16x32_bf16 v[64:67], v[116:119], v[192:195], v[64:67]
	v_mfma_f32_16x16x32_bf16 v[60:63], v[150:153], v[192:195], v[60:63]
	v_mfma_f32_16x16x32_bf16 v[48:51], v[116:119], v[200:203], v[48:51]
	v_mfma_f32_16x16x32_bf16 v[44:47], v[150:153], v[200:203], v[44:47]
	v_mfma_f32_16x16x32_bf16 v[32:35], v[116:119], v[208:211], v[32:35]
	v_mfma_f32_16x16x32_bf16 v[28:31], v[150:153], v[208:211], v[28:31]
	v_mfma_f32_16x16x32_bf16 v[16:19], v[116:119], v[216:219], v[16:19]
	v_mfma_f32_16x16x32_bf16 v[12:15], v[150:153], v[216:219], v[12:15]
	v_mfma_f32_16x16x32_bf16 v[64:67], v[120:123], v[196:199], v[64:67]
	v_mfma_f32_16x16x32_bf16 v[60:63], v[154:157], v[196:199], v[60:63]
	v_mfma_f32_16x16x32_bf16 v[48:51], v[120:123], v[204:207], v[48:51]
	v_mfma_f32_16x16x32_bf16 v[44:47], v[154:157], v[204:207], v[44:47]
	v_mfma_f32_16x16x32_bf16 v[32:35], v[120:123], v[212:215], v[32:35]
	v_mfma_f32_16x16x32_bf16 v[28:31], v[154:157], v[212:215], v[28:31]
	v_mfma_f32_16x16x32_bf16 v[16:19], v[120:123], v[220:223], v[16:19]
	v_mfma_f32_16x16x32_bf16 v[12:15], v[154:157], v[220:223], v[12:15]
	v_mfma_f32_16x16x32_bf16 v[56:59], v[162:165], v[192:195], v[56:59]
	v_mfma_f32_16x16x32_bf16 v[52:55], v[184:187], v[192:195], v[52:55]
	v_mfma_f32_16x16x32_bf16 v[40:43], v[162:165], v[200:203], v[40:43]
	v_mfma_f32_16x16x32_bf16 v[36:39], v[184:187], v[200:203], v[36:39]
	v_mfma_f32_16x16x32_bf16 v[24:27], v[162:165], v[208:211], v[24:27]
	v_mfma_f32_16x16x32_bf16 v[20:23], v[184:187], v[208:211], v[20:23]
	v_mfma_f32_16x16x32_bf16 v[8:11], v[162:165], v[216:219], v[8:11]
	v_mfma_f32_16x16x32_bf16 v[4:7], v[184:187], v[216:219], v[4:7]
	v_mfma_f32_16x16x32_bf16 v[56:59], v[166:169], v[196:199], v[56:59]
	v_mfma_f32_16x16x32_bf16 v[52:55], v[188:191], v[196:199], v[52:55]
	v_mfma_f32_16x16x32_bf16 v[40:43], v[166:169], v[204:207], v[40:43]
	v_mfma_f32_16x16x32_bf16 v[36:39], v[188:191], v[204:207], v[36:39]
	v_mfma_f32_16x16x32_bf16 v[24:27], v[166:169], v[212:215], v[24:27]
	v_mfma_f32_16x16x32_bf16 v[20:23], v[188:191], v[212:215], v[20:23]
	v_mfma_f32_16x16x32_bf16 v[8:11], v[166:169], v[220:223], v[8:11]
	v_mfma_f32_16x16x32_bf16 v[4:7], v[188:191], v[220:223], v[4:7]
	s_barrier
	s_add_i32 s60, 0, 0x18000
	s_add_i32 s61, 0, 0x1c000
	v_add_u32_e32 v154, s60, v159
	v_add_u32_e32 v179, s61, v159
	ds_read_b128 v[116:119], v154
	ds_read_b128 v[120:123], v154 offset:1024
	ds_read_b128 v[150:153], v154 offset:2048
	ds_read_b128 v[154:157], v154 offset:3072
	ds_read_b128 v[162:165], v179
	ds_read_b128 v[166:169], v179 offset:1024
	ds_read_b128 v[184:187], v179 offset:2048
	ds_read_b128 v[188:191], v179 offset:3072
	s_add_u32 s0, s18, 0x158000
	s_addc_u32 s1, s19, 0
	s_mov_b32 m0, s35
	v_lshl_add_u64 v[230:231], s[0:1], 0, v[144:145]
	ds_read_b128 v[192:195], v161 offset:32768
	ds_read_b128 v[196:199], v161 offset:33792
	ds_read_b128 v[200:203], v161 offset:34816
	ds_read_b128 v[204:207], v161 offset:35840
	ds_read_b128 v[208:211], v161 offset:36864
	ds_read_b128 v[212:215], v161 offset:37888
	ds_read_b128 v[216:219], v161 offset:38912
	ds_read_b128 v[220:223], v161 offset:39936
	global_load_lds_dwordx4 v[230:231], off
	v_lshl_add_u64 v[230:231], s[0:1], 0, v[142:143]
	s_mov_b32 m0, s52
	s_nop 0
	global_load_lds_dwordx4 v[230:231], off
	s_waitcnt vmcnt(8)
	s_waitcnt lgkmcnt(0)
	s_barrier
	s_waitcnt lgkmcnt(0)
	v_mfma_f32_16x16x32_bf16 v[136:139], v[116:119], v[192:195], v[136:139]
	v_mfma_f32_16x16x32_bf16 v[132:135], v[150:153], v[192:195], v[132:135]
	v_mfma_f32_16x16x32_bf16 v[112:115], v[116:119], v[200:203], v[112:115]
	v_mfma_f32_16x16x32_bf16 v[108:111], v[150:153], v[200:203], v[108:111]
	v_mfma_f32_16x16x32_bf16 v[96:99], v[116:119], v[208:211], v[96:99]
	v_mfma_f32_16x16x32_bf16 v[92:95], v[150:153], v[208:211], v[92:95]
	v_mfma_f32_16x16x32_bf16 v[80:83], v[116:119], v[216:219], v[80:83]
	v_mfma_f32_16x16x32_bf16 v[76:79], v[150:153], v[216:219], v[76:79]
	v_mfma_f32_16x16x32_bf16 v[136:139], v[120:123], v[196:199], v[136:139]
	v_mfma_f32_16x16x32_bf16 v[132:135], v[154:157], v[196:199], v[132:135]
	v_mfma_f32_16x16x32_bf16 v[112:115], v[120:123], v[204:207], v[112:115]
	v_mfma_f32_16x16x32_bf16 v[108:111], v[154:157], v[204:207], v[108:111]
	v_mfma_f32_16x16x32_bf16 v[96:99], v[120:123], v[212:215], v[96:99]
	v_mfma_f32_16x16x32_bf16 v[92:95], v[154:157], v[212:215], v[92:95]
	v_mfma_f32_16x16x32_bf16 v[80:83], v[120:123], v[220:223], v[80:83]
	v_mfma_f32_16x16x32_bf16 v[76:79], v[154:157], v[220:223], v[76:79]
	v_mfma_f32_16x16x32_bf16 v[128:131], v[162:165], v[192:195], v[128:131]
	v_mfma_f32_16x16x32_bf16 v[124:127], v[184:187], v[192:195], v[124:127]
	v_mfma_f32_16x16x32_bf16 v[104:107], v[162:165], v[200:203], v[104:107]
	v_mfma_f32_16x16x32_bf16 v[100:103], v[184:187], v[200:203], v[100:103]
	v_mfma_f32_16x16x32_bf16 v[88:91], v[162:165], v[208:211], v[88:91]
	v_mfma_f32_16x16x32_bf16 v[84:87], v[184:187], v[208:211], v[84:87]
	v_mfma_f32_16x16x32_bf16 v[72:75], v[162:165], v[216:219], v[72:75]
	v_mfma_f32_16x16x32_bf16 v[68:71], v[184:187], v[216:219], v[68:71]
	v_mfma_f32_16x16x32_bf16 v[128:131], v[166:169], v[196:199], v[128:131]
	v_mfma_f32_16x16x32_bf16 v[124:127], v[188:191], v[196:199], v[124:127]
	v_mfma_f32_16x16x32_bf16 v[104:107], v[166:169], v[204:207], v[104:107]
	v_mfma_f32_16x16x32_bf16 v[100:103], v[188:191], v[204:207], v[100:103]
	v_mfma_f32_16x16x32_bf16 v[88:91], v[166:169], v[212:215], v[88:91]
	v_mfma_f32_16x16x32_bf16 v[84:87], v[188:191], v[212:215], v[84:87]
	v_mfma_f32_16x16x32_bf16 v[72:75], v[166:169], v[220:223], v[72:75]
	v_mfma_f32_16x16x32_bf16 v[68:71], v[188:191], v[220:223], v[68:71]
	s_barrier
; #define PG8_STAGE(bufoff, gbase, voff) do { _Pragma("unroll") for (int _i = 0; _i < 2; ++_i) \
;         __builtin_amdgcn_global_load_lds((const unsigned*)((const char*)(gbase) + (voff)[_i]), (PG8_LAS unsigned*)(lds + (bufoff) + ldsw + _i * 8192), 16, 0, 0); } while (0)
; #define PG8_LDA(dst, b, h) do { _Pragma("unroll") for (int m = 0; m < 4; ++m) _Pragma("unroll") for (int k = 0; k < 2; ++k) dst[m][k] = *(const PG8_LAS bf16x8*)(lds + PG8_SA(b, h) + aoff + m * 2048 + k * 1024); } while (0)
; #define PG8_MMA(ai, bj, At, Bt) do { __builtin_amdgcn_s_setprio(1); _Pragma("unroll") for (int m = 0; m < 4; ++m) _Pragma("unroll") for (int n = 0; n < 2; ++n) _Pragma("unroll") for (int k = 0; k < 2; ++k) \
;         acc[ai][bj][m][n] = __builtin_amdgcn_mfma_f32_16x16x32_bf16(Bt[n][k], At[m][k], acc[ai][bj][m][n], 0, 0, 0); __builtin_amdgcn_s_setprio(0); } while (0)
; #define PG8_WAIT_V(n) asm volatile("s_waitcnt vmcnt(" #n ")" ::: "memory")
; #define PG8_WAIT_L(n) asm volatile("s_waitcnt lgkmcnt(" #n ")" ::: "memory")
; #define PG8_BAR __builtin_amdgcn_s_barrier()
; #define PG8_SCHED __builtin_amdgcn_sched_barrier(0)
; template <class Epi, class Sched, bool ALIGN_EPI = false, bool SP2 = false>
; __device__ __forceinline__ void gemm_phase(PG8_LAS unsigned char* lds, const Gemm g, const Sched& S, const Epi& E) {
;     ...
;             PG8_LDA(At, 1, 1); PG8_STAGE(PG8_SB(1, 0), b3, voffB); PG8_STAGE(PG8_SB(1, 1), b3 + hstep, voffB); PG8_STAGE(PG8_SA(1, 0), a3, voffA);
;             PG8_WAIT_V(8); PG8_WAIT_L(0); PG8_BAR; PG8_MMA(1, 0, At, B0); PG8_MMA(1, 1, At, B1); PG8_BAR; PG8_SCHED;
	s_add_i32 s0, s60, s30
	v_lshl_add_u64 v[170:171], v[170:171], 0, s[10:11]
	s_mov_b32 m0, s0
	ds_read_b128 v[192:195], v161 offset:49152
	ds_read_b128 v[196:199], v161 offset:50176
	ds_read_b128 v[200:203], v161 offset:51200
	ds_read_b128 v[204:207], v161 offset:52224
	ds_read_b128 v[208:211], v161 offset:53248
	ds_read_b128 v[212:215], v161 offset:54272
	ds_read_b128 v[216:219], v161 offset:55296
	ds_read_b128 v[220:223], v161 offset:56320
	global_load_lds_dwordx4 v[170:171], off
	s_add_i32 m0, s0, 0x2000
	s_add_u32 s0, s16, 0x158080
	v_lshl_add_u64 v[170:171], v[224:225], 0, s[10:11]
	s_addc_u32 s1, s17, 0
	s_add_i32 s16, s61, s30
	global_load_lds_dwordx4 v[170:171], off
	v_lshl_add_u64 v[170:171], s[0:1], 0, v[174:175]
	s_mov_b32 m0, s16
	s_nop 0
	global_load_lds_dwordx4 v[170:171], off
	v_lshl_add_u64 v[170:171], s[0:1], 0, v[140:141]
	s_add_i32 m0, s16, 0x2000
	s_nop 0
	global_load_lds_dwordx4 v[170:171], off
	v_lshl_add_u64 v[170:171], v[226:227], 0, s[10:11]
	s_mov_b32 m0, s54
	s_nop 0
	global_load_lds_dwordx4 v[170:171], off
	v_lshl_add_u64 v[170:171], v[228:229], 0, s[10:11]
	s_mov_b32 m0, s55
	s_nop 0
	global_load_lds_dwordx4 v[170:171], off
	s_waitcnt vmcnt(8)
	s_waitcnt lgkmcnt(0)
	s_barrier
	s_waitcnt lgkmcnt(0)
	v_mfma_f32_16x16x32_bf16 v[64:67], v[116:119], v[192:195], v[64:67]
	v_mfma_f32_16x16x32_bf16 v[60:63], v[150:153], v[192:195], v[60:63]
	v_mfma_f32_16x16x32_bf16 v[48:51], v[116:119], v[200:203], v[48:51]
	v_mfma_f32_16x16x32_bf16 v[44:47], v[150:153], v[200:203], v[44:47]
	v_mfma_f32_16x16x32_bf16 v[32:35], v[116:119], v[208:211], v[32:35]
	v_mfma_f32_16x16x32_bf16 v[28:31], v[150:153], v[208:211], v[28:31]
	v_mfma_f32_16x16x32_bf16 v[16:19], v[116:119], v[216:219], v[16:19]
	v_mfma_f32_16x16x32_bf16 v[12:15], v[150:153], v[216:219], v[12:15]
	v_mfma_f32_16x16x32_bf16 v[64:67], v[120:123], v[196:199], v[64:67]
	v_mfma_f32_16x16x32_bf16 v[60:63], v[154:157], v[196:199], v[60:63]
	v_mfma_f32_16x16x32_bf16 v[48:51], v[120:123], v[204:207], v[48:51]
	v_mfma_f32_16x16x32_bf16 v[44:47], v[154:157], v[204:207], v[44:47]
	v_mfma_f32_16x16x32_bf16 v[32:35], v[120:123], v[212:215], v[32:35]
	v_mfma_f32_16x16x32_bf16 v[28:31], v[154:157], v[212:215], v[28:31]
	v_mfma_f32_16x16x32_bf16 v[16:19], v[120:123], v[220:223], v[16:19]
	v_mfma_f32_16x16x32_bf16 v[12:15], v[154:157], v[220:223], v[12:15]
	v_mfma_f32_16x16x32_bf16 v[56:59], v[162:165], v[192:195], v[56:59]
	v_mfma_f32_16x16x32_bf16 v[52:55], v[184:187], v[192:195], v[52:55]
	v_mfma_f32_16x16x32_bf16 v[40:43], v[162:165], v[200:203], v[40:43]
	v_mfma_f32_16x16x32_bf16 v[36:39], v[184:187], v[200:203], v[36:39]
	v_mfma_f32_16x16x32_bf16 v[24:27], v[162:165], v[208:211], v[24:27]
	v_mfma_f32_16x16x32_bf16 v[20:23], v[184:187], v[208:211], v[20:23]
	v_mfma_f32_16x16x32_bf16 v[8:11], v[162:165], v[216:219], v[8:11]
	v_mfma_f32_16x16x32_bf16 v[4:7], v[184:187], v[216:219], v[4:7]
	v_mfma_f32_16x16x32_bf16 v[56:59], v[166:169], v[196:199], v[56:59]
	v_mfma_f32_16x16x32_bf16 v[52:55], v[188:191], v[196:199], v[52:55]
	v_mfma_f32_16x16x32_bf16 v[40:43], v[166:169], v[204:207], v[40:43]
	v_mfma_f32_16x16x32_bf16 v[36:39], v[188:191], v[204:207], v[36:39]
	v_mfma_f32_16x16x32_bf16 v[24:27], v[166:169], v[212:215], v[24:27]
	v_mfma_f32_16x16x32_bf16 v[20:23], v[188:191], v[212:215], v[20:23]
	v_mfma_f32_16x16x32_bf16 v[8:11], v[166:169], v[220:223], v[8:11]
	v_mfma_f32_16x16x32_bf16 v[4:7], v[188:191], v[220:223], v[4:7]
	s_barrier
	s_add_i32 s25, s25, 2
	s_add_u32 s23, s23, 0x100
	s_addc_u32 s24, s24, 0
	s_cmpk_gt_u32 s25, 0x53
	s_mov_b64 s[0:1], s[14:15]
	s_cbranch_scc0 .LBB0_822
	s_and_b64 vcc, exec, s[48:49]
	s_cbranch_vccz .LBB0_825
	s_barrier
